# s_setprio 0 issued in the shadow of the last MFMA of each segment (before the closing barrier) so the released load-segment wave never contends at equal priority
# speedup vs baseline: 1.0030x; 1.0030x over previous
; #define PG8_STAGE(bufoff, gbase, voff) do { _Pragma("unroll") for (int _i = 0; _i < 2; ++_i) \
;         __builtin_amdgcn_global_load_lds((const unsigned*)((const char*)(gbase) + (voff)[_i]), (PG8_LAS unsigned*)(lds + (bufoff) + ldsw + _i * 8192), 16, 0, 0); } while (0)
; #define PG8_LDA(dst, b, h) do { _Pragma("unroll") for (int m = 0; m < 4; ++m) _Pragma("unroll") for (int k = 0; k < 2; ++k) dst[m][k] = *(const PG8_LAS bf16x8*)(lds + PG8_SA(b, h) + aoff + m * 2048 + k * 1024); } while (0)
; #define PG8_LDB(dst, b, h) do { _Pragma("unroll") for (int n = 0; n < 2; ++n) _Pragma("unroll") for (int k = 0; k < 2; ++k) dst[n][k] = *(const PG8_LAS bf16x8*)(lds + PG8_SB(b, h) + boff + n * 2048 + k * 1024); } while (0)
; #define PG8_WAIT_V(n) asm volatile("s_waitcnt vmcnt(" #n ")" ::: "memory")
; #define PG8_WAIT_L(n) asm volatile("s_waitcnt lgkmcnt(" #n ")" ::: "memory")
; #define PG8_BAR __builtin_amdgcn_s_barrier()
; #define PG8_SCHED __builtin_amdgcn_sched_barrier(0)
; template <class Epi, class Sched, bool ALIGN_EPI = false, bool SP2 = false>
; __device__ __forceinline__ void gemm_phase(PG8_LAS unsigned char* lds, const Gemm g, const Sched& S, const Epi& E) {
;     ...
;         const char* nA = has_next ? (const char*)g.A + (size_t)nxt.pm * tstep : cA; const char* nB = has_next ? (const char*)g.Bt + (size_t)nxt.pn * tstep : cB;
;         for (int t = 0; t < nt; t += 2) {
;             const bool last = (t == nt - 2);
;             const char* a1 = cA + (size_t)(t + 1) * kstep;
;             const char* a2 = last ? nA : cA + (size_t)(t + 2) * kstep; const char* b2 = last ? nB : cB + (size_t)(t + 2) * kstep;
;             const char* a3 = a2 + kstep; const char* b3 = b2 + kstep;
;             if (last && has_next) S.a_ready(nxt, ui + 1);
;             if constexpr (SP2) {
;             PG8_LDB(B0, 0, 0); PG8_LDB(B1, 0, 1); PG8_SCHED; PG8_LDA(At, 0, 0); PG8_STAGE(PG8_SA(1, 1), a1 + hstep, voffA);
;             PG8_WAIT_V(8); PG8_WAIT_L(0); PG8_BAR; PG8_MMA(0, 0, At, B0); PG8_MMA(0, 1, At, B1); PG8_BAR; PG8_SCHED;
;             PG8_LDA(At, 0, 1); PG8_STAGE(PG8_SB(0, 0), b2, voffB); PG8_STAGE(PG8_SB(0, 1), b2 + hstep, voffB); PG8_STAGE(PG8_SA(0, 0), a2, voffA);
;             PG8_WAIT_V(8); PG8_WAIT_L(0); PG8_BAR; PG8_MMA(1, 0, At, B0); PG8_MMA(1, 1, At, B1); PG8_BAR; PG8_SCHED;
.LBB0_336:
	s_ashr_i32 s17, s16, 31
	s_lshl_b64 s[18:19], s[16:17], 19
	s_add_u32 s18, s36, s18
	s_addc_u32 s19, s37, s19
	s_and_b64 s[20:21], s[0:1], exec
	s_cselect_b32 s17, s19, s25
	s_cselect_b32 s50, s18, s24
	s_ashr_i32 s15, s14, 31
	s_lshl_b64 s[20:21], s[14:15], 19
	s_add_u32 s20, s34, s20
	s_addc_u32 s21, s35, s21
	s_and_b64 s[28:29], s[0:1], exec
	s_cselect_b32 s15, s21, s27
	s_cselect_b32 s51, s20, s26
	s_add_u32 s24, s24, 0x40080
	s_addc_u32 s25, s25, 0
	s_add_u32 s52, s26, 0x100
	s_addc_u32 s53, s27, 0
	s_mov_b32 s54, -2
	s_add_u32 s26, s24, 0xfffc0080
	s_addc_u32 s27, s25, -1
	s_cmp_eq_u32 s54, 12
	s_cselect_b32 s29, s17, s27
	s_cselect_b32 s28, s50, s26
	s_cselect_b32 s27, s15, s53
	s_cselect_b32 s26, s51, s52
	s_add_i32 m0, s23, 0xc000
	s_nop 0
	global_load_lds_dwordx4 v136, s[24:25]
	s_add_i32 m0, s23, 0xe000
	s_nop 0
	global_load_lds_dwordx4 v138, s[24:25]
	s_waitcnt vmcnt(8)
	s_waitcnt lgkmcnt(0)
	s_setprio 1
	s_barrier
	v_mfma_f32_16x16x32_bf16 v[124:127], v[152:155], v[184:187], 0
	v_mfma_f32_16x16x32_bf16 v[120:123], v[160:163], v[184:187], 0
	v_mfma_f32_16x16x32_bf16 v[108:111], v[152:155], v[192:195], 0
	v_mfma_f32_16x16x32_bf16 v[104:107], v[160:163], v[192:195], 0
	v_mfma_f32_16x16x32_bf16 v[92:95], v[152:155], v[200:203], 0
	v_mfma_f32_16x16x32_bf16 v[88:91], v[160:163], v[200:203], 0
	v_mfma_f32_16x16x32_bf16 v[76:79], v[152:155], v[208:211], 0
	v_mfma_f32_16x16x32_bf16 v[72:75], v[160:163], v[208:211], 0
	v_mfma_f32_16x16x32_bf16 v[124:127], v[156:159], v[188:191], v[124:127]
	v_mfma_f32_16x16x32_bf16 v[120:123], v[164:167], v[188:191], v[120:123]
	v_mfma_f32_16x16x32_bf16 v[108:111], v[156:159], v[196:199], v[108:111]
	v_mfma_f32_16x16x32_bf16 v[104:107], v[164:167], v[196:199], v[104:107]
	v_mfma_f32_16x16x32_bf16 v[92:95], v[156:159], v[204:207], v[92:95]
	v_mfma_f32_16x16x32_bf16 v[88:91], v[164:167], v[204:207], v[88:91]
	v_mfma_f32_16x16x32_bf16 v[76:79], v[156:159], v[212:215], v[76:79]
	v_mfma_f32_16x16x32_bf16 v[72:75], v[164:167], v[212:215], v[72:75]
	v_mfma_f32_16x16x32_bf16 v[116:119], v[168:171], v[184:187], 0
	v_mfma_f32_16x16x32_bf16 v[112:115], v[176:179], v[184:187], 0
	v_mfma_f32_16x16x32_bf16 v[100:103], v[168:171], v[192:195], 0
	v_mfma_f32_16x16x32_bf16 v[96:99], v[176:179], v[192:195], 0
	v_mfma_f32_16x16x32_bf16 v[84:87], v[168:171], v[200:203], 0
	v_mfma_f32_16x16x32_bf16 v[80:83], v[176:179], v[200:203], 0
	v_mfma_f32_16x16x32_bf16 v[68:71], v[168:171], v[208:211], 0
	v_mfma_f32_16x16x32_bf16 v[64:67], v[176:179], v[208:211], 0
	v_mfma_f32_16x16x32_bf16 v[116:119], v[172:175], v[188:191], v[116:119]
	v_mfma_f32_16x16x32_bf16 v[112:115], v[180:183], v[188:191], v[112:115]
	v_mfma_f32_16x16x32_bf16 v[100:103], v[172:175], v[196:199], v[100:103]
	v_mfma_f32_16x16x32_bf16 v[96:99], v[180:183], v[196:199], v[96:99]
	v_mfma_f32_16x16x32_bf16 v[84:87], v[172:175], v[204:207], v[84:87]
	v_mfma_f32_16x16x32_bf16 v[80:83], v[180:183], v[204:207], v[80:83]
	v_mfma_f32_16x16x32_bf16 v[68:71], v[172:175], v[212:215], v[68:71]
	s_setprio 0
	v_mfma_f32_16x16x32_bf16 v[64:67], v[180:183], v[212:215], v[64:67]
	s_barrier
	s_add_i32 s55, s44, s33
	v_lshl_add_u64 v[216:217], s[26:27], 0, v[132:133]
	s_mov_b32 m0, s55
	ds_read_b128 v[184:187], v150 offset:16384
	ds_read_b128 v[188:191], v150 offset:17408
	ds_read_b128 v[192:195], v150 offset:18432
	ds_read_b128 v[196:199], v150 offset:19456
	ds_read_b128 v[200:203], v150 offset:20480
	ds_read_b128 v[204:207], v150 offset:21504
	ds_read_b128 v[208:211], v150 offset:22528
	ds_read_b128 v[212:215], v150 offset:23552
	global_load_lds_dwordx4 v[216:217], off
	s_add_i32 m0, s55, 0x2000
	s_add_u32 s56, s26, 0x40000
	v_lshl_add_u64 v[218:219], s[26:27], 0, v[128:129]
	s_addc_u32 s57, s27, 0
	s_add_i32 s55, s45, s33
	global_load_lds_dwordx4 v[218:219], off
	s_mov_b32 m0, s55
	v_lshl_add_u64 v[222:223], s[28:29], 0, v[130:131]
	global_load_lds_dwordx4 v132, s[56:57]
	s_add_i32 m0, s55, 0x2000
	s_nop 0
	global_load_lds_dwordx4 v128, s[56:57]
	v_lshl_add_u64 v[220:221], s[28:29], 0, v[134:135]
	s_mov_b32 m0, s23
	s_nop 0
	global_load_lds_dwordx4 v[220:221], off
	s_mov_b32 m0, s39
	s_nop 0
	global_load_lds_dwordx4 v[222:223], off
	s_waitcnt vmcnt(8)
	s_waitcnt lgkmcnt(0)
	s_setprio 1
	s_barrier
	v_mfma_f32_16x16x32_bf16 v[60:63], v[152:155], v[184:187], 0
	v_mfma_f32_16x16x32_bf16 v[56:59], v[160:163], v[184:187], 0
	v_mfma_f32_16x16x32_bf16 v[44:47], v[152:155], v[192:195], 0
	v_mfma_f32_16x16x32_bf16 v[40:43], v[160:163], v[192:195], 0
	v_mfma_f32_16x16x32_bf16 v[28:31], v[152:155], v[200:203], 0
	v_mfma_f32_16x16x32_bf16 v[24:27], v[160:163], v[200:203], 0
	v_mfma_f32_16x16x32_bf16 v[12:15], v[152:155], v[208:211], 0
	v_mfma_f32_16x16x32_bf16 v[8:11], v[160:163], v[208:211], 0
	v_mfma_f32_16x16x32_bf16 v[60:63], v[156:159], v[188:191], v[60:63]
	v_mfma_f32_16x16x32_bf16 v[56:59], v[164:167], v[188:191], v[56:59]
	v_mfma_f32_16x16x32_bf16 v[44:47], v[156:159], v[196:199], v[44:47]
	v_mfma_f32_16x16x32_bf16 v[40:43], v[164:167], v[196:199], v[40:43]
	v_mfma_f32_16x16x32_bf16 v[28:31], v[156:159], v[204:207], v[28:31]
	v_mfma_f32_16x16x32_bf16 v[24:27], v[164:167], v[204:207], v[24:27]
	v_mfma_f32_16x16x32_bf16 v[12:15], v[156:159], v[212:215], v[12:15]
	v_mfma_f32_16x16x32_bf16 v[8:11], v[164:167], v[212:215], v[8:11]
	v_mfma_f32_16x16x32_bf16 v[52:55], v[168:171], v[184:187], 0
	v_mfma_f32_16x16x32_bf16 v[48:51], v[176:179], v[184:187], 0
	v_mfma_f32_16x16x32_bf16 v[36:39], v[168:171], v[192:195], 0
	v_mfma_f32_16x16x32_bf16 v[32:35], v[176:179], v[192:195], 0
	v_mfma_f32_16x16x32_bf16 v[20:23], v[168:171], v[200:203], 0
	v_mfma_f32_16x16x32_bf16 v[16:19], v[176:179], v[200:203], 0
	v_mfma_f32_16x16x32_bf16 v[4:7], v[168:171], v[208:211], 0
	v_mfma_f32_16x16x32_bf16 v[0:3], v[176:179], v[208:211], 0
	v_mfma_f32_16x16x32_bf16 v[52:55], v[172:175], v[188:191], v[52:55]
	v_mfma_f32_16x16x32_bf16 v[48:51], v[180:183], v[188:191], v[48:51]
	v_mfma_f32_16x16x32_bf16 v[36:39], v[172:175], v[196:199], v[36:39]
	v_mfma_f32_16x16x32_bf16 v[32:35], v[180:183], v[196:199], v[32:35]
	v_mfma_f32_16x16x32_bf16 v[20:23], v[172:175], v[204:207], v[20:23]
	v_mfma_f32_16x16x32_bf16 v[16:19], v[180:183], v[204:207], v[16:19]
	v_mfma_f32_16x16x32_bf16 v[4:7], v[172:175], v[212:215], v[4:7]
	s_setprio 0
	v_mfma_f32_16x16x32_bf16 v[0:3], v[180:183], v[212:215], v[0:3]
	s_barrier
; #define PG8_STAGE(bufoff, gbase, voff) do { _Pragma("unroll") for (int _i = 0; _i < 2; ++_i) \
;         __builtin_amdgcn_global_load_lds((const unsigned*)((const char*)(gbase) + (voff)[_i]), (PG8_LAS unsigned*)(lds + (bufoff) + ldsw + _i * 8192), 16, 0, 0); } while (0)
; #define PG8_LDA(dst, b, h) do { _Pragma("unroll") for (int m = 0; m < 4; ++m) _Pragma("unroll") for (int k = 0; k < 2; ++k) dst[m][k] = *(const PG8_LAS bf16x8*)(lds + PG8_SA(b, h) + aoff + m * 2048 + k * 1024); } while (0)
; #define PG8_LDB(dst, b, h) do { _Pragma("unroll") for (int n = 0; n < 2; ++n) _Pragma("unroll") for (int k = 0; k < 2; ++k) dst[n][k] = *(const PG8_LAS bf16x8*)(lds + PG8_SB(b, h) + boff + n * 2048 + k * 1024); } while (0)
; #define PG8_MMA(ai, bj, At, Bt) do { __builtin_amdgcn_s_setprio(1); _Pragma("unroll") for (int m = 0; m < 4; ++m) _Pragma("unroll") for (int n = 0; n < 2; ++n) _Pragma("unroll") for (int k = 0; k < 2; ++k) \
;         acc[ai][bj][m][n] = __builtin_amdgcn_mfma_f32_16x16x32_bf16(Bt[n][k], At[m][k], acc[ai][bj][m][n], 0, 0, 0); __builtin_amdgcn_s_setprio(0); } while (0)
; #define PG8_WAIT_V(n) asm volatile("s_waitcnt vmcnt(" #n ")" ::: "memory")
; #define PG8_WAIT_L(n) asm volatile("s_waitcnt lgkmcnt(" #n ")" ::: "memory")
; #define PG8_BAR __builtin_amdgcn_s_barrier()
; #define PG8_SCHED __builtin_amdgcn_sched_barrier(0)
; template <class Epi, class Sched, bool ALIGN_EPI = false, bool SP2 = false>
; __device__ __forceinline__ void gemm_phase(PG8_LAS unsigned char* lds, const Gemm g, const Sched& S, const Epi& E) {
;     ...
;             PG8_LDB(B0, 1, 0); PG8_LDB(B1, 1, 1); PG8_SCHED; PG8_LDA(At, 1, 0); PG8_STAGE(PG8_SA(0, 1), a2 + hstep, voffA);
;             PG8_WAIT_V(8); PG8_WAIT_L(0); PG8_BAR; PG8_MMA(0, 0, At, B0); PG8_MMA(0, 1, At, B1); PG8_BAR; PG8_SCHED;
;             PG8_LDA(At, 1, 1); PG8_STAGE(PG8_SB(1, 0), b3, voffB); PG8_STAGE(PG8_SB(1, 1), b3 + hstep, voffB); PG8_STAGE(PG8_SA(1, 0), a3, voffA);
;             PG8_WAIT_V(8); PG8_WAIT_L(0); PG8_BAR; PG8_MMA(1, 0, At, B0); PG8_MMA(1, 1, At, B1); PG8_BAR; PG8_SCHED;
	s_add_i32 s55, 0, 0x18000
	v_add_u32_e32 v151, s55, v145
	s_add_i32 s56, 0, 0x1c000
	ds_read_b128 v[152:155], v151
	ds_read_b128 v[156:159], v151 offset:1024
	ds_read_b128 v[160:163], v151 offset:2048
	ds_read_b128 v[164:167], v151 offset:3072
	v_add_u32_e32 v151, s56, v145
	ds_read_b128 v[168:171], v151
	ds_read_b128 v[172:175], v151 offset:1024
	ds_read_b128 v[176:179], v151 offset:2048
	ds_read_b128 v[180:183], v151 offset:3072
	s_add_u32 s28, s28, 0x40000
	s_addc_u32 s29, s29, 0
	s_mov_b32 m0, s40
	ds_read_b128 v[184:187], v150 offset:32768
	ds_read_b128 v[188:191], v150 offset:33792
	ds_read_b128 v[192:195], v150 offset:34816
	ds_read_b128 v[196:199], v150 offset:35840
	ds_read_b128 v[200:203], v150 offset:36864
	ds_read_b128 v[204:207], v150 offset:37888
	ds_read_b128 v[208:211], v150 offset:38912
	ds_read_b128 v[212:215], v150 offset:39936
	global_load_lds_dwordx4 v134, s[28:29]
	s_mov_b32 m0, s41
	s_nop 0
	global_load_lds_dwordx4 v130, s[28:29]
	s_waitcnt vmcnt(8)
	s_waitcnt lgkmcnt(0)
	s_setprio 1
	s_barrier
	v_mfma_f32_16x16x32_bf16 v[124:127], v[152:155], v[184:187], v[124:127]
	v_mfma_f32_16x16x32_bf16 v[120:123], v[160:163], v[184:187], v[120:123]
	v_mfma_f32_16x16x32_bf16 v[108:111], v[152:155], v[192:195], v[108:111]
	v_mfma_f32_16x16x32_bf16 v[104:107], v[160:163], v[192:195], v[104:107]
	v_mfma_f32_16x16x32_bf16 v[92:95], v[152:155], v[200:203], v[92:95]
	v_mfma_f32_16x16x32_bf16 v[88:91], v[160:163], v[200:203], v[88:91]
	v_mfma_f32_16x16x32_bf16 v[76:79], v[152:155], v[208:211], v[76:79]
	v_mfma_f32_16x16x32_bf16 v[72:75], v[160:163], v[208:211], v[72:75]
	v_mfma_f32_16x16x32_bf16 v[124:127], v[156:159], v[188:191], v[124:127]
	v_mfma_f32_16x16x32_bf16 v[120:123], v[164:167], v[188:191], v[120:123]
	v_mfma_f32_16x16x32_bf16 v[108:111], v[156:159], v[196:199], v[108:111]
	v_mfma_f32_16x16x32_bf16 v[104:107], v[164:167], v[196:199], v[104:107]
	v_mfma_f32_16x16x32_bf16 v[92:95], v[156:159], v[204:207], v[92:95]
	v_mfma_f32_16x16x32_bf16 v[88:91], v[164:167], v[204:207], v[88:91]
	v_mfma_f32_16x16x32_bf16 v[76:79], v[156:159], v[212:215], v[76:79]
	v_mfma_f32_16x16x32_bf16 v[72:75], v[164:167], v[212:215], v[72:75]
	v_mfma_f32_16x16x32_bf16 v[116:119], v[168:171], v[184:187], v[116:119]
	v_mfma_f32_16x16x32_bf16 v[112:115], v[176:179], v[184:187], v[112:115]
	v_mfma_f32_16x16x32_bf16 v[100:103], v[168:171], v[192:195], v[100:103]
	v_mfma_f32_16x16x32_bf16 v[96:99], v[176:179], v[192:195], v[96:99]
	v_mfma_f32_16x16x32_bf16 v[84:87], v[168:171], v[200:203], v[84:87]
	v_mfma_f32_16x16x32_bf16 v[80:83], v[176:179], v[200:203], v[80:83]
	v_mfma_f32_16x16x32_bf16 v[68:71], v[168:171], v[208:211], v[68:71]
	v_mfma_f32_16x16x32_bf16 v[64:67], v[176:179], v[208:211], v[64:67]
	v_mfma_f32_16x16x32_bf16 v[116:119], v[172:175], v[188:191], v[116:119]
	v_mfma_f32_16x16x32_bf16 v[112:115], v[180:183], v[188:191], v[112:115]
	v_mfma_f32_16x16x32_bf16 v[100:103], v[172:175], v[196:199], v[100:103]
	v_mfma_f32_16x16x32_bf16 v[96:99], v[180:183], v[196:199], v[96:99]
	v_mfma_f32_16x16x32_bf16 v[84:87], v[172:175], v[204:207], v[84:87]
	v_mfma_f32_16x16x32_bf16 v[80:83], v[180:183], v[204:207], v[80:83]
	v_mfma_f32_16x16x32_bf16 v[68:71], v[172:175], v[212:215], v[68:71]
	s_setprio 0
	v_mfma_f32_16x16x32_bf16 v[64:67], v[180:183], v[212:215], v[64:67]
	s_barrier
	s_add_i32 s28, s55, s33
	v_lshl_add_u64 v[216:217], v[216:217], 0, s[8:9]
	s_mov_b32 m0, s28
	ds_read_b128 v[184:187], v150 offset:49152
	ds_read_b128 v[188:191], v150 offset:50176
	ds_read_b128 v[192:195], v150 offset:51200
	ds_read_b128 v[196:199], v150 offset:52224
	ds_read_b128 v[200:203], v150 offset:53248
	ds_read_b128 v[204:207], v150 offset:54272
	ds_read_b128 v[208:211], v150 offset:55296
	ds_read_b128 v[212:215], v150 offset:56320
	global_load_lds_dwordx4 v[216:217], off
	s_add_i32 m0, s28, 0x2000
	s_add_u32 s26, s26, 0x40080
	v_lshl_add_u64 v[216:217], v[218:219], 0, s[8:9]
	s_addc_u32 s27, s27, 0
	s_add_i32 s28, s56, s33
	global_load_lds_dwordx4 v[216:217], off
	s_mov_b32 m0, s28
	s_nop 0
	global_load_lds_dwordx4 v132, s[26:27]
	s_add_i32 m0, s28, 0x2000
	s_nop 0
	global_load_lds_dwordx4 v128, s[26:27]
	v_lshl_add_u64 v[216:217], v[220:221], 0, s[8:9]
	s_mov_b32 m0, s42
	s_nop 0
	global_load_lds_dwordx4 v[216:217], off
	v_lshl_add_u64 v[216:217], v[222:223], 0, s[8:9]
	s_mov_b32 m0, s43
	s_nop 0
	global_load_lds_dwordx4 v[216:217], off
	s_waitcnt vmcnt(8)
	s_waitcnt lgkmcnt(0)
	s_setprio 1
	s_barrier
	v_mfma_f32_16x16x32_bf16 v[60:63], v[152:155], v[184:187], v[60:63]
	v_mfma_f32_16x16x32_bf16 v[56:59], v[160:163], v[184:187], v[56:59]
	v_mfma_f32_16x16x32_bf16 v[44:47], v[152:155], v[192:195], v[44:47]
	v_mfma_f32_16x16x32_bf16 v[40:43], v[160:163], v[192:195], v[40:43]
	v_mfma_f32_16x16x32_bf16 v[28:31], v[152:155], v[200:203], v[28:31]
	v_mfma_f32_16x16x32_bf16 v[24:27], v[160:163], v[200:203], v[24:27]
	v_mfma_f32_16x16x32_bf16 v[12:15], v[152:155], v[208:211], v[12:15]
	v_mfma_f32_16x16x32_bf16 v[8:11], v[160:163], v[208:211], v[8:11]
	v_mfma_f32_16x16x32_bf16 v[60:63], v[156:159], v[188:191], v[60:63]
	v_mfma_f32_16x16x32_bf16 v[56:59], v[164:167], v[188:191], v[56:59]
	v_mfma_f32_16x16x32_bf16 v[44:47], v[156:159], v[196:199], v[44:47]
	v_mfma_f32_16x16x32_bf16 v[40:43], v[164:167], v[196:199], v[40:43]
	v_mfma_f32_16x16x32_bf16 v[28:31], v[156:159], v[204:207], v[28:31]
	v_mfma_f32_16x16x32_bf16 v[24:27], v[164:167], v[204:207], v[24:27]
	v_mfma_f32_16x16x32_bf16 v[12:15], v[156:159], v[212:215], v[12:15]
	v_mfma_f32_16x16x32_bf16 v[8:11], v[164:167], v[212:215], v[8:11]
	v_mfma_f32_16x16x32_bf16 v[52:55], v[168:171], v[184:187], v[52:55]
	v_mfma_f32_16x16x32_bf16 v[48:51], v[176:179], v[184:187], v[48:51]
	v_mfma_f32_16x16x32_bf16 v[36:39], v[168:171], v[192:195], v[36:39]
	v_mfma_f32_16x16x32_bf16 v[32:35], v[176:179], v[192:195], v[32:35]
	v_mfma_f32_16x16x32_bf16 v[20:23], v[168:171], v[200:203], v[20:23]
	v_mfma_f32_16x16x32_bf16 v[16:19], v[176:179], v[200:203], v[16:19]
	v_mfma_f32_16x16x32_bf16 v[4:7], v[168:171], v[208:211], v[4:7]
	v_mfma_f32_16x16x32_bf16 v[0:3], v[176:179], v[208:211], v[0:3]
	v_mfma_f32_16x16x32_bf16 v[52:55], v[172:175], v[188:191], v[52:55]
	v_mfma_f32_16x16x32_bf16 v[48:51], v[180:183], v[188:191], v[48:51]
	v_mfma_f32_16x16x32_bf16 v[36:39], v[172:175], v[196:199], v[36:39]
	v_mfma_f32_16x16x32_bf16 v[32:35], v[180:183], v[196:199], v[32:35]
	v_mfma_f32_16x16x32_bf16 v[20:23], v[172:175], v[204:207], v[20:23]
	v_mfma_f32_16x16x32_bf16 v[16:19], v[180:183], v[204:207], v[16:19]
	v_mfma_f32_16x16x32_bf16 v[4:7], v[172:175], v[212:215], v[4:7]
	s_setprio 0
	v_mfma_f32_16x16x32_bf16 v[0:3], v[180:183], v[212:215], v[0:3]
	s_barrier
	s_add_i32 s54, s54, 2
	s_add_u32 s24, s24, 0x100
	s_addc_u32 s25, s25, 0
	s_add_u32 s52, s52, 0x100
	s_addc_u32 s53, s53, 0
	s_cmp_gt_u32 s54, 13
; #define PG8_STAGE(bufoff, gbase, voff) do { _Pragma("unroll") for (int _i = 0; _i < 2; ++_i) \
;         __builtin_amdgcn_global_load_lds((const unsigned*)((const char*)(gbase) + (voff)[_i]), (PG8_LAS unsigned*)(lds + (bufoff) + ldsw + _i * 8192), 16, 0, 0); } while (0)
; #define PG8_LDA(dst, b, h) do { _Pragma("unroll") for (int m = 0; m < 4; ++m) _Pragma("unroll") for (int k = 0; k < 2; ++k) dst[m][k] = *(const PG8_LAS bf16x8*)(lds + PG8_SA(b, h) + aoff + m * 2048 + k * 1024); } while (0)
; #define PG8_LDB(dst, b, h) do { _Pragma("unroll") for (int n = 0; n < 2; ++n) _Pragma("unroll") for (int k = 0; k < 2; ++k) dst[n][k] = *(const PG8_LAS bf16x8*)(lds + PG8_SB(b, h) + boff + n * 2048 + k * 1024); } while (0)
; #define PG8_MMA(ai, bj, At, Bt) do { __builtin_amdgcn_s_setprio(1); _Pragma("unroll") for (int m = 0; m < 4; ++m) _Pragma("unroll") for (int n = 0; n < 2; ++n) _Pragma("unroll") for (int k = 0; k < 2; ++k) \
;         acc[ai][bj][m][n] = __builtin_amdgcn_mfma_f32_16x16x32_bf16(Bt[n][k], At[m][k], acc[ai][bj][m][n], 0, 0, 0); __builtin_amdgcn_s_setprio(0); } while (0)
; #define PG8_WAIT_V(n) asm volatile("s_waitcnt vmcnt(" #n ")" ::: "memory")
; #define PG8_WAIT_L(n) asm volatile("s_waitcnt lgkmcnt(" #n ")" ::: "memory")
; template <class Epi, class Sched, bool ALIGN_EPI = false, bool SP2 = false>
; __device__ __forceinline__ void gemm_phase(PG8_LAS unsigned char* lds, const Gemm g, const Sched& S, const Epi& E) {
;     ...
;             const bool last = (t == nt - 2);
;             const char* a1 = cA + (size_t)(t + 1) * kstep;
;             const char* a2 = last ? nA : cA + (size_t)(t + 2) * kstep; const char* b2 = last ? nB : cB + (size_t)(t + 2) * kstep;
;             const char* a3 = a2 + kstep; const char* b3 = b2 + kstep;
;             if (last && has_next) S.a_ready(nxt, ui + 1);
;             if constexpr (SP2) {
;             PG8_LDB(B0, 0, 0); PG8_LDB(B1, 0, 1); PG8_SCHED; PG8_LDA(At, 0, 0); PG8_STAGE(PG8_SA(1, 1), a1 + hstep, voffA);
;             PG8_WAIT_V(8); PG8_WAIT_L(0); PG8_BAR; PG8_MMA(0, 0, At, B0); PG8_MMA(0, 1, At, B1); PG8_BAR; PG8_SCHED;
;             PG8_LDA(At, 0, 1); PG8_STAGE(PG8_SB(0, 0), b2, voffB); PG8_STAGE(PG8_SB(0, 1), b2 + hstep, voffB); PG8_STAGE(PG8_SA(0, 0), a2, voffA);
;             PG8_WAIT_V(8); PG8_WAIT_L(0); PG8_BAR; PG8_MMA(1, 0, At, B0); PG8_MMA(1, 1, At, B1); PG8_BAR; PG8_SCHED;
.LBB0_337:
	ds_read_b128 v[152:155], v148
	ds_read_b128 v[156:159], v148 offset:1024
	ds_read_b128 v[160:163], v148 offset:2048
	ds_read_b128 v[164:167], v148 offset:3072
	ds_read_b128 v[168:171], v149
	ds_read_b128 v[172:175], v149 offset:1024
	ds_read_b128 v[176:179], v149 offset:2048
	ds_read_b128 v[180:183], v149 offset:3072
	s_add_u32 s26, s24, 0xfffc0080
	s_addc_u32 s27, s25, -1
	s_cmp_eq_u32 s54, 12
	s_cselect_b32 s29, s17, s27
	s_cselect_b32 s28, s50, s26
	s_cselect_b32 s27, s15, s53
	s_cselect_b32 s26, s51, s52
	s_add_i32 m0, s23, 0xc000
	ds_read_b128 v[184:187], v150
	ds_read_b128 v[188:191], v150 offset:1024
	ds_read_b128 v[192:195], v150 offset:2048
	ds_read_b128 v[196:199], v150 offset:3072
	ds_read_b128 v[200:203], v150 offset:4096
	ds_read_b128 v[204:207], v150 offset:5120
	ds_read_b128 v[208:211], v150 offset:6144
	ds_read_b128 v[212:215], v150 offset:7168
	global_load_lds_dwordx4 v136, s[24:25]
	s_add_i32 m0, s23, 0xe000
	s_nop 0
	global_load_lds_dwordx4 v138, s[24:25]
	s_waitcnt vmcnt(8)
	s_waitcnt lgkmcnt(0)
	s_setprio 1
	s_barrier
	v_mfma_f32_16x16x32_bf16 v[124:127], v[152:155], v[184:187], v[124:127]
	v_mfma_f32_16x16x32_bf16 v[120:123], v[160:163], v[184:187], v[120:123]
	v_mfma_f32_16x16x32_bf16 v[108:111], v[152:155], v[192:195], v[108:111]
	v_mfma_f32_16x16x32_bf16 v[104:107], v[160:163], v[192:195], v[104:107]
	v_mfma_f32_16x16x32_bf16 v[92:95], v[152:155], v[200:203], v[92:95]
	v_mfma_f32_16x16x32_bf16 v[88:91], v[160:163], v[200:203], v[88:91]
	v_mfma_f32_16x16x32_bf16 v[76:79], v[152:155], v[208:211], v[76:79]
	v_mfma_f32_16x16x32_bf16 v[72:75], v[160:163], v[208:211], v[72:75]
	v_mfma_f32_16x16x32_bf16 v[124:127], v[156:159], v[188:191], v[124:127]
	v_mfma_f32_16x16x32_bf16 v[120:123], v[164:167], v[188:191], v[120:123]
	v_mfma_f32_16x16x32_bf16 v[108:111], v[156:159], v[196:199], v[108:111]
	v_mfma_f32_16x16x32_bf16 v[104:107], v[164:167], v[196:199], v[104:107]
	v_mfma_f32_16x16x32_bf16 v[92:95], v[156:159], v[204:207], v[92:95]
	v_mfma_f32_16x16x32_bf16 v[88:91], v[164:167], v[204:207], v[88:91]
	v_mfma_f32_16x16x32_bf16 v[76:79], v[156:159], v[212:215], v[76:79]
	v_mfma_f32_16x16x32_bf16 v[72:75], v[164:167], v[212:215], v[72:75]
	v_mfma_f32_16x16x32_bf16 v[116:119], v[168:171], v[184:187], v[116:119]
	v_mfma_f32_16x16x32_bf16 v[112:115], v[176:179], v[184:187], v[112:115]
	v_mfma_f32_16x16x32_bf16 v[100:103], v[168:171], v[192:195], v[100:103]
	v_mfma_f32_16x16x32_bf16 v[96:99], v[176:179], v[192:195], v[96:99]
	v_mfma_f32_16x16x32_bf16 v[84:87], v[168:171], v[200:203], v[84:87]
	v_mfma_f32_16x16x32_bf16 v[80:83], v[176:179], v[200:203], v[80:83]
	v_mfma_f32_16x16x32_bf16 v[68:71], v[168:171], v[208:211], v[68:71]
	v_mfma_f32_16x16x32_bf16 v[64:67], v[176:179], v[208:211], v[64:67]
	v_mfma_f32_16x16x32_bf16 v[116:119], v[172:175], v[188:191], v[116:119]
	v_mfma_f32_16x16x32_bf16 v[112:115], v[180:183], v[188:191], v[112:115]
	v_mfma_f32_16x16x32_bf16 v[100:103], v[172:175], v[196:199], v[100:103]
	v_mfma_f32_16x16x32_bf16 v[96:99], v[180:183], v[196:199], v[96:99]
	v_mfma_f32_16x16x32_bf16 v[84:87], v[172:175], v[204:207], v[84:87]
	v_mfma_f32_16x16x32_bf16 v[80:83], v[180:183], v[204:207], v[80:83]
	v_mfma_f32_16x16x32_bf16 v[68:71], v[172:175], v[212:215], v[68:71]
	s_setprio 0
	v_mfma_f32_16x16x32_bf16 v[64:67], v[180:183], v[212:215], v[64:67]
	s_barrier
	s_add_i32 s55, s44, s33
	v_lshl_add_u64 v[216:217], s[26:27], 0, v[132:133]
	s_mov_b32 m0, s55
	ds_read_b128 v[184:187], v150 offset:16384
	ds_read_b128 v[188:191], v150 offset:17408
	ds_read_b128 v[192:195], v150 offset:18432
	ds_read_b128 v[196:199], v150 offset:19456
	ds_read_b128 v[200:203], v150 offset:20480
	ds_read_b128 v[204:207], v150 offset:21504
	ds_read_b128 v[208:211], v150 offset:22528
	ds_read_b128 v[212:215], v150 offset:23552
	global_load_lds_dwordx4 v[216:217], off
	s_add_i32 m0, s55, 0x2000
	s_add_u32 s56, s26, 0x40000
	v_lshl_add_u64 v[218:219], s[26:27], 0, v[128:129]
	s_addc_u32 s57, s27, 0
	s_add_i32 s55, s45, s33
	global_load_lds_dwordx4 v[218:219], off
	s_mov_b32 m0, s55
	v_lshl_add_u64 v[222:223], s[28:29], 0, v[130:131]
	global_load_lds_dwordx4 v132, s[56:57]
	s_add_i32 m0, s55, 0x2000
	s_nop 0
	global_load_lds_dwordx4 v128, s[56:57]
	v_lshl_add_u64 v[220:221], s[28:29], 0, v[134:135]
	s_mov_b32 m0, s23
	s_nop 0
	global_load_lds_dwordx4 v[220:221], off
	s_mov_b32 m0, s39
	s_nop 0
	global_load_lds_dwordx4 v[222:223], off
	s_waitcnt vmcnt(8)
	s_waitcnt lgkmcnt(0)
	s_setprio 1
	s_barrier
	v_mfma_f32_16x16x32_bf16 v[60:63], v[152:155], v[184:187], v[60:63]
	v_mfma_f32_16x16x32_bf16 v[56:59], v[160:163], v[184:187], v[56:59]
	v_mfma_f32_16x16x32_bf16 v[44:47], v[152:155], v[192:195], v[44:47]
	v_mfma_f32_16x16x32_bf16 v[40:43], v[160:163], v[192:195], v[40:43]
	v_mfma_f32_16x16x32_bf16 v[28:31], v[152:155], v[200:203], v[28:31]
	v_mfma_f32_16x16x32_bf16 v[24:27], v[160:163], v[200:203], v[24:27]
	v_mfma_f32_16x16x32_bf16 v[12:15], v[152:155], v[208:211], v[12:15]
	v_mfma_f32_16x16x32_bf16 v[8:11], v[160:163], v[208:211], v[8:11]
	v_mfma_f32_16x16x32_bf16 v[60:63], v[156:159], v[188:191], v[60:63]
	v_mfma_f32_16x16x32_bf16 v[56:59], v[164:167], v[188:191], v[56:59]
	v_mfma_f32_16x16x32_bf16 v[44:47], v[156:159], v[196:199], v[44:47]
	v_mfma_f32_16x16x32_bf16 v[40:43], v[164:167], v[196:199], v[40:43]
	v_mfma_f32_16x16x32_bf16 v[28:31], v[156:159], v[204:207], v[28:31]
	v_mfma_f32_16x16x32_bf16 v[24:27], v[164:167], v[204:207], v[24:27]
	v_mfma_f32_16x16x32_bf16 v[12:15], v[156:159], v[212:215], v[12:15]
	v_mfma_f32_16x16x32_bf16 v[8:11], v[164:167], v[212:215], v[8:11]
	v_mfma_f32_16x16x32_bf16 v[52:55], v[168:171], v[184:187], v[52:55]
	v_mfma_f32_16x16x32_bf16 v[48:51], v[176:179], v[184:187], v[48:51]
	v_mfma_f32_16x16x32_bf16 v[36:39], v[168:171], v[192:195], v[36:39]
	v_mfma_f32_16x16x32_bf16 v[32:35], v[176:179], v[192:195], v[32:35]
	v_mfma_f32_16x16x32_bf16 v[20:23], v[168:171], v[200:203], v[20:23]
	v_mfma_f32_16x16x32_bf16 v[16:19], v[176:179], v[200:203], v[16:19]
	v_mfma_f32_16x16x32_bf16 v[4:7], v[168:171], v[208:211], v[4:7]
	v_mfma_f32_16x16x32_bf16 v[0:3], v[176:179], v[208:211], v[0:3]
	v_mfma_f32_16x16x32_bf16 v[52:55], v[172:175], v[188:191], v[52:55]
	v_mfma_f32_16x16x32_bf16 v[48:51], v[180:183], v[188:191], v[48:51]
	v_mfma_f32_16x16x32_bf16 v[36:39], v[172:175], v[196:199], v[36:39]
	v_mfma_f32_16x16x32_bf16 v[32:35], v[180:183], v[196:199], v[32:35]
	v_mfma_f32_16x16x32_bf16 v[20:23], v[172:175], v[204:207], v[20:23]
	v_mfma_f32_16x16x32_bf16 v[16:19], v[180:183], v[204:207], v[16:19]
	v_mfma_f32_16x16x32_bf16 v[4:7], v[172:175], v[212:215], v[4:7]
	s_setprio 0
	v_mfma_f32_16x16x32_bf16 v[0:3], v[180:183], v[212:215], v[0:3]
	s_barrier
; #define PG8_STAGE(bufoff, gbase, voff) do { _Pragma("unroll") for (int _i = 0; _i < 2; ++_i) \
;         __builtin_amdgcn_global_load_lds((const unsigned*)((const char*)(gbase) + (voff)[_i]), (PG8_LAS unsigned*)(lds + (bufoff) + ldsw + _i * 8192), 16, 0, 0); } while (0)
; #define PG8_LDA(dst, b, h) do { _Pragma("unroll") for (int m = 0; m < 4; ++m) _Pragma("unroll") for (int k = 0; k < 2; ++k) dst[m][k] = *(const PG8_LAS bf16x8*)(lds + PG8_SA(b, h) + aoff + m * 2048 + k * 1024); } while (0)
; #define PG8_LDB(dst, b, h) do { _Pragma("unroll") for (int n = 0; n < 2; ++n) _Pragma("unroll") for (int k = 0; k < 2; ++k) dst[n][k] = *(const PG8_LAS bf16x8*)(lds + PG8_SB(b, h) + boff + n * 2048 + k * 1024); } while (0)
; #define PG8_MMA(ai, bj, At, Bt) do { __builtin_amdgcn_s_setprio(1); _Pragma("unroll") for (int m = 0; m < 4; ++m) _Pragma("unroll") for (int n = 0; n < 2; ++n) _Pragma("unroll") for (int k = 0; k < 2; ++k) \
;         acc[ai][bj][m][n] = __builtin_amdgcn_mfma_f32_16x16x32_bf16(Bt[n][k], At[m][k], acc[ai][bj][m][n], 0, 0, 0); __builtin_amdgcn_s_setprio(0); } while (0)
; #define PG8_WAIT_V(n) asm volatile("s_waitcnt vmcnt(" #n ")" ::: "memory")
; #define PG8_WAIT_L(n) asm volatile("s_waitcnt lgkmcnt(" #n ")" ::: "memory")
; #define PG8_BAR __builtin_amdgcn_s_barrier()
; #define PG8_SCHED __builtin_amdgcn_sched_barrier(0)
; template <class Epi, class Sched, bool ALIGN_EPI = false, bool SP2 = false>
; __device__ __forceinline__ void gemm_phase(PG8_LAS unsigned char* lds, const Gemm g, const Sched& S, const Epi& E) {
;     ...
;             PG8_LDB(B0, 1, 0); PG8_LDB(B1, 1, 1); PG8_SCHED; PG8_LDA(At, 1, 0); PG8_STAGE(PG8_SA(0, 1), a2 + hstep, voffA);
;             PG8_WAIT_V(8); PG8_WAIT_L(0); PG8_BAR; PG8_MMA(0, 0, At, B0); PG8_MMA(0, 1, At, B1); PG8_BAR; PG8_SCHED;
;             PG8_LDA(At, 1, 1); PG8_STAGE(PG8_SB(1, 0), b3, voffB); PG8_STAGE(PG8_SB(1, 1), b3 + hstep, voffB); PG8_STAGE(PG8_SA(1, 0), a3, voffA);
;             PG8_WAIT_V(8); PG8_WAIT_L(0); PG8_BAR; PG8_MMA(1, 0, At, B0); PG8_MMA(1, 1, At, B1); PG8_BAR; PG8_SCHED;
;     ...
;         if constexpr (ALIGN_EPI) { if (wr == 0) PG8_BAR; }
	s_add_i32 s55, 0, 0x18000
	v_add_u32_e32 v151, s55, v145
	s_add_i32 s56, 0, 0x1c000
	ds_read_b128 v[152:155], v151
	ds_read_b128 v[156:159], v151 offset:1024
	ds_read_b128 v[160:163], v151 offset:2048
	ds_read_b128 v[164:167], v151 offset:3072
	v_add_u32_e32 v151, s56, v145
	ds_read_b128 v[168:171], v151
	ds_read_b128 v[172:175], v151 offset:1024
	ds_read_b128 v[176:179], v151 offset:2048
	ds_read_b128 v[180:183], v151 offset:3072
	s_add_u32 s28, s28, 0x40000
	s_addc_u32 s29, s29, 0
	s_mov_b32 m0, s40
	ds_read_b128 v[184:187], v150 offset:32768
	ds_read_b128 v[188:191], v150 offset:33792
	ds_read_b128 v[192:195], v150 offset:34816
	ds_read_b128 v[196:199], v150 offset:35840
	ds_read_b128 v[200:203], v150 offset:36864
	ds_read_b128 v[204:207], v150 offset:37888
	ds_read_b128 v[208:211], v150 offset:38912
	ds_read_b128 v[212:215], v150 offset:39936
	global_load_lds_dwordx4 v134, s[28:29]
	s_mov_b32 m0, s41
	s_nop 0
	global_load_lds_dwordx4 v130, s[28:29]
	s_waitcnt vmcnt(8)
	s_waitcnt lgkmcnt(0)
	s_setprio 1
	s_barrier
	v_mfma_f32_16x16x32_bf16 v[124:127], v[152:155], v[184:187], v[124:127]
	v_mfma_f32_16x16x32_bf16 v[120:123], v[160:163], v[184:187], v[120:123]
	v_mfma_f32_16x16x32_bf16 v[108:111], v[152:155], v[192:195], v[108:111]
	v_mfma_f32_16x16x32_bf16 v[104:107], v[160:163], v[192:195], v[104:107]
	v_mfma_f32_16x16x32_bf16 v[92:95], v[152:155], v[200:203], v[92:95]
	v_mfma_f32_16x16x32_bf16 v[88:91], v[160:163], v[200:203], v[88:91]
	v_mfma_f32_16x16x32_bf16 v[76:79], v[152:155], v[208:211], v[76:79]
	v_mfma_f32_16x16x32_bf16 v[72:75], v[160:163], v[208:211], v[72:75]
	v_mfma_f32_16x16x32_bf16 v[124:127], v[156:159], v[188:191], v[124:127]
	v_mfma_f32_16x16x32_bf16 v[120:123], v[164:167], v[188:191], v[120:123]
	v_mfma_f32_16x16x32_bf16 v[108:111], v[156:159], v[196:199], v[108:111]
	v_mfma_f32_16x16x32_bf16 v[104:107], v[164:167], v[196:199], v[104:107]
	v_mfma_f32_16x16x32_bf16 v[92:95], v[156:159], v[204:207], v[92:95]
	v_mfma_f32_16x16x32_bf16 v[88:91], v[164:167], v[204:207], v[88:91]
	v_mfma_f32_16x16x32_bf16 v[76:79], v[156:159], v[212:215], v[76:79]
	v_mfma_f32_16x16x32_bf16 v[72:75], v[164:167], v[212:215], v[72:75]
	v_mfma_f32_16x16x32_bf16 v[116:119], v[168:171], v[184:187], v[116:119]
	v_mfma_f32_16x16x32_bf16 v[112:115], v[176:179], v[184:187], v[112:115]
	v_mfma_f32_16x16x32_bf16 v[100:103], v[168:171], v[192:195], v[100:103]
	v_mfma_f32_16x16x32_bf16 v[96:99], v[176:179], v[192:195], v[96:99]
	v_mfma_f32_16x16x32_bf16 v[84:87], v[168:171], v[200:203], v[84:87]
	v_mfma_f32_16x16x32_bf16 v[80:83], v[176:179], v[200:203], v[80:83]
	v_mfma_f32_16x16x32_bf16 v[68:71], v[168:171], v[208:211], v[68:71]
	v_mfma_f32_16x16x32_bf16 v[64:67], v[176:179], v[208:211], v[64:67]
	v_mfma_f32_16x16x32_bf16 v[116:119], v[172:175], v[188:191], v[116:119]
	v_mfma_f32_16x16x32_bf16 v[112:115], v[180:183], v[188:191], v[112:115]
	v_mfma_f32_16x16x32_bf16 v[100:103], v[172:175], v[196:199], v[100:103]
	v_mfma_f32_16x16x32_bf16 v[96:99], v[180:183], v[196:199], v[96:99]
	v_mfma_f32_16x16x32_bf16 v[84:87], v[172:175], v[204:207], v[84:87]
	v_mfma_f32_16x16x32_bf16 v[80:83], v[180:183], v[204:207], v[80:83]
	v_mfma_f32_16x16x32_bf16 v[68:71], v[172:175], v[212:215], v[68:71]
	s_setprio 0
	v_mfma_f32_16x16x32_bf16 v[64:67], v[180:183], v[212:215], v[64:67]
	s_barrier
	s_add_i32 s28, s55, s33
	v_lshl_add_u64 v[216:217], v[216:217], 0, s[8:9]
	s_mov_b32 m0, s28
	ds_read_b128 v[184:187], v150 offset:49152
	ds_read_b128 v[188:191], v150 offset:50176
	ds_read_b128 v[192:195], v150 offset:51200
	ds_read_b128 v[196:199], v150 offset:52224
	ds_read_b128 v[200:203], v150 offset:53248
	ds_read_b128 v[204:207], v150 offset:54272
	ds_read_b128 v[208:211], v150 offset:55296
	ds_read_b128 v[212:215], v150 offset:56320
	global_load_lds_dwordx4 v[216:217], off
	s_add_i32 m0, s28, 0x2000
	s_add_u32 s26, s26, 0x40080
	v_lshl_add_u64 v[216:217], v[218:219], 0, s[8:9]
	s_addc_u32 s27, s27, 0
	s_add_i32 s28, s56, s33
	global_load_lds_dwordx4 v[216:217], off
	s_mov_b32 m0, s28
	s_nop 0
	global_load_lds_dwordx4 v132, s[26:27]
	s_add_i32 m0, s28, 0x2000
	s_nop 0
	global_load_lds_dwordx4 v128, s[26:27]
	v_lshl_add_u64 v[216:217], v[220:221], 0, s[8:9]
	s_mov_b32 m0, s42
	s_nop 0
	global_load_lds_dwordx4 v[216:217], off
	v_lshl_add_u64 v[216:217], v[222:223], 0, s[8:9]
	s_mov_b32 m0, s43
	s_nop 0
	global_load_lds_dwordx4 v[216:217], off
	s_waitcnt vmcnt(8)
	s_waitcnt lgkmcnt(0)
	s_setprio 1
	s_barrier
	v_mfma_f32_16x16x32_bf16 v[60:63], v[152:155], v[184:187], v[60:63]
	v_mfma_f32_16x16x32_bf16 v[56:59], v[160:163], v[184:187], v[56:59]
	v_mfma_f32_16x16x32_bf16 v[44:47], v[152:155], v[192:195], v[44:47]
	v_mfma_f32_16x16x32_bf16 v[40:43], v[160:163], v[192:195], v[40:43]
	v_mfma_f32_16x16x32_bf16 v[28:31], v[152:155], v[200:203], v[28:31]
	v_mfma_f32_16x16x32_bf16 v[24:27], v[160:163], v[200:203], v[24:27]
	v_mfma_f32_16x16x32_bf16 v[12:15], v[152:155], v[208:211], v[12:15]
	v_mfma_f32_16x16x32_bf16 v[8:11], v[160:163], v[208:211], v[8:11]
	v_mfma_f32_16x16x32_bf16 v[60:63], v[156:159], v[188:191], v[60:63]
	v_mfma_f32_16x16x32_bf16 v[56:59], v[164:167], v[188:191], v[56:59]
	v_mfma_f32_16x16x32_bf16 v[44:47], v[156:159], v[196:199], v[44:47]
	v_mfma_f32_16x16x32_bf16 v[40:43], v[164:167], v[196:199], v[40:43]
	v_mfma_f32_16x16x32_bf16 v[28:31], v[156:159], v[204:207], v[28:31]
	v_mfma_f32_16x16x32_bf16 v[24:27], v[164:167], v[204:207], v[24:27]
	v_mfma_f32_16x16x32_bf16 v[12:15], v[156:159], v[212:215], v[12:15]
	v_mfma_f32_16x16x32_bf16 v[8:11], v[164:167], v[212:215], v[8:11]
	v_mfma_f32_16x16x32_bf16 v[52:55], v[168:171], v[184:187], v[52:55]
	v_mfma_f32_16x16x32_bf16 v[48:51], v[176:179], v[184:187], v[48:51]
	v_mfma_f32_16x16x32_bf16 v[36:39], v[168:171], v[192:195], v[36:39]
	v_mfma_f32_16x16x32_bf16 v[32:35], v[176:179], v[192:195], v[32:35]
	v_mfma_f32_16x16x32_bf16 v[20:23], v[168:171], v[200:203], v[20:23]
	v_mfma_f32_16x16x32_bf16 v[16:19], v[176:179], v[200:203], v[16:19]
	v_mfma_f32_16x16x32_bf16 v[4:7], v[168:171], v[208:211], v[4:7]
	v_mfma_f32_16x16x32_bf16 v[0:3], v[176:179], v[208:211], v[0:3]
	v_mfma_f32_16x16x32_bf16 v[52:55], v[172:175], v[188:191], v[52:55]
	v_mfma_f32_16x16x32_bf16 v[48:51], v[180:183], v[188:191], v[48:51]
	v_mfma_f32_16x16x32_bf16 v[36:39], v[172:175], v[196:199], v[36:39]
	v_mfma_f32_16x16x32_bf16 v[32:35], v[180:183], v[196:199], v[32:35]
	v_mfma_f32_16x16x32_bf16 v[20:23], v[172:175], v[204:207], v[20:23]
	v_mfma_f32_16x16x32_bf16 v[16:19], v[180:183], v[204:207], v[16:19]
	v_mfma_f32_16x16x32_bf16 v[4:7], v[172:175], v[212:215], v[4:7]
	s_setprio 0
	v_mfma_f32_16x16x32_bf16 v[0:3], v[180:183], v[212:215], v[0:3]
	s_barrier
	s_add_i32 s54, s54, 2
	s_add_u32 s24, s24, 0x100
	s_addc_u32 s25, s25, 0
	s_add_u32 s52, s52, 0x100
	s_addc_u32 s53, s53, 0
	s_cmp_gt_u32 s54, 13
	s_cbranch_scc0 .LBB0_337
	s_and_b64 vcc, exec, s[12:13]
	s_cbranch_vccz .LBB0_340
	s_barrier

; #define PG8_STAGE(bufoff, gbase, voff) do { _Pragma("unroll") for (int _i = 0; _i < 2; ++_i) \
;         __builtin_amdgcn_global_load_lds((const unsigned*)((const char*)(gbase) + (voff)[_i]), (PG8_LAS unsigned*)(lds + (bufoff) + ldsw + _i * 8192), 16, 0, 0); } while (0)
; #define PG8_LDA(dst, b, h) do { _Pragma("unroll") for (int m = 0; m < 4; ++m) _Pragma("unroll") for (int k = 0; k < 2; ++k) dst[m][k] = *(const PG8_LAS bf16x8*)(lds + PG8_SA(b, h) + aoff + m * 2048 + k * 1024); } while (0)
; #define PG8_LDB(dst, b, h) do { _Pragma("unroll") for (int n = 0; n < 2; ++n) _Pragma("unroll") for (int k = 0; k < 2; ++k) dst[n][k] = *(const PG8_LAS bf16x8*)(lds + PG8_SB(b, h) + boff + n * 2048 + k * 1024); } while (0)
; #define PG8_MMA(ai, bj, At, Bt) do { __builtin_amdgcn_s_setprio(1); _Pragma("unroll") for (int m = 0; m < 4; ++m) _Pragma("unroll") for (int n = 0; n < 2; ++n) _Pragma("unroll") for (int k = 0; k < 2; ++k) \
;         acc[ai][bj][m][n] = __builtin_amdgcn_mfma_f32_16x16x32_bf16(Bt[n][k], At[m][k], acc[ai][bj][m][n], 0, 0, 0); __builtin_amdgcn_s_setprio(0); } while (0)
; #define PG8_WAIT_V(n) asm volatile("s_waitcnt vmcnt(" #n ")" ::: "memory")
; #define PG8_WAIT_L(n) asm volatile("s_waitcnt lgkmcnt(" #n ")" ::: "memory")
; template <class Epi, class Sched, bool ALIGN_EPI = false, bool SP2 = false>
; __device__ __forceinline__ void gemm_phase(PG8_LAS unsigned char* lds, const Gemm g, const Sched& S, const Epi& E) {
;     ...
;             const bool last = (t == nt - 2);
;             const char* a1 = cA + (size_t)(t + 1) * kstep;
;             const char* a2 = last ? nA : cA + (size_t)(t + 2) * kstep; const char* b2 = last ? nB : cB + (size_t)(t + 2) * kstep;
;             const char* a3 = a2 + kstep; const char* b3 = b2 + kstep;
;             if (last && has_next) S.a_ready(nxt, ui + 1);
;             if constexpr (SP2) {
;             PG8_LDB(B0, 0, 0); PG8_LDB(B1, 0, 1); PG8_SCHED; PG8_LDA(At, 0, 0); PG8_STAGE(PG8_SA(1, 1), a1 + hstep, voffA);
;             PG8_WAIT_V(8); PG8_WAIT_L(0); PG8_BAR; PG8_MMA(0, 0, At, B0); PG8_MMA(0, 1, At, B1); PG8_BAR; PG8_SCHED;
;             PG8_LDA(At, 0, 1); PG8_STAGE(PG8_SB(0, 0), b2, voffB); PG8_STAGE(PG8_SB(0, 1), b2 + hstep, voffB); PG8_STAGE(PG8_SA(0, 0), a2, voffA);
;             PG8_WAIT_V(8); PG8_WAIT_L(0); PG8_BAR; PG8_MMA(1, 0, At, B0); PG8_MMA(1, 1, At, B1); PG8_BAR; PG8_SCHED;
.LBB0_417:
	s_add_u32 s24, s24, 0xb0080
	s_addc_u32 s25, s25, 0
	s_add_u32 s51, s26, 0x100
	s_addc_u32 s52, s27, 0
	s_mov_b32 s53, -2
	s_waitcnt lgkmcnt(0)
	s_add_u32 s26, s24, 0xfff50080
	s_addc_u32 s27, s25, -1
	s_cmp_eq_u32 s53, 40
	s_cselect_b32 s29, s7, s27
	s_cselect_b32 s28, s6, s26
	s_cselect_b32 s27, s23, s52
	s_cselect_b32 s26, s22, s51
	s_add_i32 m0, s35, 0xc000
	s_nop 0
	global_load_lds_dwordx4 v200, s[24:25]
	s_add_i32 m0, s35, 0xe000
	s_nop 0
	global_load_lds_dwordx4 v202, s[24:25]
	s_waitcnt vmcnt(8)
	s_waitcnt lgkmcnt(0)
	s_setprio 1
	s_barrier
	v_mfma_f32_16x16x32_bf16 v[132:135], v[120:123], v[160:163], 0
	v_mfma_f32_16x16x32_bf16 v[124:127], v[136:139], v[160:163], 0
	v_mfma_f32_16x16x32_bf16 v[108:111], v[120:123], v[168:171], 0
	v_mfma_f32_16x16x32_bf16 v[104:107], v[136:139], v[168:171], 0
	v_mfma_f32_16x16x32_bf16 v[92:95], v[120:123], v[176:179], 0
	v_mfma_f32_16x16x32_bf16 v[88:91], v[136:139], v[176:179], 0
	v_mfma_f32_16x16x32_bf16 v[76:79], v[120:123], v[184:187], 0
	v_mfma_f32_16x16x32_bf16 v[72:75], v[136:139], v[184:187], 0
	v_mfma_f32_16x16x32_bf16 v[132:135], v[128:131], v[164:167], v[132:135]
	v_mfma_f32_16x16x32_bf16 v[124:127], v[140:143], v[164:167], v[124:127]
	v_mfma_f32_16x16x32_bf16 v[108:111], v[128:131], v[172:175], v[108:111]
	v_mfma_f32_16x16x32_bf16 v[104:107], v[140:143], v[172:175], v[104:107]
	v_mfma_f32_16x16x32_bf16 v[92:95], v[128:131], v[180:183], v[92:95]
	v_mfma_f32_16x16x32_bf16 v[88:91], v[140:143], v[180:183], v[88:91]
	v_mfma_f32_16x16x32_bf16 v[76:79], v[128:131], v[188:191], v[76:79]
	v_mfma_f32_16x16x32_bf16 v[72:75], v[140:143], v[188:191], v[72:75]
	v_mfma_f32_16x16x32_bf16 v[116:119], v[144:147], v[160:163], 0
	v_mfma_f32_16x16x32_bf16 v[112:115], v[152:155], v[160:163], 0
	v_mfma_f32_16x16x32_bf16 v[100:103], v[144:147], v[168:171], 0
	v_mfma_f32_16x16x32_bf16 v[96:99], v[152:155], v[168:171], 0
	v_mfma_f32_16x16x32_bf16 v[84:87], v[144:147], v[176:179], 0
	v_mfma_f32_16x16x32_bf16 v[80:83], v[152:155], v[176:179], 0
	v_mfma_f32_16x16x32_bf16 v[68:71], v[144:147], v[184:187], 0
	v_mfma_f32_16x16x32_bf16 v[64:67], v[152:155], v[184:187], 0
	v_mfma_f32_16x16x32_bf16 v[116:119], v[148:151], v[164:167], v[116:119]
	v_mfma_f32_16x16x32_bf16 v[112:115], v[156:159], v[164:167], v[112:115]
	v_mfma_f32_16x16x32_bf16 v[100:103], v[148:151], v[172:175], v[100:103]
	v_mfma_f32_16x16x32_bf16 v[96:99], v[156:159], v[172:175], v[96:99]
	v_mfma_f32_16x16x32_bf16 v[84:87], v[148:151], v[180:183], v[84:87]
	v_mfma_f32_16x16x32_bf16 v[80:83], v[156:159], v[180:183], v[80:83]
	v_mfma_f32_16x16x32_bf16 v[68:71], v[148:151], v[188:191], v[68:71]
	s_setprio 0
	v_mfma_f32_16x16x32_bf16 v[64:67], v[156:159], v[188:191], v[64:67]
	s_barrier
	s_add_i32 s54, s45, s34
	v_lshl_add_u64 v[204:205], s[26:27], 0, v[194:195]
	s_mov_b32 m0, s54
	ds_read_b128 v[160:163], v247 offset:16384
	ds_read_b128 v[164:167], v247 offset:17408
	ds_read_b128 v[168:171], v247 offset:18432
	ds_read_b128 v[172:175], v247 offset:19456
	ds_read_b128 v[176:179], v247 offset:20480
	ds_read_b128 v[180:183], v247 offset:21504
	ds_read_b128 v[184:187], v247 offset:22528
	ds_read_b128 v[188:191], v247 offset:23552
	global_load_lds_dwordx4 v[204:205], off
	s_add_i32 m0, s54, 0x2000
	s_add_u32 s54, s26, 0xb0000
	v_lshl_add_u64 v[206:207], s[26:27], 0, v[198:199]
	s_addc_u32 s55, s27, 0
	s_add_i32 s56, s46, s34
	global_load_lds_dwordx4 v[206:207], off
	s_mov_b32 m0, s56
	v_lshl_add_u64 v[210:211], s[28:29], 0, v[196:197]
	global_load_lds_dwordx4 v194, s[54:55]
	s_add_i32 m0, s56, 0x2000
	s_nop 0
	global_load_lds_dwordx4 v198, s[54:55]
	v_lshl_add_u64 v[208:209], s[28:29], 0, v[192:193]
	s_mov_b32 m0, s35
	s_nop 0
	global_load_lds_dwordx4 v[208:209], off
	s_mov_b32 m0, s36
	s_nop 0
	global_load_lds_dwordx4 v[210:211], off
	s_waitcnt vmcnt(8)
	s_waitcnt lgkmcnt(0)
	s_setprio 1
	s_barrier
	v_mfma_f32_16x16x32_bf16 v[60:63], v[120:123], v[160:163], 0
	v_mfma_f32_16x16x32_bf16 v[56:59], v[136:139], v[160:163], 0
	v_mfma_f32_16x16x32_bf16 v[44:47], v[120:123], v[168:171], 0
	v_mfma_f32_16x16x32_bf16 v[40:43], v[136:139], v[168:171], 0
	v_mfma_f32_16x16x32_bf16 v[28:31], v[120:123], v[176:179], 0
	v_mfma_f32_16x16x32_bf16 v[24:27], v[136:139], v[176:179], 0
	v_mfma_f32_16x16x32_bf16 v[12:15], v[120:123], v[184:187], 0
	v_mfma_f32_16x16x32_bf16 v[8:11], v[136:139], v[184:187], 0
	v_mfma_f32_16x16x32_bf16 v[60:63], v[128:131], v[164:167], v[60:63]
	v_mfma_f32_16x16x32_bf16 v[56:59], v[140:143], v[164:167], v[56:59]
	v_mfma_f32_16x16x32_bf16 v[44:47], v[128:131], v[172:175], v[44:47]
	v_mfma_f32_16x16x32_bf16 v[40:43], v[140:143], v[172:175], v[40:43]
	v_mfma_f32_16x16x32_bf16 v[28:31], v[128:131], v[180:183], v[28:31]
	v_mfma_f32_16x16x32_bf16 v[24:27], v[140:143], v[180:183], v[24:27]
	v_mfma_f32_16x16x32_bf16 v[12:15], v[128:131], v[188:191], v[12:15]
	v_mfma_f32_16x16x32_bf16 v[8:11], v[140:143], v[188:191], v[8:11]
	v_mfma_f32_16x16x32_bf16 v[52:55], v[144:147], v[160:163], 0
	v_mfma_f32_16x16x32_bf16 v[48:51], v[152:155], v[160:163], 0
	v_mfma_f32_16x16x32_bf16 v[36:39], v[144:147], v[168:171], 0
	v_mfma_f32_16x16x32_bf16 v[32:35], v[152:155], v[168:171], 0
	v_mfma_f32_16x16x32_bf16 v[20:23], v[144:147], v[176:179], 0
	v_mfma_f32_16x16x32_bf16 v[16:19], v[152:155], v[176:179], 0
	v_mfma_f32_16x16x32_bf16 v[4:7], v[144:147], v[184:187], 0
	v_mfma_f32_16x16x32_bf16 v[0:3], v[152:155], v[184:187], 0
	v_mfma_f32_16x16x32_bf16 v[52:55], v[148:151], v[164:167], v[52:55]
	v_mfma_f32_16x16x32_bf16 v[48:51], v[156:159], v[164:167], v[48:51]
	v_mfma_f32_16x16x32_bf16 v[36:39], v[148:151], v[172:175], v[36:39]
	v_mfma_f32_16x16x32_bf16 v[32:35], v[156:159], v[172:175], v[32:35]
	v_mfma_f32_16x16x32_bf16 v[20:23], v[148:151], v[180:183], v[20:23]
	v_mfma_f32_16x16x32_bf16 v[16:19], v[156:159], v[180:183], v[16:19]
	v_mfma_f32_16x16x32_bf16 v[4:7], v[148:151], v[188:191], v[4:7]
	s_setprio 0
	v_mfma_f32_16x16x32_bf16 v[0:3], v[156:159], v[188:191], v[0:3]
	s_barrier
; #define PG8_STAGE(bufoff, gbase, voff) do { _Pragma("unroll") for (int _i = 0; _i < 2; ++_i) \
;         __builtin_amdgcn_global_load_lds((const unsigned*)((const char*)(gbase) + (voff)[_i]), (PG8_LAS unsigned*)(lds + (bufoff) + ldsw + _i * 8192), 16, 0, 0); } while (0)
; #define PG8_LDA(dst, b, h) do { _Pragma("unroll") for (int m = 0; m < 4; ++m) _Pragma("unroll") for (int k = 0; k < 2; ++k) dst[m][k] = *(const PG8_LAS bf16x8*)(lds + PG8_SA(b, h) + aoff + m * 2048 + k * 1024); } while (0)
; #define PG8_LDB(dst, b, h) do { _Pragma("unroll") for (int n = 0; n < 2; ++n) _Pragma("unroll") for (int k = 0; k < 2; ++k) dst[n][k] = *(const PG8_LAS bf16x8*)(lds + PG8_SB(b, h) + boff + n * 2048 + k * 1024); } while (0)
; #define PG8_MMA(ai, bj, At, Bt) do { __builtin_amdgcn_s_setprio(1); _Pragma("unroll") for (int m = 0; m < 4; ++m) _Pragma("unroll") for (int n = 0; n < 2; ++n) _Pragma("unroll") for (int k = 0; k < 2; ++k) \
;         acc[ai][bj][m][n] = __builtin_amdgcn_mfma_f32_16x16x32_bf16(Bt[n][k], At[m][k], acc[ai][bj][m][n], 0, 0, 0); __builtin_amdgcn_s_setprio(0); } while (0)
; #define PG8_WAIT_V(n) asm volatile("s_waitcnt vmcnt(" #n ")" ::: "memory")
; #define PG8_WAIT_L(n) asm volatile("s_waitcnt lgkmcnt(" #n ")" ::: "memory")
; #define PG8_BAR __builtin_amdgcn_s_barrier()
; #define PG8_SCHED __builtin_amdgcn_sched_barrier(0)
; template <class Epi, class Sched, bool ALIGN_EPI = false, bool SP2 = false>
; __device__ __forceinline__ void gemm_phase(PG8_LAS unsigned char* lds, const Gemm g, const Sched& S, const Epi& E) {
;     ...
;             PG8_LDB(B0, 1, 0); PG8_LDB(B1, 1, 1); PG8_SCHED; PG8_LDA(At, 1, 0); PG8_STAGE(PG8_SA(0, 1), a2 + hstep, voffA);
;             PG8_WAIT_V(8); PG8_WAIT_L(0); PG8_BAR; PG8_MMA(0, 0, At, B0); PG8_MMA(0, 1, At, B1); PG8_BAR; PG8_SCHED;
;             PG8_LDA(At, 1, 1); PG8_STAGE(PG8_SB(1, 0), b3, voffB); PG8_STAGE(PG8_SB(1, 1), b3 + hstep, voffB); PG8_STAGE(PG8_SA(1, 0), a3, voffA);
;             PG8_WAIT_V(8); PG8_WAIT_L(0); PG8_BAR; PG8_MMA(1, 0, At, B0); PG8_MMA(1, 1, At, B1); PG8_BAR; PG8_SCHED;
	s_add_i32 s54, 0, 0x18000
	s_add_i32 s55, 0, 0x1c000
	v_add_u32_e32 v140, s54, v243
	v_add_u32_e32 v156, s55, v243
	ds_read_b128 v[120:123], v140
	ds_read_b128 v[128:131], v140 offset:1024
	ds_read_b128 v[136:139], v140 offset:2048
	ds_read_b128 v[140:143], v140 offset:3072
	ds_read_b128 v[144:147], v156
	ds_read_b128 v[148:151], v156 offset:1024
	ds_read_b128 v[152:155], v156 offset:2048
	ds_read_b128 v[156:159], v156 offset:3072
	s_add_u32 s28, s28, 0xb0000
	s_addc_u32 s29, s29, 0
	s_mov_b32 m0, s37
	ds_read_b128 v[160:163], v247 offset:32768
	ds_read_b128 v[164:167], v247 offset:33792
	ds_read_b128 v[168:171], v247 offset:34816
	ds_read_b128 v[172:175], v247 offset:35840
	ds_read_b128 v[176:179], v247 offset:36864
	ds_read_b128 v[180:183], v247 offset:37888
	ds_read_b128 v[184:187], v247 offset:38912
	ds_read_b128 v[188:191], v247 offset:39936
	global_load_lds_dwordx4 v192, s[28:29]
	s_mov_b32 m0, s38
	s_nop 0
	global_load_lds_dwordx4 v196, s[28:29]
	s_waitcnt vmcnt(8)
	s_waitcnt lgkmcnt(0)
	s_setprio 1
	s_barrier
	v_mfma_f32_16x16x32_bf16 v[132:135], v[120:123], v[160:163], v[132:135]
	v_mfma_f32_16x16x32_bf16 v[124:127], v[136:139], v[160:163], v[124:127]
	v_mfma_f32_16x16x32_bf16 v[108:111], v[120:123], v[168:171], v[108:111]
	v_mfma_f32_16x16x32_bf16 v[104:107], v[136:139], v[168:171], v[104:107]
	v_mfma_f32_16x16x32_bf16 v[92:95], v[120:123], v[176:179], v[92:95]
	v_mfma_f32_16x16x32_bf16 v[88:91], v[136:139], v[176:179], v[88:91]
	v_mfma_f32_16x16x32_bf16 v[76:79], v[120:123], v[184:187], v[76:79]
	v_mfma_f32_16x16x32_bf16 v[72:75], v[136:139], v[184:187], v[72:75]
	v_mfma_f32_16x16x32_bf16 v[132:135], v[128:131], v[164:167], v[132:135]
	v_mfma_f32_16x16x32_bf16 v[124:127], v[140:143], v[164:167], v[124:127]
	v_mfma_f32_16x16x32_bf16 v[108:111], v[128:131], v[172:175], v[108:111]
	v_mfma_f32_16x16x32_bf16 v[104:107], v[140:143], v[172:175], v[104:107]
	v_mfma_f32_16x16x32_bf16 v[92:95], v[128:131], v[180:183], v[92:95]
	v_mfma_f32_16x16x32_bf16 v[88:91], v[140:143], v[180:183], v[88:91]
	v_mfma_f32_16x16x32_bf16 v[76:79], v[128:131], v[188:191], v[76:79]
	v_mfma_f32_16x16x32_bf16 v[72:75], v[140:143], v[188:191], v[72:75]
	v_mfma_f32_16x16x32_bf16 v[116:119], v[144:147], v[160:163], v[116:119]
	v_mfma_f32_16x16x32_bf16 v[112:115], v[152:155], v[160:163], v[112:115]
	v_mfma_f32_16x16x32_bf16 v[100:103], v[144:147], v[168:171], v[100:103]
	v_mfma_f32_16x16x32_bf16 v[96:99], v[152:155], v[168:171], v[96:99]
	v_mfma_f32_16x16x32_bf16 v[84:87], v[144:147], v[176:179], v[84:87]
	v_mfma_f32_16x16x32_bf16 v[80:83], v[152:155], v[176:179], v[80:83]
	v_mfma_f32_16x16x32_bf16 v[68:71], v[144:147], v[184:187], v[68:71]
	v_mfma_f32_16x16x32_bf16 v[64:67], v[152:155], v[184:187], v[64:67]
	v_mfma_f32_16x16x32_bf16 v[116:119], v[148:151], v[164:167], v[116:119]
	v_mfma_f32_16x16x32_bf16 v[112:115], v[156:159], v[164:167], v[112:115]
	v_mfma_f32_16x16x32_bf16 v[100:103], v[148:151], v[172:175], v[100:103]
	v_mfma_f32_16x16x32_bf16 v[96:99], v[156:159], v[172:175], v[96:99]
	v_mfma_f32_16x16x32_bf16 v[84:87], v[148:151], v[180:183], v[84:87]
	v_mfma_f32_16x16x32_bf16 v[80:83], v[156:159], v[180:183], v[80:83]
	v_mfma_f32_16x16x32_bf16 v[68:71], v[148:151], v[188:191], v[68:71]
	s_setprio 0
	v_mfma_f32_16x16x32_bf16 v[64:67], v[156:159], v[188:191], v[64:67]
	s_barrier
	s_add_i32 s28, s54, s34
	v_lshl_add_u64 v[204:205], v[204:205], 0, s[18:19]
	s_mov_b32 m0, s28
	ds_read_b128 v[160:163], v247 offset:49152
	ds_read_b128 v[164:167], v247 offset:50176
	ds_read_b128 v[168:171], v247 offset:51200
	ds_read_b128 v[172:175], v247 offset:52224
	ds_read_b128 v[176:179], v247 offset:53248
	ds_read_b128 v[180:183], v247 offset:54272
	ds_read_b128 v[184:187], v247 offset:55296
	ds_read_b128 v[188:191], v247 offset:56320
	global_load_lds_dwordx4 v[204:205], off
	s_add_i32 m0, s28, 0x2000
	s_add_u32 s26, s26, 0xb0080
	v_lshl_add_u64 v[204:205], v[206:207], 0, s[18:19]
	s_addc_u32 s27, s27, 0
	s_add_i32 s28, s55, s34
	global_load_lds_dwordx4 v[204:205], off
	s_mov_b32 m0, s28
	s_nop 0
	global_load_lds_dwordx4 v194, s[26:27]
	s_add_i32 m0, s28, 0x2000
	s_nop 0
	global_load_lds_dwordx4 v198, s[26:27]
	v_lshl_add_u64 v[204:205], v[208:209], 0, s[18:19]
	s_mov_b32 m0, s40
	s_nop 0
	global_load_lds_dwordx4 v[204:205], off
	v_lshl_add_u64 v[204:205], v[210:211], 0, s[18:19]
	s_mov_b32 m0, s41
	s_nop 0
	global_load_lds_dwordx4 v[204:205], off
	s_waitcnt vmcnt(8)
	s_waitcnt lgkmcnt(0)
	s_setprio 1
	s_barrier
	v_mfma_f32_16x16x32_bf16 v[60:63], v[120:123], v[160:163], v[60:63]
	v_mfma_f32_16x16x32_bf16 v[56:59], v[136:139], v[160:163], v[56:59]
	v_mfma_f32_16x16x32_bf16 v[44:47], v[120:123], v[168:171], v[44:47]
	v_mfma_f32_16x16x32_bf16 v[40:43], v[136:139], v[168:171], v[40:43]
	v_mfma_f32_16x16x32_bf16 v[28:31], v[120:123], v[176:179], v[28:31]
	v_mfma_f32_16x16x32_bf16 v[24:27], v[136:139], v[176:179], v[24:27]
	v_mfma_f32_16x16x32_bf16 v[12:15], v[120:123], v[184:187], v[12:15]
	v_mfma_f32_16x16x32_bf16 v[8:11], v[136:139], v[184:187], v[8:11]
	v_mfma_f32_16x16x32_bf16 v[60:63], v[128:131], v[164:167], v[60:63]
	v_mfma_f32_16x16x32_bf16 v[56:59], v[140:143], v[164:167], v[56:59]
	v_mfma_f32_16x16x32_bf16 v[44:47], v[128:131], v[172:175], v[44:47]
	v_mfma_f32_16x16x32_bf16 v[40:43], v[140:143], v[172:175], v[40:43]
	v_mfma_f32_16x16x32_bf16 v[28:31], v[128:131], v[180:183], v[28:31]
	v_mfma_f32_16x16x32_bf16 v[24:27], v[140:143], v[180:183], v[24:27]
	v_mfma_f32_16x16x32_bf16 v[12:15], v[128:131], v[188:191], v[12:15]
	v_mfma_f32_16x16x32_bf16 v[8:11], v[140:143], v[188:191], v[8:11]
	v_mfma_f32_16x16x32_bf16 v[52:55], v[144:147], v[160:163], v[52:55]
	v_mfma_f32_16x16x32_bf16 v[48:51], v[152:155], v[160:163], v[48:51]
	v_mfma_f32_16x16x32_bf16 v[36:39], v[144:147], v[168:171], v[36:39]
	v_mfma_f32_16x16x32_bf16 v[32:35], v[152:155], v[168:171], v[32:35]
	v_mfma_f32_16x16x32_bf16 v[20:23], v[144:147], v[176:179], v[20:23]
	v_mfma_f32_16x16x32_bf16 v[16:19], v[152:155], v[176:179], v[16:19]
	v_mfma_f32_16x16x32_bf16 v[4:7], v[144:147], v[184:187], v[4:7]
	v_mfma_f32_16x16x32_bf16 v[0:3], v[152:155], v[184:187], v[0:3]
	v_mfma_f32_16x16x32_bf16 v[52:55], v[148:151], v[164:167], v[52:55]
	v_mfma_f32_16x16x32_bf16 v[48:51], v[156:159], v[164:167], v[48:51]
	v_mfma_f32_16x16x32_bf16 v[36:39], v[148:151], v[172:175], v[36:39]
	v_mfma_f32_16x16x32_bf16 v[32:35], v[156:159], v[172:175], v[32:35]
	v_mfma_f32_16x16x32_bf16 v[20:23], v[148:151], v[180:183], v[20:23]
	v_mfma_f32_16x16x32_bf16 v[16:19], v[156:159], v[180:183], v[16:19]
	v_mfma_f32_16x16x32_bf16 v[4:7], v[148:151], v[188:191], v[4:7]
	s_setprio 0
	v_mfma_f32_16x16x32_bf16 v[0:3], v[156:159], v[188:191], v[0:3]
	s_barrier
	s_add_i32 s53, s53, 2
	s_add_u32 s24, s24, 0x100
	s_addc_u32 s25, s25, 0
	s_add_u32 s51, s51, 0x100
	s_addc_u32 s52, s52, 0
	s_cmp_gt_u32 s53, 41
; #define PG8_STAGE(bufoff, gbase, voff) do { _Pragma("unroll") for (int _i = 0; _i < 2; ++_i) \
;         __builtin_amdgcn_global_load_lds((const unsigned*)((const char*)(gbase) + (voff)[_i]), (PG8_LAS unsigned*)(lds + (bufoff) + ldsw + _i * 8192), 16, 0, 0); } while (0)
; #define PG8_LDA(dst, b, h) do { _Pragma("unroll") for (int m = 0; m < 4; ++m) _Pragma("unroll") for (int k = 0; k < 2; ++k) dst[m][k] = *(const PG8_LAS bf16x8*)(lds + PG8_SA(b, h) + aoff + m * 2048 + k * 1024); } while (0)
; #define PG8_LDB(dst, b, h) do { _Pragma("unroll") for (int n = 0; n < 2; ++n) _Pragma("unroll") for (int k = 0; k < 2; ++k) dst[n][k] = *(const PG8_LAS bf16x8*)(lds + PG8_SB(b, h) + boff + n * 2048 + k * 1024); } while (0)
; #define PG8_MMA(ai, bj, At, Bt) do { __builtin_amdgcn_s_setprio(1); _Pragma("unroll") for (int m = 0; m < 4; ++m) _Pragma("unroll") for (int n = 0; n < 2; ++n) _Pragma("unroll") for (int k = 0; k < 2; ++k) \
;         acc[ai][bj][m][n] = __builtin_amdgcn_mfma_f32_16x16x32_bf16(Bt[n][k], At[m][k], acc[ai][bj][m][n], 0, 0, 0); __builtin_amdgcn_s_setprio(0); } while (0)
; #define PG8_WAIT_V(n) asm volatile("s_waitcnt vmcnt(" #n ")" ::: "memory")
; #define PG8_WAIT_L(n) asm volatile("s_waitcnt lgkmcnt(" #n ")" ::: "memory")
; template <class Epi, class Sched, bool ALIGN_EPI = false, bool SP2 = false>
; __device__ __forceinline__ void gemm_phase(PG8_LAS unsigned char* lds, const Gemm g, const Sched& S, const Epi& E) {
;     ...
;             const bool last = (t == nt - 2);
;             const char* a1 = cA + (size_t)(t + 1) * kstep;
;             const char* a2 = last ? nA : cA + (size_t)(t + 2) * kstep; const char* b2 = last ? nB : cB + (size_t)(t + 2) * kstep;
;             const char* a3 = a2 + kstep; const char* b3 = b2 + kstep;
;             if (last && has_next) S.a_ready(nxt, ui + 1);
;             if constexpr (SP2) {
;             PG8_LDB(B0, 0, 0); PG8_LDB(B1, 0, 1); PG8_SCHED; PG8_LDA(At, 0, 0); PG8_STAGE(PG8_SA(1, 1), a1 + hstep, voffA);
;             PG8_WAIT_V(8); PG8_WAIT_L(0); PG8_BAR; PG8_MMA(0, 0, At, B0); PG8_MMA(0, 1, At, B1); PG8_BAR; PG8_SCHED;
;             PG8_LDA(At, 0, 1); PG8_STAGE(PG8_SB(0, 0), b2, voffB); PG8_STAGE(PG8_SB(0, 1), b2 + hstep, voffB); PG8_STAGE(PG8_SA(0, 0), a2, voffA);
;             PG8_WAIT_V(8); PG8_WAIT_L(0); PG8_BAR; PG8_MMA(1, 0, At, B0); PG8_MMA(1, 1, At, B1); PG8_BAR; PG8_SCHED;
.LBB0_418:
	ds_read_b128 v[120:123], v245
	ds_read_b128 v[128:131], v245 offset:1024
	ds_read_b128 v[136:139], v245 offset:2048
	ds_read_b128 v[140:143], v245 offset:3072
	ds_read_b128 v[144:147], v246
	ds_read_b128 v[148:151], v246 offset:1024
	ds_read_b128 v[152:155], v246 offset:2048
	ds_read_b128 v[156:159], v246 offset:3072
	s_add_u32 s26, s24, 0xfff50080
	s_addc_u32 s27, s25, -1
	s_cmp_eq_u32 s53, 40
	s_cselect_b32 s29, s7, s27
	s_cselect_b32 s28, s6, s26
	s_cselect_b32 s27, s23, s52
	s_cselect_b32 s26, s22, s51
	s_add_i32 m0, s35, 0xc000
	ds_read_b128 v[160:163], v247
	ds_read_b128 v[164:167], v247 offset:1024
	ds_read_b128 v[168:171], v247 offset:2048
	ds_read_b128 v[172:175], v247 offset:3072
	ds_read_b128 v[176:179], v247 offset:4096
	ds_read_b128 v[180:183], v247 offset:5120
	ds_read_b128 v[184:187], v247 offset:6144
	ds_read_b128 v[188:191], v247 offset:7168
	global_load_lds_dwordx4 v200, s[24:25]
	s_add_i32 m0, s35, 0xe000
	s_nop 0
	global_load_lds_dwordx4 v202, s[24:25]
	s_waitcnt vmcnt(8)
	s_waitcnt lgkmcnt(0)
	s_setprio 1
	s_barrier
	v_mfma_f32_16x16x32_bf16 v[132:135], v[120:123], v[160:163], v[132:135]
	v_mfma_f32_16x16x32_bf16 v[124:127], v[136:139], v[160:163], v[124:127]
	v_mfma_f32_16x16x32_bf16 v[108:111], v[120:123], v[168:171], v[108:111]
	v_mfma_f32_16x16x32_bf16 v[104:107], v[136:139], v[168:171], v[104:107]
	v_mfma_f32_16x16x32_bf16 v[92:95], v[120:123], v[176:179], v[92:95]
	v_mfma_f32_16x16x32_bf16 v[88:91], v[136:139], v[176:179], v[88:91]
	v_mfma_f32_16x16x32_bf16 v[76:79], v[120:123], v[184:187], v[76:79]
	v_mfma_f32_16x16x32_bf16 v[72:75], v[136:139], v[184:187], v[72:75]
	v_mfma_f32_16x16x32_bf16 v[132:135], v[128:131], v[164:167], v[132:135]
	v_mfma_f32_16x16x32_bf16 v[124:127], v[140:143], v[164:167], v[124:127]
	v_mfma_f32_16x16x32_bf16 v[108:111], v[128:131], v[172:175], v[108:111]
	v_mfma_f32_16x16x32_bf16 v[104:107], v[140:143], v[172:175], v[104:107]
	v_mfma_f32_16x16x32_bf16 v[92:95], v[128:131], v[180:183], v[92:95]
	v_mfma_f32_16x16x32_bf16 v[88:91], v[140:143], v[180:183], v[88:91]
	v_mfma_f32_16x16x32_bf16 v[76:79], v[128:131], v[188:191], v[76:79]
	v_mfma_f32_16x16x32_bf16 v[72:75], v[140:143], v[188:191], v[72:75]
	v_mfma_f32_16x16x32_bf16 v[116:119], v[144:147], v[160:163], v[116:119]
	v_mfma_f32_16x16x32_bf16 v[112:115], v[152:155], v[160:163], v[112:115]
	v_mfma_f32_16x16x32_bf16 v[100:103], v[144:147], v[168:171], v[100:103]
	v_mfma_f32_16x16x32_bf16 v[96:99], v[152:155], v[168:171], v[96:99]
	v_mfma_f32_16x16x32_bf16 v[84:87], v[144:147], v[176:179], v[84:87]
	v_mfma_f32_16x16x32_bf16 v[80:83], v[152:155], v[176:179], v[80:83]
	v_mfma_f32_16x16x32_bf16 v[68:71], v[144:147], v[184:187], v[68:71]
	v_mfma_f32_16x16x32_bf16 v[64:67], v[152:155], v[184:187], v[64:67]
	v_mfma_f32_16x16x32_bf16 v[116:119], v[148:151], v[164:167], v[116:119]
	v_mfma_f32_16x16x32_bf16 v[112:115], v[156:159], v[164:167], v[112:115]
	v_mfma_f32_16x16x32_bf16 v[100:103], v[148:151], v[172:175], v[100:103]
	v_mfma_f32_16x16x32_bf16 v[96:99], v[156:159], v[172:175], v[96:99]
	v_mfma_f32_16x16x32_bf16 v[84:87], v[148:151], v[180:183], v[84:87]
	v_mfma_f32_16x16x32_bf16 v[80:83], v[156:159], v[180:183], v[80:83]
	v_mfma_f32_16x16x32_bf16 v[68:71], v[148:151], v[188:191], v[68:71]
	s_setprio 0
	v_mfma_f32_16x16x32_bf16 v[64:67], v[156:159], v[188:191], v[64:67]
	s_barrier
	s_add_i32 s54, s45, s34
	v_lshl_add_u64 v[204:205], s[26:27], 0, v[194:195]
	s_mov_b32 m0, s54
	ds_read_b128 v[160:163], v247 offset:16384
	ds_read_b128 v[164:167], v247 offset:17408
	ds_read_b128 v[168:171], v247 offset:18432
	ds_read_b128 v[172:175], v247 offset:19456
	ds_read_b128 v[176:179], v247 offset:20480
	ds_read_b128 v[180:183], v247 offset:21504
	ds_read_b128 v[184:187], v247 offset:22528
	ds_read_b128 v[188:191], v247 offset:23552
	global_load_lds_dwordx4 v[204:205], off
	s_add_i32 m0, s54, 0x2000
	s_add_u32 s54, s26, 0xb0000
	v_lshl_add_u64 v[206:207], s[26:27], 0, v[198:199]
	s_addc_u32 s55, s27, 0
	s_add_i32 s56, s46, s34
	global_load_lds_dwordx4 v[206:207], off
	s_mov_b32 m0, s56
	v_lshl_add_u64 v[210:211], s[28:29], 0, v[196:197]
	global_load_lds_dwordx4 v194, s[54:55]
	s_add_i32 m0, s56, 0x2000
	s_nop 0
	global_load_lds_dwordx4 v198, s[54:55]
	v_lshl_add_u64 v[208:209], s[28:29], 0, v[192:193]
	s_mov_b32 m0, s35
	s_nop 0
	global_load_lds_dwordx4 v[208:209], off
	s_mov_b32 m0, s36
	s_nop 0
	global_load_lds_dwordx4 v[210:211], off
	s_waitcnt vmcnt(8)
	s_waitcnt lgkmcnt(0)
	s_setprio 1
	s_barrier
	v_mfma_f32_16x16x32_bf16 v[60:63], v[120:123], v[160:163], v[60:63]
	v_mfma_f32_16x16x32_bf16 v[56:59], v[136:139], v[160:163], v[56:59]
	v_mfma_f32_16x16x32_bf16 v[44:47], v[120:123], v[168:171], v[44:47]
	v_mfma_f32_16x16x32_bf16 v[40:43], v[136:139], v[168:171], v[40:43]
	v_mfma_f32_16x16x32_bf16 v[28:31], v[120:123], v[176:179], v[28:31]
	v_mfma_f32_16x16x32_bf16 v[24:27], v[136:139], v[176:179], v[24:27]
	v_mfma_f32_16x16x32_bf16 v[12:15], v[120:123], v[184:187], v[12:15]
	v_mfma_f32_16x16x32_bf16 v[8:11], v[136:139], v[184:187], v[8:11]
	v_mfma_f32_16x16x32_bf16 v[60:63], v[128:131], v[164:167], v[60:63]
	v_mfma_f32_16x16x32_bf16 v[56:59], v[140:143], v[164:167], v[56:59]
	v_mfma_f32_16x16x32_bf16 v[44:47], v[128:131], v[172:175], v[44:47]
	v_mfma_f32_16x16x32_bf16 v[40:43], v[140:143], v[172:175], v[40:43]
	v_mfma_f32_16x16x32_bf16 v[28:31], v[128:131], v[180:183], v[28:31]
	v_mfma_f32_16x16x32_bf16 v[24:27], v[140:143], v[180:183], v[24:27]
	v_mfma_f32_16x16x32_bf16 v[12:15], v[128:131], v[188:191], v[12:15]
	v_mfma_f32_16x16x32_bf16 v[8:11], v[140:143], v[188:191], v[8:11]
	v_mfma_f32_16x16x32_bf16 v[52:55], v[144:147], v[160:163], v[52:55]
	v_mfma_f32_16x16x32_bf16 v[48:51], v[152:155], v[160:163], v[48:51]
	v_mfma_f32_16x16x32_bf16 v[36:39], v[144:147], v[168:171], v[36:39]
	v_mfma_f32_16x16x32_bf16 v[32:35], v[152:155], v[168:171], v[32:35]
	v_mfma_f32_16x16x32_bf16 v[20:23], v[144:147], v[176:179], v[20:23]
	v_mfma_f32_16x16x32_bf16 v[16:19], v[152:155], v[176:179], v[16:19]
	v_mfma_f32_16x16x32_bf16 v[4:7], v[144:147], v[184:187], v[4:7]
	v_mfma_f32_16x16x32_bf16 v[0:3], v[152:155], v[184:187], v[0:3]
	v_mfma_f32_16x16x32_bf16 v[52:55], v[148:151], v[164:167], v[52:55]
	v_mfma_f32_16x16x32_bf16 v[48:51], v[156:159], v[164:167], v[48:51]
	v_mfma_f32_16x16x32_bf16 v[36:39], v[148:151], v[172:175], v[36:39]
	v_mfma_f32_16x16x32_bf16 v[32:35], v[156:159], v[172:175], v[32:35]
	v_mfma_f32_16x16x32_bf16 v[20:23], v[148:151], v[180:183], v[20:23]
	v_mfma_f32_16x16x32_bf16 v[16:19], v[156:159], v[180:183], v[16:19]
	v_mfma_f32_16x16x32_bf16 v[4:7], v[148:151], v[188:191], v[4:7]
	s_setprio 0
	v_mfma_f32_16x16x32_bf16 v[0:3], v[156:159], v[188:191], v[0:3]
	s_barrier
; #define PG8_STAGE(bufoff, gbase, voff) do { _Pragma("unroll") for (int _i = 0; _i < 2; ++_i) \
;         __builtin_amdgcn_global_load_lds((const unsigned*)((const char*)(gbase) + (voff)[_i]), (PG8_LAS unsigned*)(lds + (bufoff) + ldsw + _i * 8192), 16, 0, 0); } while (0)
; #define PG8_LDA(dst, b, h) do { _Pragma("unroll") for (int m = 0; m < 4; ++m) _Pragma("unroll") for (int k = 0; k < 2; ++k) dst[m][k] = *(const PG8_LAS bf16x8*)(lds + PG8_SA(b, h) + aoff + m * 2048 + k * 1024); } while (0)
; #define PG8_LDB(dst, b, h) do { _Pragma("unroll") for (int n = 0; n < 2; ++n) _Pragma("unroll") for (int k = 0; k < 2; ++k) dst[n][k] = *(const PG8_LAS bf16x8*)(lds + PG8_SB(b, h) + boff + n * 2048 + k * 1024); } while (0)
; #define PG8_MMA(ai, bj, At, Bt) do { __builtin_amdgcn_s_setprio(1); _Pragma("unroll") for (int m = 0; m < 4; ++m) _Pragma("unroll") for (int n = 0; n < 2; ++n) _Pragma("unroll") for (int k = 0; k < 2; ++k) \
;         acc[ai][bj][m][n] = __builtin_amdgcn_mfma_f32_16x16x32_bf16(Bt[n][k], At[m][k], acc[ai][bj][m][n], 0, 0, 0); __builtin_amdgcn_s_setprio(0); } while (0)
; #define PG8_WAIT_V(n) asm volatile("s_waitcnt vmcnt(" #n ")" ::: "memory")
; #define PG8_WAIT_L(n) asm volatile("s_waitcnt lgkmcnt(" #n ")" ::: "memory")
; #define PG8_BAR __builtin_amdgcn_s_barrier()
; #define PG8_SCHED __builtin_amdgcn_sched_barrier(0)
; template <class Epi, class Sched, bool ALIGN_EPI = false, bool SP2 = false>
; __device__ __forceinline__ void gemm_phase(PG8_LAS unsigned char* lds, const Gemm g, const Sched& S, const Epi& E) {
;     ...
;             PG8_LDB(B0, 1, 0); PG8_LDB(B1, 1, 1); PG8_SCHED; PG8_LDA(At, 1, 0); PG8_STAGE(PG8_SA(0, 1), a2 + hstep, voffA);
;             PG8_WAIT_V(8); PG8_WAIT_L(0); PG8_BAR; PG8_MMA(0, 0, At, B0); PG8_MMA(0, 1, At, B1); PG8_BAR; PG8_SCHED;
;             PG8_LDA(At, 1, 1); PG8_STAGE(PG8_SB(1, 0), b3, voffB); PG8_STAGE(PG8_SB(1, 1), b3 + hstep, voffB); PG8_STAGE(PG8_SA(1, 0), a3, voffA);
;             PG8_WAIT_V(8); PG8_WAIT_L(0); PG8_BAR; PG8_MMA(1, 0, At, B0); PG8_MMA(1, 1, At, B1); PG8_BAR; PG8_SCHED;
;     ...
;         if constexpr (ALIGN_EPI) { if (wr == 0) PG8_BAR; }
	s_add_i32 s54, 0, 0x18000
	s_add_i32 s55, 0, 0x1c000
	v_add_u32_e32 v140, s54, v243
	v_add_u32_e32 v156, s55, v243
	ds_read_b128 v[120:123], v140
	ds_read_b128 v[128:131], v140 offset:1024
	ds_read_b128 v[136:139], v140 offset:2048
	ds_read_b128 v[140:143], v140 offset:3072
	ds_read_b128 v[144:147], v156
	ds_read_b128 v[148:151], v156 offset:1024
	ds_read_b128 v[152:155], v156 offset:2048
	ds_read_b128 v[156:159], v156 offset:3072
	s_add_u32 s28, s28, 0xb0000
	s_addc_u32 s29, s29, 0
	s_mov_b32 m0, s37
	ds_read_b128 v[160:163], v247 offset:32768
	ds_read_b128 v[164:167], v247 offset:33792
	ds_read_b128 v[168:171], v247 offset:34816
	ds_read_b128 v[172:175], v247 offset:35840
	ds_read_b128 v[176:179], v247 offset:36864
	ds_read_b128 v[180:183], v247 offset:37888
	ds_read_b128 v[184:187], v247 offset:38912
	ds_read_b128 v[188:191], v247 offset:39936
	global_load_lds_dwordx4 v192, s[28:29]
	v_lshl_add_u64 v[212:213], s[28:29], 0, v[196:197]
	s_mov_b32 m0, s38
	s_nop 0
	global_load_lds_dwordx4 v[212:213], off
	s_waitcnt vmcnt(8)
	s_waitcnt lgkmcnt(0)
	s_setprio 1
	s_barrier
	v_mfma_f32_16x16x32_bf16 v[132:135], v[120:123], v[160:163], v[132:135]
	v_mfma_f32_16x16x32_bf16 v[124:127], v[136:139], v[160:163], v[124:127]
	v_mfma_f32_16x16x32_bf16 v[108:111], v[120:123], v[168:171], v[108:111]
	v_mfma_f32_16x16x32_bf16 v[104:107], v[136:139], v[168:171], v[104:107]
	v_mfma_f32_16x16x32_bf16 v[92:95], v[120:123], v[176:179], v[92:95]
	v_mfma_f32_16x16x32_bf16 v[88:91], v[136:139], v[176:179], v[88:91]
	v_mfma_f32_16x16x32_bf16 v[76:79], v[120:123], v[184:187], v[76:79]
	v_mfma_f32_16x16x32_bf16 v[72:75], v[136:139], v[184:187], v[72:75]
	v_mfma_f32_16x16x32_bf16 v[132:135], v[128:131], v[164:167], v[132:135]
	v_mfma_f32_16x16x32_bf16 v[124:127], v[140:143], v[164:167], v[124:127]
	v_mfma_f32_16x16x32_bf16 v[108:111], v[128:131], v[172:175], v[108:111]
	v_mfma_f32_16x16x32_bf16 v[104:107], v[140:143], v[172:175], v[104:107]
	v_mfma_f32_16x16x32_bf16 v[92:95], v[128:131], v[180:183], v[92:95]
	v_mfma_f32_16x16x32_bf16 v[88:91], v[140:143], v[180:183], v[88:91]
	v_mfma_f32_16x16x32_bf16 v[76:79], v[128:131], v[188:191], v[76:79]
	v_mfma_f32_16x16x32_bf16 v[72:75], v[140:143], v[188:191], v[72:75]
	v_mfma_f32_16x16x32_bf16 v[116:119], v[144:147], v[160:163], v[116:119]
	v_mfma_f32_16x16x32_bf16 v[112:115], v[152:155], v[160:163], v[112:115]
	v_mfma_f32_16x16x32_bf16 v[100:103], v[144:147], v[168:171], v[100:103]
	v_mfma_f32_16x16x32_bf16 v[96:99], v[152:155], v[168:171], v[96:99]
	v_mfma_f32_16x16x32_bf16 v[84:87], v[144:147], v[176:179], v[84:87]
	v_mfma_f32_16x16x32_bf16 v[80:83], v[152:155], v[176:179], v[80:83]
	v_mfma_f32_16x16x32_bf16 v[68:71], v[144:147], v[184:187], v[68:71]
	v_mfma_f32_16x16x32_bf16 v[64:67], v[152:155], v[184:187], v[64:67]
	v_mfma_f32_16x16x32_bf16 v[116:119], v[148:151], v[164:167], v[116:119]
	v_mfma_f32_16x16x32_bf16 v[112:115], v[156:159], v[164:167], v[112:115]
	v_mfma_f32_16x16x32_bf16 v[100:103], v[148:151], v[172:175], v[100:103]
	v_mfma_f32_16x16x32_bf16 v[96:99], v[156:159], v[172:175], v[96:99]
	v_mfma_f32_16x16x32_bf16 v[84:87], v[148:151], v[180:183], v[84:87]
	v_mfma_f32_16x16x32_bf16 v[80:83], v[156:159], v[180:183], v[80:83]
	v_mfma_f32_16x16x32_bf16 v[68:71], v[148:151], v[188:191], v[68:71]
	s_setprio 0
	v_mfma_f32_16x16x32_bf16 v[64:67], v[156:159], v[188:191], v[64:67]
	s_barrier
	s_add_i32 s28, s54, s34
	v_lshl_add_u64 v[204:205], v[204:205], 0, s[18:19]
	s_mov_b32 m0, s28
	ds_read_b128 v[160:163], v247 offset:49152
	ds_read_b128 v[164:167], v247 offset:50176
	ds_read_b128 v[168:171], v247 offset:51200
	ds_read_b128 v[172:175], v247 offset:52224
	ds_read_b128 v[176:179], v247 offset:53248
	ds_read_b128 v[180:183], v247 offset:54272
	ds_read_b128 v[184:187], v247 offset:55296
	ds_read_b128 v[188:191], v247 offset:56320
	global_load_lds_dwordx4 v[204:205], off
	s_add_i32 m0, s28, 0x2000
	s_add_u32 s26, s26, 0xb0080
	v_lshl_add_u64 v[204:205], v[206:207], 0, s[18:19]
	s_addc_u32 s27, s27, 0
	s_add_i32 s28, s55, s34
	global_load_lds_dwordx4 v[204:205], off
	s_mov_b32 m0, s28
	s_nop 0
	global_load_lds_dwordx4 v194, s[26:27]
	s_add_i32 m0, s28, 0x2000
	s_nop 0
	global_load_lds_dwordx4 v198, s[26:27]
	v_lshl_add_u64 v[204:205], v[208:209], 0, s[18:19]
	s_mov_b32 m0, s40
	s_nop 0
	global_load_lds_dwordx4 v[204:205], off
	v_lshl_add_u64 v[204:205], v[210:211], 0, s[18:19]
	s_mov_b32 m0, s41
	s_nop 0
	global_load_lds_dwordx4 v[204:205], off
	s_waitcnt vmcnt(8)
	s_waitcnt lgkmcnt(0)
	s_setprio 1
	s_barrier
	v_mfma_f32_16x16x32_bf16 v[60:63], v[120:123], v[160:163], v[60:63]
	v_mfma_f32_16x16x32_bf16 v[56:59], v[136:139], v[160:163], v[56:59]
	v_mfma_f32_16x16x32_bf16 v[44:47], v[120:123], v[168:171], v[44:47]
	v_mfma_f32_16x16x32_bf16 v[40:43], v[136:139], v[168:171], v[40:43]
	v_mfma_f32_16x16x32_bf16 v[28:31], v[120:123], v[176:179], v[28:31]
	v_mfma_f32_16x16x32_bf16 v[24:27], v[136:139], v[176:179], v[24:27]
	v_mfma_f32_16x16x32_bf16 v[12:15], v[120:123], v[184:187], v[12:15]
	v_mfma_f32_16x16x32_bf16 v[8:11], v[136:139], v[184:187], v[8:11]
	v_mfma_f32_16x16x32_bf16 v[60:63], v[128:131], v[164:167], v[60:63]
	v_mfma_f32_16x16x32_bf16 v[56:59], v[140:143], v[164:167], v[56:59]
	v_mfma_f32_16x16x32_bf16 v[44:47], v[128:131], v[172:175], v[44:47]
	v_mfma_f32_16x16x32_bf16 v[40:43], v[140:143], v[172:175], v[40:43]
	v_mfma_f32_16x16x32_bf16 v[28:31], v[128:131], v[180:183], v[28:31]
	v_mfma_f32_16x16x32_bf16 v[24:27], v[140:143], v[180:183], v[24:27]
	v_mfma_f32_16x16x32_bf16 v[12:15], v[128:131], v[188:191], v[12:15]
	v_mfma_f32_16x16x32_bf16 v[8:11], v[140:143], v[188:191], v[8:11]
	v_mfma_f32_16x16x32_bf16 v[52:55], v[144:147], v[160:163], v[52:55]
	v_mfma_f32_16x16x32_bf16 v[48:51], v[152:155], v[160:163], v[48:51]
	v_mfma_f32_16x16x32_bf16 v[36:39], v[144:147], v[168:171], v[36:39]
	v_mfma_f32_16x16x32_bf16 v[32:35], v[152:155], v[168:171], v[32:35]
	v_mfma_f32_16x16x32_bf16 v[20:23], v[144:147], v[176:179], v[20:23]
	v_mfma_f32_16x16x32_bf16 v[16:19], v[152:155], v[176:179], v[16:19]
	v_mfma_f32_16x16x32_bf16 v[4:7], v[144:147], v[184:187], v[4:7]
	v_mfma_f32_16x16x32_bf16 v[0:3], v[152:155], v[184:187], v[0:3]
	v_mfma_f32_16x16x32_bf16 v[52:55], v[148:151], v[164:167], v[52:55]
	v_mfma_f32_16x16x32_bf16 v[48:51], v[156:159], v[164:167], v[48:51]
	v_mfma_f32_16x16x32_bf16 v[36:39], v[148:151], v[172:175], v[36:39]
	v_mfma_f32_16x16x32_bf16 v[32:35], v[156:159], v[172:175], v[32:35]
	v_mfma_f32_16x16x32_bf16 v[20:23], v[148:151], v[180:183], v[20:23]
	v_mfma_f32_16x16x32_bf16 v[16:19], v[156:159], v[180:183], v[16:19]
	v_mfma_f32_16x16x32_bf16 v[4:7], v[148:151], v[188:191], v[4:7]
	s_setprio 0
	v_mfma_f32_16x16x32_bf16 v[0:3], v[156:159], v[188:191], v[0:3]
	s_barrier
	s_add_i32 s53, s53, 2
	s_add_u32 s24, s24, 0x100
	s_addc_u32 s25, s25, 0
	s_add_u32 s51, s51, 0x100
	s_addc_u32 s52, s52, 0
	s_cmp_gt_u32 s53, 41
	s_cbranch_scc0 .LBB0_418
	s_and_b64 vcc, exec, s[20:21]
	s_cbranch_vccz .LBB0_421
	s_barrier

; #define PG8_STAGE(bufoff, gbase, voff) do { _Pragma("unroll") for (int _i = 0; _i < 2; ++_i) \
;         __builtin_amdgcn_global_load_lds((const unsigned*)((const char*)(gbase) + (voff)[_i]), (PG8_LAS unsigned*)(lds + (bufoff) + ldsw + _i * 8192), 16, 0, 0); } while (0)
; #define PG8_LDA(dst, b, h) do { _Pragma("unroll") for (int m = 0; m < 4; ++m) _Pragma("unroll") for (int k = 0; k < 2; ++k) dst[m][k] = *(const PG8_LAS bf16x8*)(lds + PG8_SA(b, h) + aoff + m * 2048 + k * 1024); } while (0)
; #define PG8_LDB(dst, b, h) do { _Pragma("unroll") for (int n = 0; n < 2; ++n) _Pragma("unroll") for (int k = 0; k < 2; ++k) dst[n][k] = *(const PG8_LAS bf16x8*)(lds + PG8_SB(b, h) + boff + n * 2048 + k * 1024); } while (0)
; #define PG8_WAIT_V(n) asm volatile("s_waitcnt vmcnt(" #n ")" ::: "memory")
; #define PG8_WAIT_L(n) asm volatile("s_waitcnt lgkmcnt(" #n ")" ::: "memory")
; #define PG8_BAR __builtin_amdgcn_s_barrier()
; #define PG8_SCHED __builtin_amdgcn_sched_barrier(0)
; template <class Epi, class Sched, bool ALIGN_EPI = false, bool SP2 = false>
; __device__ __forceinline__ void gemm_phase(PG8_LAS unsigned char* lds, const Gemm g, const Sched& S, const Epi& E) {
;     ...
;         const bool has_next = S.next(ui + 1, nxt);
;         const char* nA = has_next ? (const char*)g.A + (size_t)nxt.pm * tstep : cA; const char* nB = has_next ? (const char*)g.Bt + (size_t)nxt.pn * tstep : cB;
;         for (int t = 0; t < nt; t += 2) {
;             const bool last = (t == nt - 2);
;             const char* a1 = cA + (size_t)(t + 1) * kstep;
;             const char* a2 = last ? nA : cA + (size_t)(t + 2) * kstep; const char* b2 = last ? nB : cB + (size_t)(t + 2) * kstep;
;             const char* a3 = a2 + kstep; const char* b3 = b2 + kstep;
;             if (last && has_next) S.a_ready(nxt, ui + 1);
;             if constexpr (SP2) {
;             PG8_LDB(B0, 0, 0); PG8_LDB(B1, 0, 1); PG8_SCHED; PG8_LDA(At, 0, 0); PG8_STAGE(PG8_SA(1, 1), a1 + hstep, voffA);
;             PG8_WAIT_V(8); PG8_WAIT_L(0); PG8_BAR; PG8_MMA(0, 0, At, B0); PG8_MMA(0, 1, At, B1); PG8_BAR; PG8_SCHED;
;             PG8_LDA(At, 0, 1); PG8_STAGE(PG8_SB(0, 0), b2, voffB); PG8_STAGE(PG8_SB(0, 1), b2 + hstep, voffB); PG8_STAGE(PG8_SA(0, 0), a2, voffA);
;             PG8_WAIT_V(8); PG8_WAIT_L(0); PG8_BAR; PG8_MMA(1, 0, At, B0); PG8_MMA(1, 1, At, B1); PG8_BAR; PG8_SCHED;
.LBB0_508:
	s_ashr_i32 s31, s30, 31
	s_lshl_b64 s[34:35], s[30:31], 19
	s_add_u32 s34, s48, s34
	s_addc_u32 s35, s49, s35
	s_and_b64 s[36:37], s[4:5], exec
	s_cselect_b32 s9, s35, s39
	s_cselect_b32 s14, s34, s38
	s_ashr_i32 s29, s28, 31
	s_lshl_b64 s[36:37], s[28:29], 19
	s_add_u32 s36, s50, s36
	s_addc_u32 s37, s51, s37
	s_and_b64 s[42:43], s[4:5], exec
	s_cselect_b32 s29, s37, s41
	s_cselect_b32 s31, s36, s40
	s_add_u32 s38, s38, 0x40080
	s_addc_u32 s39, s39, 0
	s_add_u32 s44, s40, 0x100
	s_addc_u32 s45, s41, 0
	s_mov_b32 s70, -2
	s_add_u32 s40, s38, 0xfffc0080
	s_addc_u32 s41, s39, -1
	s_cmp_eq_u32 s70, 12
	s_cselect_b32 s43, s9, s41
	s_cselect_b32 s42, s14, s40
	s_cselect_b32 s41, s29, s45
	s_cselect_b32 s40, s31, s44
	v_lshl_add_u64 v[226:227], s[38:39], 0, v[132:133]
	s_add_i32 m0, s52, 0xc000
	s_nop 0
	global_load_lds_dwordx4 v[226:227], off
	v_lshl_add_u64 v[226:227], s[38:39], 0, v[134:135]
	s_add_i32 m0, s52, 0xe000
	s_nop 0
	global_load_lds_dwordx4 v[226:227], off
	s_waitcnt vmcnt(8)
	s_waitcnt lgkmcnt(0)
	s_setprio 1
	s_barrier
	v_mfma_f32_16x16x32_bf16 v[124:127], v[148:151], v[194:197], 0
	v_mfma_f32_16x16x32_bf16 v[120:123], v[170:173], v[194:197], 0
	v_mfma_f32_16x16x32_bf16 v[108:111], v[148:151], v[202:205], 0
	v_mfma_f32_16x16x32_bf16 v[104:107], v[170:173], v[202:205], 0
	v_mfma_f32_16x16x32_bf16 v[92:95], v[148:151], v[210:213], 0
	v_mfma_f32_16x16x32_bf16 v[88:91], v[170:173], v[210:213], 0
	v_mfma_f32_16x16x32_bf16 v[76:79], v[148:151], v[218:221], 0
	v_mfma_f32_16x16x32_bf16 v[72:75], v[170:173], v[218:221], 0
	v_mfma_f32_16x16x32_bf16 v[124:127], v[166:169], v[198:201], v[124:127]
	v_mfma_f32_16x16x32_bf16 v[120:123], v[174:177], v[198:201], v[120:123]
	v_mfma_f32_16x16x32_bf16 v[108:111], v[166:169], v[206:209], v[108:111]
	v_mfma_f32_16x16x32_bf16 v[104:107], v[174:177], v[206:209], v[104:107]
	v_mfma_f32_16x16x32_bf16 v[92:95], v[166:169], v[214:217], v[92:95]
	v_mfma_f32_16x16x32_bf16 v[88:91], v[174:177], v[214:217], v[88:91]
	v_mfma_f32_16x16x32_bf16 v[76:79], v[166:169], v[222:225], v[76:79]
	v_mfma_f32_16x16x32_bf16 v[72:75], v[174:177], v[222:225], v[72:75]
	v_mfma_f32_16x16x32_bf16 v[116:119], v[178:181], v[194:197], 0
	v_mfma_f32_16x16x32_bf16 v[112:115], v[186:189], v[194:197], 0
	v_mfma_f32_16x16x32_bf16 v[100:103], v[178:181], v[202:205], 0
	v_mfma_f32_16x16x32_bf16 v[96:99], v[186:189], v[202:205], 0
	v_mfma_f32_16x16x32_bf16 v[84:87], v[178:181], v[210:213], 0
	v_mfma_f32_16x16x32_bf16 v[80:83], v[186:189], v[210:213], 0
	v_mfma_f32_16x16x32_bf16 v[68:71], v[178:181], v[218:221], 0
	v_mfma_f32_16x16x32_bf16 v[64:67], v[186:189], v[218:221], 0
	v_mfma_f32_16x16x32_bf16 v[116:119], v[182:185], v[198:201], v[116:119]
	v_mfma_f32_16x16x32_bf16 v[112:115], v[190:193], v[198:201], v[112:115]
	v_mfma_f32_16x16x32_bf16 v[100:103], v[182:185], v[206:209], v[100:103]
	v_mfma_f32_16x16x32_bf16 v[96:99], v[190:193], v[206:209], v[96:99]
	v_mfma_f32_16x16x32_bf16 v[84:87], v[182:185], v[214:217], v[84:87]
	v_mfma_f32_16x16x32_bf16 v[80:83], v[190:193], v[214:217], v[80:83]
	v_mfma_f32_16x16x32_bf16 v[68:71], v[182:185], v[222:225], v[68:71]
	s_setprio 0
	v_mfma_f32_16x16x32_bf16 v[64:67], v[190:193], v[222:225], v[64:67]
	s_barrier
	s_add_i32 s71, s61, s33
	v_lshl_add_u64 v[226:227], s[40:41], 0, v[138:139]
	s_mov_b32 m0, s71
	ds_read_b128 v[194:197], v164 offset:16384
	ds_read_b128 v[198:201], v164 offset:17408
	ds_read_b128 v[202:205], v164 offset:18432
	ds_read_b128 v[206:209], v164 offset:19456
	ds_read_b128 v[210:213], v164 offset:20480
	ds_read_b128 v[214:217], v164 offset:21504
	ds_read_b128 v[218:221], v164 offset:22528
	ds_read_b128 v[222:225], v164 offset:23552
	global_load_lds_dwordx4 v[226:227], off
	s_add_i32 m0, s71, 0x2000
	s_add_u32 s72, s40, 0x40000
	v_lshl_add_u64 v[228:229], s[40:41], 0, v[142:143]
	s_addc_u32 s73, s41, 0
	s_add_i32 s71, s62, s33
	global_load_lds_dwordx4 v[228:229], off
	v_lshl_add_u64 v[230:231], s[72:73], 0, v[138:139]
	s_mov_b32 m0, s71
	v_lshl_add_u64 v[232:233], s[42:43], 0, v[140:141]
	global_load_lds_dwordx4 v[230:231], off
	v_lshl_add_u64 v[230:231], s[72:73], 0, v[142:143]
	s_add_i32 m0, s71, 0x2000
	s_nop 0
	global_load_lds_dwordx4 v[230:231], off
	v_lshl_add_u64 v[230:231], s[42:43], 0, v[136:137]
	s_mov_b32 m0, s52
	s_nop 0
	global_load_lds_dwordx4 v[230:231], off
	s_mov_b32 m0, s53
	s_nop 0
	global_load_lds_dwordx4 v[232:233], off
	s_waitcnt vmcnt(8)
	s_waitcnt lgkmcnt(0)
	s_setprio 1
	s_barrier
	v_mfma_f32_16x16x32_bf16 v[60:63], v[148:151], v[194:197], 0
	v_mfma_f32_16x16x32_bf16 v[56:59], v[170:173], v[194:197], 0
	v_mfma_f32_16x16x32_bf16 v[44:47], v[148:151], v[202:205], 0
	v_mfma_f32_16x16x32_bf16 v[40:43], v[170:173], v[202:205], 0
	v_mfma_f32_16x16x32_bf16 v[28:31], v[148:151], v[210:213], 0
	v_mfma_f32_16x16x32_bf16 v[24:27], v[170:173], v[210:213], 0
	v_mfma_f32_16x16x32_bf16 v[12:15], v[148:151], v[218:221], 0
	v_mfma_f32_16x16x32_bf16 v[8:11], v[170:173], v[218:221], 0
	v_mfma_f32_16x16x32_bf16 v[60:63], v[166:169], v[198:201], v[60:63]
	v_mfma_f32_16x16x32_bf16 v[56:59], v[174:177], v[198:201], v[56:59]
	v_mfma_f32_16x16x32_bf16 v[44:47], v[166:169], v[206:209], v[44:47]
	v_mfma_f32_16x16x32_bf16 v[40:43], v[174:177], v[206:209], v[40:43]
	v_mfma_f32_16x16x32_bf16 v[28:31], v[166:169], v[214:217], v[28:31]
	v_mfma_f32_16x16x32_bf16 v[24:27], v[174:177], v[214:217], v[24:27]
	v_mfma_f32_16x16x32_bf16 v[12:15], v[166:169], v[222:225], v[12:15]
	v_mfma_f32_16x16x32_bf16 v[8:11], v[174:177], v[222:225], v[8:11]
	v_mfma_f32_16x16x32_bf16 v[52:55], v[178:181], v[194:197], 0
	v_mfma_f32_16x16x32_bf16 v[48:51], v[186:189], v[194:197], 0
	v_mfma_f32_16x16x32_bf16 v[36:39], v[178:181], v[202:205], 0
	v_mfma_f32_16x16x32_bf16 v[32:35], v[186:189], v[202:205], 0
	v_mfma_f32_16x16x32_bf16 v[20:23], v[178:181], v[210:213], 0
	v_mfma_f32_16x16x32_bf16 v[16:19], v[186:189], v[210:213], 0
	v_mfma_f32_16x16x32_bf16 v[4:7], v[178:181], v[218:221], 0
	v_mfma_f32_16x16x32_bf16 v[0:3], v[186:189], v[218:221], 0
	v_mfma_f32_16x16x32_bf16 v[52:55], v[182:185], v[198:201], v[52:55]
	v_mfma_f32_16x16x32_bf16 v[48:51], v[190:193], v[198:201], v[48:51]
	v_mfma_f32_16x16x32_bf16 v[36:39], v[182:185], v[206:209], v[36:39]
	v_mfma_f32_16x16x32_bf16 v[32:35], v[190:193], v[206:209], v[32:35]
	v_mfma_f32_16x16x32_bf16 v[20:23], v[182:185], v[214:217], v[20:23]
	v_mfma_f32_16x16x32_bf16 v[16:19], v[190:193], v[214:217], v[16:19]
	v_mfma_f32_16x16x32_bf16 v[4:7], v[182:185], v[222:225], v[4:7]
	s_setprio 0
	v_mfma_f32_16x16x32_bf16 v[0:3], v[190:193], v[222:225], v[0:3]
	s_barrier
; #define PG8_STAGE(bufoff, gbase, voff) do { _Pragma("unroll") for (int _i = 0; _i < 2; ++_i) \
;         __builtin_amdgcn_global_load_lds((const unsigned*)((const char*)(gbase) + (voff)[_i]), (PG8_LAS unsigned*)(lds + (bufoff) + ldsw + _i * 8192), 16, 0, 0); } while (0)
; #define PG8_LDA(dst, b, h) do { _Pragma("unroll") for (int m = 0; m < 4; ++m) _Pragma("unroll") for (int k = 0; k < 2; ++k) dst[m][k] = *(const PG8_LAS bf16x8*)(lds + PG8_SA(b, h) + aoff + m * 2048 + k * 1024); } while (0)
; #define PG8_LDB(dst, b, h) do { _Pragma("unroll") for (int n = 0; n < 2; ++n) _Pragma("unroll") for (int k = 0; k < 2; ++k) dst[n][k] = *(const PG8_LAS bf16x8*)(lds + PG8_SB(b, h) + boff + n * 2048 + k * 1024); } while (0)
; #define PG8_MMA(ai, bj, At, Bt) do { __builtin_amdgcn_s_setprio(1); _Pragma("unroll") for (int m = 0; m < 4; ++m) _Pragma("unroll") for (int n = 0; n < 2; ++n) _Pragma("unroll") for (int k = 0; k < 2; ++k) \
;         acc[ai][bj][m][n] = __builtin_amdgcn_mfma_f32_16x16x32_bf16(Bt[n][k], At[m][k], acc[ai][bj][m][n], 0, 0, 0); __builtin_amdgcn_s_setprio(0); } while (0)
; #define PG8_WAIT_V(n) asm volatile("s_waitcnt vmcnt(" #n ")" ::: "memory")
; #define PG8_WAIT_L(n) asm volatile("s_waitcnt lgkmcnt(" #n ")" ::: "memory")
; #define PG8_BAR __builtin_amdgcn_s_barrier()
; #define PG8_SCHED __builtin_amdgcn_sched_barrier(0)
; template <class Epi, class Sched, bool ALIGN_EPI = false, bool SP2 = false>
; __device__ __forceinline__ void gemm_phase(PG8_LAS unsigned char* lds, const Gemm g, const Sched& S, const Epi& E) {
;     ...
;         for (int t = 0; t < nt; t += 2) {
;             const bool last = (t == nt - 2);
;     ...
;             PG8_LDB(B0, 1, 0); PG8_LDB(B1, 1, 1); PG8_SCHED; PG8_LDA(At, 1, 0); PG8_STAGE(PG8_SA(0, 1), a2 + hstep, voffA);
;             PG8_WAIT_V(8); PG8_WAIT_L(0); PG8_BAR; PG8_MMA(0, 0, At, B0); PG8_MMA(0, 1, At, B1); PG8_BAR; PG8_SCHED;
;             PG8_LDA(At, 1, 1); PG8_STAGE(PG8_SB(1, 0), b3, voffB); PG8_STAGE(PG8_SB(1, 1), b3 + hstep, voffB); PG8_STAGE(PG8_SA(1, 0), a3, voffA);
;             PG8_WAIT_V(8); PG8_WAIT_L(0); PG8_BAR; PG8_MMA(1, 0, At, B0); PG8_MMA(1, 1, At, B1); PG8_BAR; PG8_SCHED;
	s_add_i32 s71, 0, 0x18000
	v_add_u32_e32 v130, s71, v160
	s_add_i32 s72, 0, 0x1c000
	ds_read_b128 v[148:151], v130
	ds_read_b128 v[166:169], v130 offset:1024
	ds_read_b128 v[170:173], v130 offset:2048
	ds_read_b128 v[174:177], v130 offset:3072
	v_add_u32_e32 v130, s72, v160
	ds_read_b128 v[178:181], v130
	ds_read_b128 v[182:185], v130 offset:1024
	ds_read_b128 v[186:189], v130 offset:2048
	ds_read_b128 v[190:193], v130 offset:3072
	s_add_u32 s42, s42, 0x40000
	s_addc_u32 s43, s43, 0
	s_mov_b32 m0, s54
	v_lshl_add_u64 v[234:235], s[42:43], 0, v[136:137]
	ds_read_b128 v[194:197], v164 offset:32768
	ds_read_b128 v[198:201], v164 offset:33792
	ds_read_b128 v[202:205], v164 offset:34816
	ds_read_b128 v[206:209], v164 offset:35840
	ds_read_b128 v[210:213], v164 offset:36864
	ds_read_b128 v[214:217], v164 offset:37888
	ds_read_b128 v[218:221], v164 offset:38912
	ds_read_b128 v[222:225], v164 offset:39936
	global_load_lds_dwordx4 v[234:235], off
	v_lshl_add_u64 v[234:235], s[42:43], 0, v[140:141]
	s_mov_b32 m0, s55
	s_nop 0
	global_load_lds_dwordx4 v[234:235], off
	s_waitcnt vmcnt(8)
	s_waitcnt lgkmcnt(0)
	s_setprio 1
	s_barrier
	v_mfma_f32_16x16x32_bf16 v[124:127], v[148:151], v[194:197], v[124:127]
	v_mfma_f32_16x16x32_bf16 v[120:123], v[170:173], v[194:197], v[120:123]
	v_mfma_f32_16x16x32_bf16 v[108:111], v[148:151], v[202:205], v[108:111]
	v_mfma_f32_16x16x32_bf16 v[104:107], v[170:173], v[202:205], v[104:107]
	v_mfma_f32_16x16x32_bf16 v[92:95], v[148:151], v[210:213], v[92:95]
	v_mfma_f32_16x16x32_bf16 v[88:91], v[170:173], v[210:213], v[88:91]
	v_mfma_f32_16x16x32_bf16 v[76:79], v[148:151], v[218:221], v[76:79]
	v_mfma_f32_16x16x32_bf16 v[72:75], v[170:173], v[218:221], v[72:75]
	v_mfma_f32_16x16x32_bf16 v[124:127], v[166:169], v[198:201], v[124:127]
	v_mfma_f32_16x16x32_bf16 v[120:123], v[174:177], v[198:201], v[120:123]
	v_mfma_f32_16x16x32_bf16 v[108:111], v[166:169], v[206:209], v[108:111]
	v_mfma_f32_16x16x32_bf16 v[104:107], v[174:177], v[206:209], v[104:107]
	v_mfma_f32_16x16x32_bf16 v[92:95], v[166:169], v[214:217], v[92:95]
	v_mfma_f32_16x16x32_bf16 v[88:91], v[174:177], v[214:217], v[88:91]
	v_mfma_f32_16x16x32_bf16 v[76:79], v[166:169], v[222:225], v[76:79]
	v_mfma_f32_16x16x32_bf16 v[72:75], v[174:177], v[222:225], v[72:75]
	v_mfma_f32_16x16x32_bf16 v[116:119], v[178:181], v[194:197], v[116:119]
	v_mfma_f32_16x16x32_bf16 v[112:115], v[186:189], v[194:197], v[112:115]
	v_mfma_f32_16x16x32_bf16 v[100:103], v[178:181], v[202:205], v[100:103]
	v_mfma_f32_16x16x32_bf16 v[96:99], v[186:189], v[202:205], v[96:99]
	v_mfma_f32_16x16x32_bf16 v[84:87], v[178:181], v[210:213], v[84:87]
	v_mfma_f32_16x16x32_bf16 v[80:83], v[186:189], v[210:213], v[80:83]
	v_mfma_f32_16x16x32_bf16 v[68:71], v[178:181], v[218:221], v[68:71]
	v_mfma_f32_16x16x32_bf16 v[64:67], v[186:189], v[218:221], v[64:67]
	v_mfma_f32_16x16x32_bf16 v[116:119], v[182:185], v[198:201], v[116:119]
	v_mfma_f32_16x16x32_bf16 v[112:115], v[190:193], v[198:201], v[112:115]
	v_mfma_f32_16x16x32_bf16 v[100:103], v[182:185], v[206:209], v[100:103]
	v_mfma_f32_16x16x32_bf16 v[96:99], v[190:193], v[206:209], v[96:99]
	v_mfma_f32_16x16x32_bf16 v[84:87], v[182:185], v[214:217], v[84:87]
	v_mfma_f32_16x16x32_bf16 v[80:83], v[190:193], v[214:217], v[80:83]
	v_mfma_f32_16x16x32_bf16 v[68:71], v[182:185], v[222:225], v[68:71]
	s_setprio 0
	v_mfma_f32_16x16x32_bf16 v[64:67], v[190:193], v[222:225], v[64:67]
	s_barrier
	s_add_i32 s42, s71, s33
	v_lshl_add_u64 v[226:227], v[226:227], 0, s[24:25]
	s_mov_b32 m0, s42
	ds_read_b128 v[194:197], v164 offset:49152
	ds_read_b128 v[198:201], v164 offset:50176
	ds_read_b128 v[202:205], v164 offset:51200
	ds_read_b128 v[206:209], v164 offset:52224
	ds_read_b128 v[210:213], v164 offset:53248
	ds_read_b128 v[214:217], v164 offset:54272
	ds_read_b128 v[218:221], v164 offset:55296
	ds_read_b128 v[222:225], v164 offset:56320
	global_load_lds_dwordx4 v[226:227], off
	s_add_i32 m0, s42, 0x2000
	s_add_u32 s40, s40, 0x40080
	v_lshl_add_u64 v[226:227], v[228:229], 0, s[24:25]
	s_addc_u32 s41, s41, 0
	s_add_i32 s42, s72, s33
	global_load_lds_dwordx4 v[226:227], off
	v_lshl_add_u64 v[226:227], s[40:41], 0, v[138:139]
	s_mov_b32 m0, s42
	s_nop 0
	global_load_lds_dwordx4 v[226:227], off
	v_lshl_add_u64 v[226:227], s[40:41], 0, v[142:143]
	s_add_i32 m0, s42, 0x2000
	s_nop 0
	global_load_lds_dwordx4 v[226:227], off
	v_lshl_add_u64 v[226:227], v[230:231], 0, s[24:25]
	s_mov_b32 m0, s57
	s_nop 0
	global_load_lds_dwordx4 v[226:227], off
	v_lshl_add_u64 v[226:227], v[232:233], 0, s[24:25]
	s_mov_b32 m0, s58
	s_nop 0
	global_load_lds_dwordx4 v[226:227], off
	s_waitcnt vmcnt(8)
	s_waitcnt lgkmcnt(0)
	s_setprio 1
	s_barrier
	v_mfma_f32_16x16x32_bf16 v[60:63], v[148:151], v[194:197], v[60:63]
	v_mfma_f32_16x16x32_bf16 v[56:59], v[170:173], v[194:197], v[56:59]
	v_mfma_f32_16x16x32_bf16 v[44:47], v[148:151], v[202:205], v[44:47]
	v_mfma_f32_16x16x32_bf16 v[40:43], v[170:173], v[202:205], v[40:43]
	v_mfma_f32_16x16x32_bf16 v[28:31], v[148:151], v[210:213], v[28:31]
	v_mfma_f32_16x16x32_bf16 v[24:27], v[170:173], v[210:213], v[24:27]
	v_mfma_f32_16x16x32_bf16 v[12:15], v[148:151], v[218:221], v[12:15]
	v_mfma_f32_16x16x32_bf16 v[8:11], v[170:173], v[218:221], v[8:11]
	v_mfma_f32_16x16x32_bf16 v[60:63], v[166:169], v[198:201], v[60:63]
	v_mfma_f32_16x16x32_bf16 v[56:59], v[174:177], v[198:201], v[56:59]
	v_mfma_f32_16x16x32_bf16 v[44:47], v[166:169], v[206:209], v[44:47]
	v_mfma_f32_16x16x32_bf16 v[40:43], v[174:177], v[206:209], v[40:43]
	v_mfma_f32_16x16x32_bf16 v[28:31], v[166:169], v[214:217], v[28:31]
	v_mfma_f32_16x16x32_bf16 v[24:27], v[174:177], v[214:217], v[24:27]
	v_mfma_f32_16x16x32_bf16 v[12:15], v[166:169], v[222:225], v[12:15]
	v_mfma_f32_16x16x32_bf16 v[8:11], v[174:177], v[222:225], v[8:11]
	v_mfma_f32_16x16x32_bf16 v[52:55], v[178:181], v[194:197], v[52:55]
	v_mfma_f32_16x16x32_bf16 v[48:51], v[186:189], v[194:197], v[48:51]
	v_mfma_f32_16x16x32_bf16 v[36:39], v[178:181], v[202:205], v[36:39]
	v_mfma_f32_16x16x32_bf16 v[32:35], v[186:189], v[202:205], v[32:35]
	v_mfma_f32_16x16x32_bf16 v[20:23], v[178:181], v[210:213], v[20:23]
	v_mfma_f32_16x16x32_bf16 v[16:19], v[186:189], v[210:213], v[16:19]
	v_mfma_f32_16x16x32_bf16 v[4:7], v[178:181], v[218:221], v[4:7]
	v_mfma_f32_16x16x32_bf16 v[0:3], v[186:189], v[218:221], v[0:3]
	v_mfma_f32_16x16x32_bf16 v[52:55], v[182:185], v[198:201], v[52:55]
	v_mfma_f32_16x16x32_bf16 v[48:51], v[190:193], v[198:201], v[48:51]
	v_mfma_f32_16x16x32_bf16 v[36:39], v[182:185], v[206:209], v[36:39]
	v_mfma_f32_16x16x32_bf16 v[32:35], v[190:193], v[206:209], v[32:35]
	v_mfma_f32_16x16x32_bf16 v[20:23], v[182:185], v[214:217], v[20:23]
	v_mfma_f32_16x16x32_bf16 v[16:19], v[190:193], v[214:217], v[16:19]
	v_mfma_f32_16x16x32_bf16 v[4:7], v[182:185], v[222:225], v[4:7]
	s_setprio 0
	v_mfma_f32_16x16x32_bf16 v[0:3], v[190:193], v[222:225], v[0:3]
	s_barrier
	s_add_i32 s70, s70, 2
	s_add_u32 s38, s38, 0x100
	s_addc_u32 s39, s39, 0
	s_add_u32 s44, s44, 0x100
	s_addc_u32 s45, s45, 0
	s_cmp_gt_u32 s70, 13
; #define PG8_STAGE(bufoff, gbase, voff) do { _Pragma("unroll") for (int _i = 0; _i < 2; ++_i) \
;         __builtin_amdgcn_global_load_lds((const unsigned*)((const char*)(gbase) + (voff)[_i]), (PG8_LAS unsigned*)(lds + (bufoff) + ldsw + _i * 8192), 16, 0, 0); } while (0)
; #define PG8_LDA(dst, b, h) do { _Pragma("unroll") for (int m = 0; m < 4; ++m) _Pragma("unroll") for (int k = 0; k < 2; ++k) dst[m][k] = *(const PG8_LAS bf16x8*)(lds + PG8_SA(b, h) + aoff + m * 2048 + k * 1024); } while (0)
; #define PG8_LDB(dst, b, h) do { _Pragma("unroll") for (int n = 0; n < 2; ++n) _Pragma("unroll") for (int k = 0; k < 2; ++k) dst[n][k] = *(const PG8_LAS bf16x8*)(lds + PG8_SB(b, h) + boff + n * 2048 + k * 1024); } while (0)
; #define PG8_MMA(ai, bj, At, Bt) do { __builtin_amdgcn_s_setprio(1); _Pragma("unroll") for (int m = 0; m < 4; ++m) _Pragma("unroll") for (int n = 0; n < 2; ++n) _Pragma("unroll") for (int k = 0; k < 2; ++k) \
;         acc[ai][bj][m][n] = __builtin_amdgcn_mfma_f32_16x16x32_bf16(Bt[n][k], At[m][k], acc[ai][bj][m][n], 0, 0, 0); __builtin_amdgcn_s_setprio(0); } while (0)
; #define PG8_WAIT_V(n) asm volatile("s_waitcnt vmcnt(" #n ")" ::: "memory")
; #define PG8_WAIT_L(n) asm volatile("s_waitcnt lgkmcnt(" #n ")" ::: "memory")
; #define PG8_BAR __builtin_amdgcn_s_barrier()
; #define PG8_SCHED __builtin_amdgcn_sched_barrier(0)
; template <class Epi, class Sched, bool ALIGN_EPI = false, bool SP2 = false>
; __device__ __forceinline__ void gemm_phase(PG8_LAS unsigned char* lds, const Gemm g, const Sched& S, const Epi& E) {
;     ...
;             PG8_LDB(B0, 0, 0); PG8_LDB(B1, 0, 1); PG8_SCHED; PG8_LDA(At, 0, 0); PG8_STAGE(PG8_SA(1, 1), a1 + hstep, voffA);
;             PG8_WAIT_V(8); PG8_WAIT_L(0); PG8_BAR; PG8_MMA(0, 0, At, B0); PG8_MMA(0, 1, At, B1); PG8_BAR; PG8_SCHED;
;             PG8_LDA(At, 0, 1); PG8_STAGE(PG8_SB(0, 0), b2, voffB); PG8_STAGE(PG8_SB(0, 1), b2 + hstep, voffB); PG8_STAGE(PG8_SA(0, 0), a2, voffA);
;             PG8_WAIT_V(8); PG8_WAIT_L(0); PG8_BAR; PG8_MMA(1, 0, At, B0); PG8_MMA(1, 1, At, B1); PG8_BAR; PG8_SCHED;
.LBB0_509:
	ds_read_b128 v[148:151], v162
	ds_read_b128 v[166:169], v162 offset:1024
	ds_read_b128 v[170:173], v162 offset:2048
	ds_read_b128 v[174:177], v162 offset:3072
	ds_read_b128 v[178:181], v163
	ds_read_b128 v[182:185], v163 offset:1024
	ds_read_b128 v[186:189], v163 offset:2048
	ds_read_b128 v[190:193], v163 offset:3072
	s_add_u32 s40, s38, 0xfffc0080
	s_addc_u32 s41, s39, -1
	s_cmp_eq_u32 s70, 12
	s_cselect_b32 s43, s9, s41
	s_cselect_b32 s42, s14, s40
	s_cselect_b32 s41, s29, s45
	s_cselect_b32 s40, s31, s44
	v_lshl_add_u64 v[226:227], s[38:39], 0, v[132:133]
	s_add_i32 m0, s52, 0xc000
	ds_read_b128 v[194:197], v164
	ds_read_b128 v[198:201], v164 offset:1024
	ds_read_b128 v[202:205], v164 offset:2048
	ds_read_b128 v[206:209], v164 offset:3072
	ds_read_b128 v[210:213], v164 offset:4096
	ds_read_b128 v[214:217], v164 offset:5120
	ds_read_b128 v[218:221], v164 offset:6144
	ds_read_b128 v[222:225], v164 offset:7168
	global_load_lds_dwordx4 v[226:227], off
	v_lshl_add_u64 v[226:227], s[38:39], 0, v[134:135]
	s_add_i32 m0, s52, 0xe000
	s_nop 0
	global_load_lds_dwordx4 v[226:227], off
	s_waitcnt vmcnt(8)
	s_waitcnt lgkmcnt(0)
	s_setprio 1
	s_barrier
	v_mfma_f32_16x16x32_bf16 v[124:127], v[148:151], v[194:197], v[124:127]
	v_mfma_f32_16x16x32_bf16 v[120:123], v[170:173], v[194:197], v[120:123]
	v_mfma_f32_16x16x32_bf16 v[108:111], v[148:151], v[202:205], v[108:111]
	v_mfma_f32_16x16x32_bf16 v[104:107], v[170:173], v[202:205], v[104:107]
	v_mfma_f32_16x16x32_bf16 v[92:95], v[148:151], v[210:213], v[92:95]
	v_mfma_f32_16x16x32_bf16 v[88:91], v[170:173], v[210:213], v[88:91]
	v_mfma_f32_16x16x32_bf16 v[76:79], v[148:151], v[218:221], v[76:79]
	v_mfma_f32_16x16x32_bf16 v[72:75], v[170:173], v[218:221], v[72:75]
	v_mfma_f32_16x16x32_bf16 v[124:127], v[166:169], v[198:201], v[124:127]
	v_mfma_f32_16x16x32_bf16 v[120:123], v[174:177], v[198:201], v[120:123]
	v_mfma_f32_16x16x32_bf16 v[108:111], v[166:169], v[206:209], v[108:111]
	v_mfma_f32_16x16x32_bf16 v[104:107], v[174:177], v[206:209], v[104:107]
	v_mfma_f32_16x16x32_bf16 v[92:95], v[166:169], v[214:217], v[92:95]
	v_mfma_f32_16x16x32_bf16 v[88:91], v[174:177], v[214:217], v[88:91]
	v_mfma_f32_16x16x32_bf16 v[76:79], v[166:169], v[222:225], v[76:79]
	v_mfma_f32_16x16x32_bf16 v[72:75], v[174:177], v[222:225], v[72:75]
	v_mfma_f32_16x16x32_bf16 v[116:119], v[178:181], v[194:197], v[116:119]
	v_mfma_f32_16x16x32_bf16 v[112:115], v[186:189], v[194:197], v[112:115]
	v_mfma_f32_16x16x32_bf16 v[100:103], v[178:181], v[202:205], v[100:103]
	v_mfma_f32_16x16x32_bf16 v[96:99], v[186:189], v[202:205], v[96:99]
	v_mfma_f32_16x16x32_bf16 v[84:87], v[178:181], v[210:213], v[84:87]
	v_mfma_f32_16x16x32_bf16 v[80:83], v[186:189], v[210:213], v[80:83]
	v_mfma_f32_16x16x32_bf16 v[68:71], v[178:181], v[218:221], v[68:71]
	v_mfma_f32_16x16x32_bf16 v[64:67], v[186:189], v[218:221], v[64:67]
	v_mfma_f32_16x16x32_bf16 v[116:119], v[182:185], v[198:201], v[116:119]
	v_mfma_f32_16x16x32_bf16 v[112:115], v[190:193], v[198:201], v[112:115]
	v_mfma_f32_16x16x32_bf16 v[100:103], v[182:185], v[206:209], v[100:103]
	v_mfma_f32_16x16x32_bf16 v[96:99], v[190:193], v[206:209], v[96:99]
	v_mfma_f32_16x16x32_bf16 v[84:87], v[182:185], v[214:217], v[84:87]
	v_mfma_f32_16x16x32_bf16 v[80:83], v[190:193], v[214:217], v[80:83]
	v_mfma_f32_16x16x32_bf16 v[68:71], v[182:185], v[222:225], v[68:71]
	s_setprio 0
	v_mfma_f32_16x16x32_bf16 v[64:67], v[190:193], v[222:225], v[64:67]
	s_barrier
	s_add_i32 s71, s61, s33
	v_lshl_add_u64 v[226:227], s[40:41], 0, v[138:139]
	s_mov_b32 m0, s71
	ds_read_b128 v[194:197], v164 offset:16384
	ds_read_b128 v[198:201], v164 offset:17408
	ds_read_b128 v[202:205], v164 offset:18432
	ds_read_b128 v[206:209], v164 offset:19456
	ds_read_b128 v[210:213], v164 offset:20480
	ds_read_b128 v[214:217], v164 offset:21504
	ds_read_b128 v[218:221], v164 offset:22528
	ds_read_b128 v[222:225], v164 offset:23552
	global_load_lds_dwordx4 v[226:227], off
	s_add_i32 m0, s71, 0x2000
	s_add_u32 s72, s40, 0x40000
	v_lshl_add_u64 v[228:229], s[40:41], 0, v[142:143]
	s_addc_u32 s73, s41, 0
	s_add_i32 s71, s62, s33
	global_load_lds_dwordx4 v[228:229], off
	v_lshl_add_u64 v[230:231], s[72:73], 0, v[138:139]
	s_mov_b32 m0, s71
	v_lshl_add_u64 v[232:233], s[42:43], 0, v[140:141]
	global_load_lds_dwordx4 v[230:231], off
	v_lshl_add_u64 v[230:231], s[72:73], 0, v[142:143]
	s_add_i32 m0, s71, 0x2000
	s_nop 0
	global_load_lds_dwordx4 v[230:231], off
	v_lshl_add_u64 v[230:231], s[42:43], 0, v[136:137]
	s_mov_b32 m0, s52
	s_nop 0
	global_load_lds_dwordx4 v[230:231], off
	s_mov_b32 m0, s53
	s_nop 0
	global_load_lds_dwordx4 v[232:233], off
	s_waitcnt vmcnt(8)
	s_waitcnt lgkmcnt(0)
	s_setprio 1
	s_barrier
; #define PG8_STAGE(bufoff, gbase, voff) do { _Pragma("unroll") for (int _i = 0; _i < 2; ++_i) \
;         __builtin_amdgcn_global_load_lds((const unsigned*)((const char*)(gbase) + (voff)[_i]), (PG8_LAS unsigned*)(lds + (bufoff) + ldsw + _i * 8192), 16, 0, 0); } while (0)
; #define PG8_LDA(dst, b, h) do { _Pragma("unroll") for (int m = 0; m < 4; ++m) _Pragma("unroll") for (int k = 0; k < 2; ++k) dst[m][k] = *(const PG8_LAS bf16x8*)(lds + PG8_SA(b, h) + aoff + m * 2048 + k * 1024); } while (0)
; #define PG8_LDB(dst, b, h) do { _Pragma("unroll") for (int n = 0; n < 2; ++n) _Pragma("unroll") for (int k = 0; k < 2; ++k) dst[n][k] = *(const PG8_LAS bf16x8*)(lds + PG8_SB(b, h) + boff + n * 2048 + k * 1024); } while (0)
; #define PG8_MMA(ai, bj, At, Bt) do { __builtin_amdgcn_s_setprio(1); _Pragma("unroll") for (int m = 0; m < 4; ++m) _Pragma("unroll") for (int n = 0; n < 2; ++n) _Pragma("unroll") for (int k = 0; k < 2; ++k) \
;         acc[ai][bj][m][n] = __builtin_amdgcn_mfma_f32_16x16x32_bf16(Bt[n][k], At[m][k], acc[ai][bj][m][n], 0, 0, 0); __builtin_amdgcn_s_setprio(0); } while (0)
; #define PG8_WAIT_V(n) asm volatile("s_waitcnt vmcnt(" #n ")" ::: "memory")
; #define PG8_WAIT_L(n) asm volatile("s_waitcnt lgkmcnt(" #n ")" ::: "memory")
; #define PG8_BAR __builtin_amdgcn_s_barrier()
; #define PG8_SCHED __builtin_amdgcn_sched_barrier(0)
; template <class Epi, class Sched, bool ALIGN_EPI = false, bool SP2 = false>
; __device__ __forceinline__ void gemm_phase(PG8_LAS unsigned char* lds, const Gemm g, const Sched& S, const Epi& E) {
;     ...
;             PG8_WAIT_V(8); PG8_WAIT_L(0); PG8_BAR; PG8_MMA(0, 0, At, B0); PG8_MMA(0, 1, At, B1); PG8_BAR; PG8_SCHED;
;             PG8_LDA(At, 0, 1); PG8_STAGE(PG8_SB(0, 0), b2, voffB); PG8_STAGE(PG8_SB(0, 1), b2 + hstep, voffB); PG8_STAGE(PG8_SA(0, 0), a2, voffA);
;             PG8_WAIT_V(8); PG8_WAIT_L(0); PG8_BAR; PG8_MMA(1, 0, At, B0); PG8_MMA(1, 1, At, B1); PG8_BAR; PG8_SCHED;
;             PG8_LDB(B0, 1, 0); PG8_LDB(B1, 1, 1); PG8_SCHED; PG8_LDA(At, 1, 0); PG8_STAGE(PG8_SA(0, 1), a2 + hstep, voffA);
;             PG8_WAIT_V(8); PG8_WAIT_L(0); PG8_BAR; PG8_MMA(0, 0, At, B0); PG8_MMA(0, 1, At, B1); PG8_BAR; PG8_SCHED;
	v_mfma_f32_16x16x32_bf16 v[60:63], v[148:151], v[194:197], v[60:63]
	v_mfma_f32_16x16x32_bf16 v[56:59], v[170:173], v[194:197], v[56:59]
	v_mfma_f32_16x16x32_bf16 v[44:47], v[148:151], v[202:205], v[44:47]
	v_mfma_f32_16x16x32_bf16 v[40:43], v[170:173], v[202:205], v[40:43]
	v_mfma_f32_16x16x32_bf16 v[28:31], v[148:151], v[210:213], v[28:31]
	v_mfma_f32_16x16x32_bf16 v[24:27], v[170:173], v[210:213], v[24:27]
	v_mfma_f32_16x16x32_bf16 v[12:15], v[148:151], v[218:221], v[12:15]
	v_mfma_f32_16x16x32_bf16 v[8:11], v[170:173], v[218:221], v[8:11]
	v_mfma_f32_16x16x32_bf16 v[60:63], v[166:169], v[198:201], v[60:63]
	v_mfma_f32_16x16x32_bf16 v[56:59], v[174:177], v[198:201], v[56:59]
	v_mfma_f32_16x16x32_bf16 v[44:47], v[166:169], v[206:209], v[44:47]
	v_mfma_f32_16x16x32_bf16 v[40:43], v[174:177], v[206:209], v[40:43]
	v_mfma_f32_16x16x32_bf16 v[28:31], v[166:169], v[214:217], v[28:31]
	v_mfma_f32_16x16x32_bf16 v[24:27], v[174:177], v[214:217], v[24:27]
	v_mfma_f32_16x16x32_bf16 v[12:15], v[166:169], v[222:225], v[12:15]
	v_mfma_f32_16x16x32_bf16 v[8:11], v[174:177], v[222:225], v[8:11]
	v_mfma_f32_16x16x32_bf16 v[52:55], v[178:181], v[194:197], v[52:55]
	v_mfma_f32_16x16x32_bf16 v[48:51], v[186:189], v[194:197], v[48:51]
	v_mfma_f32_16x16x32_bf16 v[36:39], v[178:181], v[202:205], v[36:39]
	v_mfma_f32_16x16x32_bf16 v[32:35], v[186:189], v[202:205], v[32:35]
	v_mfma_f32_16x16x32_bf16 v[20:23], v[178:181], v[210:213], v[20:23]
	v_mfma_f32_16x16x32_bf16 v[16:19], v[186:189], v[210:213], v[16:19]
	v_mfma_f32_16x16x32_bf16 v[4:7], v[178:181], v[218:221], v[4:7]
	v_mfma_f32_16x16x32_bf16 v[0:3], v[186:189], v[218:221], v[0:3]
	v_mfma_f32_16x16x32_bf16 v[52:55], v[182:185], v[198:201], v[52:55]
	v_mfma_f32_16x16x32_bf16 v[48:51], v[190:193], v[198:201], v[48:51]
	v_mfma_f32_16x16x32_bf16 v[36:39], v[182:185], v[206:209], v[36:39]
	v_mfma_f32_16x16x32_bf16 v[32:35], v[190:193], v[206:209], v[32:35]
	v_mfma_f32_16x16x32_bf16 v[20:23], v[182:185], v[214:217], v[20:23]
	v_mfma_f32_16x16x32_bf16 v[16:19], v[190:193], v[214:217], v[16:19]
	v_mfma_f32_16x16x32_bf16 v[4:7], v[182:185], v[222:225], v[4:7]
	s_setprio 0
	v_mfma_f32_16x16x32_bf16 v[0:3], v[190:193], v[222:225], v[0:3]
	s_barrier
	s_add_i32 s71, 0, 0x18000
	v_add_u32_e32 v130, s71, v160
	s_add_i32 s72, 0, 0x1c000
	ds_read_b128 v[148:151], v130
	ds_read_b128 v[166:169], v130 offset:1024
	ds_read_b128 v[170:173], v130 offset:2048
	ds_read_b128 v[174:177], v130 offset:3072
	v_add_u32_e32 v130, s72, v160
	ds_read_b128 v[178:181], v130
	ds_read_b128 v[182:185], v130 offset:1024
	ds_read_b128 v[186:189], v130 offset:2048
	ds_read_b128 v[190:193], v130 offset:3072
	s_add_u32 s42, s42, 0x40000
	s_addc_u32 s43, s43, 0
	s_mov_b32 m0, s54
	v_lshl_add_u64 v[234:235], s[42:43], 0, v[136:137]
	ds_read_b128 v[194:197], v164 offset:32768
	ds_read_b128 v[198:201], v164 offset:33792
	ds_read_b128 v[202:205], v164 offset:34816
	ds_read_b128 v[206:209], v164 offset:35840
	ds_read_b128 v[210:213], v164 offset:36864
	ds_read_b128 v[214:217], v164 offset:37888
	ds_read_b128 v[218:221], v164 offset:38912
	ds_read_b128 v[222:225], v164 offset:39936
	global_load_lds_dwordx4 v[234:235], off
	v_lshl_add_u64 v[234:235], s[42:43], 0, v[140:141]
	s_mov_b32 m0, s55
	s_nop 0
	global_load_lds_dwordx4 v[234:235], off
	s_waitcnt vmcnt(8)
	s_waitcnt lgkmcnt(0)
	s_setprio 1
	s_barrier
	v_mfma_f32_16x16x32_bf16 v[124:127], v[148:151], v[194:197], v[124:127]
	v_mfma_f32_16x16x32_bf16 v[120:123], v[170:173], v[194:197], v[120:123]
	v_mfma_f32_16x16x32_bf16 v[108:111], v[148:151], v[202:205], v[108:111]
	v_mfma_f32_16x16x32_bf16 v[104:107], v[170:173], v[202:205], v[104:107]
	v_mfma_f32_16x16x32_bf16 v[92:95], v[148:151], v[210:213], v[92:95]
	v_mfma_f32_16x16x32_bf16 v[88:91], v[170:173], v[210:213], v[88:91]
	v_mfma_f32_16x16x32_bf16 v[76:79], v[148:151], v[218:221], v[76:79]
	v_mfma_f32_16x16x32_bf16 v[72:75], v[170:173], v[218:221], v[72:75]
	v_mfma_f32_16x16x32_bf16 v[124:127], v[166:169], v[198:201], v[124:127]
	v_mfma_f32_16x16x32_bf16 v[120:123], v[174:177], v[198:201], v[120:123]
	v_mfma_f32_16x16x32_bf16 v[108:111], v[166:169], v[206:209], v[108:111]
	v_mfma_f32_16x16x32_bf16 v[104:107], v[174:177], v[206:209], v[104:107]
	v_mfma_f32_16x16x32_bf16 v[92:95], v[166:169], v[214:217], v[92:95]
	v_mfma_f32_16x16x32_bf16 v[88:91], v[174:177], v[214:217], v[88:91]
	v_mfma_f32_16x16x32_bf16 v[76:79], v[166:169], v[222:225], v[76:79]
	v_mfma_f32_16x16x32_bf16 v[72:75], v[174:177], v[222:225], v[72:75]
	v_mfma_f32_16x16x32_bf16 v[116:119], v[178:181], v[194:197], v[116:119]
	v_mfma_f32_16x16x32_bf16 v[112:115], v[186:189], v[194:197], v[112:115]
	v_mfma_f32_16x16x32_bf16 v[100:103], v[178:181], v[202:205], v[100:103]
	v_mfma_f32_16x16x32_bf16 v[96:99], v[186:189], v[202:205], v[96:99]
	v_mfma_f32_16x16x32_bf16 v[84:87], v[178:181], v[210:213], v[84:87]
	v_mfma_f32_16x16x32_bf16 v[80:83], v[186:189], v[210:213], v[80:83]
	v_mfma_f32_16x16x32_bf16 v[68:71], v[178:181], v[218:221], v[68:71]
	v_mfma_f32_16x16x32_bf16 v[64:67], v[186:189], v[218:221], v[64:67]
	v_mfma_f32_16x16x32_bf16 v[116:119], v[182:185], v[198:201], v[116:119]
	v_mfma_f32_16x16x32_bf16 v[112:115], v[190:193], v[198:201], v[112:115]
	v_mfma_f32_16x16x32_bf16 v[100:103], v[182:185], v[206:209], v[100:103]
	v_mfma_f32_16x16x32_bf16 v[96:99], v[190:193], v[206:209], v[96:99]
	v_mfma_f32_16x16x32_bf16 v[84:87], v[182:185], v[214:217], v[84:87]
	v_mfma_f32_16x16x32_bf16 v[80:83], v[190:193], v[214:217], v[80:83]
	v_mfma_f32_16x16x32_bf16 v[68:71], v[182:185], v[222:225], v[68:71]
	s_setprio 0
	v_mfma_f32_16x16x32_bf16 v[64:67], v[190:193], v[222:225], v[64:67]
	s_barrier
; #define PG8_STAGE(bufoff, gbase, voff) do { _Pragma("unroll") for (int _i = 0; _i < 2; ++_i) \
;         __builtin_amdgcn_global_load_lds((const unsigned*)((const char*)(gbase) + (voff)[_i]), (PG8_LAS unsigned*)(lds + (bufoff) + ldsw + _i * 8192), 16, 0, 0); } while (0)
; #define PG8_LDA(dst, b, h) do { _Pragma("unroll") for (int m = 0; m < 4; ++m) _Pragma("unroll") for (int k = 0; k < 2; ++k) dst[m][k] = *(const PG8_LAS bf16x8*)(lds + PG8_SA(b, h) + aoff + m * 2048 + k * 1024); } while (0)
; #define PG8_MMA(ai, bj, At, Bt) do { __builtin_amdgcn_s_setprio(1); _Pragma("unroll") for (int m = 0; m < 4; ++m) _Pragma("unroll") for (int n = 0; n < 2; ++n) _Pragma("unroll") for (int k = 0; k < 2; ++k) \
;         acc[ai][bj][m][n] = __builtin_amdgcn_mfma_f32_16x16x32_bf16(Bt[n][k], At[m][k], acc[ai][bj][m][n], 0, 0, 0); __builtin_amdgcn_s_setprio(0); } while (0)
; #define PG8_WAIT_V(n) asm volatile("s_waitcnt vmcnt(" #n ")" ::: "memory")
; #define PG8_WAIT_L(n) asm volatile("s_waitcnt lgkmcnt(" #n ")" ::: "memory")
; #define PG8_BAR __builtin_amdgcn_s_barrier()
; #define PG8_SCHED __builtin_amdgcn_sched_barrier(0)
; template <class Epi, class Sched, bool ALIGN_EPI = false, bool SP2 = false>
; __device__ __forceinline__ void gemm_phase(PG8_LAS unsigned char* lds, const Gemm g, const Sched& S, const Epi& E) {
;     ...
;             PG8_LDA(At, 1, 1); PG8_STAGE(PG8_SB(1, 0), b3, voffB); PG8_STAGE(PG8_SB(1, 1), b3 + hstep, voffB); PG8_STAGE(PG8_SA(1, 0), a3, voffA);
;             PG8_WAIT_V(8); PG8_WAIT_L(0); PG8_BAR; PG8_MMA(1, 0, At, B0); PG8_MMA(1, 1, At, B1); PG8_BAR; PG8_SCHED;
;     ...
;         if constexpr (ALIGN_EPI) { if (wr == 0) PG8_BAR; }
	s_add_i32 s42, s71, s33
	v_lshl_add_u64 v[226:227], v[226:227], 0, s[24:25]
	s_mov_b32 m0, s42
	ds_read_b128 v[194:197], v164 offset:49152
	ds_read_b128 v[198:201], v164 offset:50176
	ds_read_b128 v[202:205], v164 offset:51200
	ds_read_b128 v[206:209], v164 offset:52224
	ds_read_b128 v[210:213], v164 offset:53248
	ds_read_b128 v[214:217], v164 offset:54272
	ds_read_b128 v[218:221], v164 offset:55296
	ds_read_b128 v[222:225], v164 offset:56320
	global_load_lds_dwordx4 v[226:227], off
	s_add_i32 m0, s42, 0x2000
	s_add_u32 s40, s40, 0x40080
	v_lshl_add_u64 v[226:227], v[228:229], 0, s[24:25]
	s_addc_u32 s41, s41, 0
	s_add_i32 s42, s72, s33
	global_load_lds_dwordx4 v[226:227], off
	v_lshl_add_u64 v[226:227], s[40:41], 0, v[138:139]
	s_mov_b32 m0, s42
	s_nop 0
	global_load_lds_dwordx4 v[226:227], off
	v_lshl_add_u64 v[226:227], s[40:41], 0, v[142:143]
	s_add_i32 m0, s42, 0x2000
	s_nop 0
	global_load_lds_dwordx4 v[226:227], off
	v_lshl_add_u64 v[226:227], v[230:231], 0, s[24:25]
	s_mov_b32 m0, s57
	s_nop 0
	global_load_lds_dwordx4 v[226:227], off
	v_lshl_add_u64 v[226:227], v[232:233], 0, s[24:25]
	s_mov_b32 m0, s58
	s_nop 0
	global_load_lds_dwordx4 v[226:227], off
	s_waitcnt vmcnt(8)
	s_waitcnt lgkmcnt(0)
	s_setprio 1
	s_barrier
	v_mfma_f32_16x16x32_bf16 v[60:63], v[148:151], v[194:197], v[60:63]
	v_mfma_f32_16x16x32_bf16 v[56:59], v[170:173], v[194:197], v[56:59]
	v_mfma_f32_16x16x32_bf16 v[44:47], v[148:151], v[202:205], v[44:47]
	v_mfma_f32_16x16x32_bf16 v[40:43], v[170:173], v[202:205], v[40:43]
	v_mfma_f32_16x16x32_bf16 v[28:31], v[148:151], v[210:213], v[28:31]
	v_mfma_f32_16x16x32_bf16 v[24:27], v[170:173], v[210:213], v[24:27]
	v_mfma_f32_16x16x32_bf16 v[12:15], v[148:151], v[218:221], v[12:15]
	v_mfma_f32_16x16x32_bf16 v[8:11], v[170:173], v[218:221], v[8:11]
	v_mfma_f32_16x16x32_bf16 v[60:63], v[166:169], v[198:201], v[60:63]
	v_mfma_f32_16x16x32_bf16 v[56:59], v[174:177], v[198:201], v[56:59]
	v_mfma_f32_16x16x32_bf16 v[44:47], v[166:169], v[206:209], v[44:47]
	v_mfma_f32_16x16x32_bf16 v[40:43], v[174:177], v[206:209], v[40:43]
	v_mfma_f32_16x16x32_bf16 v[28:31], v[166:169], v[214:217], v[28:31]
	v_mfma_f32_16x16x32_bf16 v[24:27], v[174:177], v[214:217], v[24:27]
	v_mfma_f32_16x16x32_bf16 v[12:15], v[166:169], v[222:225], v[12:15]
	v_mfma_f32_16x16x32_bf16 v[8:11], v[174:177], v[222:225], v[8:11]
	v_mfma_f32_16x16x32_bf16 v[52:55], v[178:181], v[194:197], v[52:55]
	v_mfma_f32_16x16x32_bf16 v[48:51], v[186:189], v[194:197], v[48:51]
	v_mfma_f32_16x16x32_bf16 v[36:39], v[178:181], v[202:205], v[36:39]
	v_mfma_f32_16x16x32_bf16 v[32:35], v[186:189], v[202:205], v[32:35]
	v_mfma_f32_16x16x32_bf16 v[20:23], v[178:181], v[210:213], v[20:23]
	v_mfma_f32_16x16x32_bf16 v[16:19], v[186:189], v[210:213], v[16:19]
	v_mfma_f32_16x16x32_bf16 v[4:7], v[178:181], v[218:221], v[4:7]
	v_mfma_f32_16x16x32_bf16 v[0:3], v[186:189], v[218:221], v[0:3]
	v_mfma_f32_16x16x32_bf16 v[52:55], v[182:185], v[198:201], v[52:55]
	v_mfma_f32_16x16x32_bf16 v[48:51], v[190:193], v[198:201], v[48:51]
	v_mfma_f32_16x16x32_bf16 v[36:39], v[182:185], v[206:209], v[36:39]
	v_mfma_f32_16x16x32_bf16 v[32:35], v[190:193], v[206:209], v[32:35]
	v_mfma_f32_16x16x32_bf16 v[20:23], v[182:185], v[214:217], v[20:23]
	v_mfma_f32_16x16x32_bf16 v[16:19], v[190:193], v[214:217], v[16:19]
	v_mfma_f32_16x16x32_bf16 v[4:7], v[182:185], v[222:225], v[4:7]
	s_setprio 0
	v_mfma_f32_16x16x32_bf16 v[0:3], v[190:193], v[222:225], v[0:3]
	s_barrier
	s_add_i32 s70, s70, 2
	s_add_u32 s38, s38, 0x100
	s_addc_u32 s39, s39, 0
	s_add_u32 s44, s44, 0x100
	s_addc_u32 s45, s45, 0
	s_cmp_gt_u32 s70, 13
	s_cbranch_scc0 .LBB0_509
	s_and_b64 vcc, exec, s[26:27]
	s_cbranch_vccz .LBB0_512
	s_barrier

; #define PG8_STAGE(bufoff, gbase, voff) do { _Pragma("unroll") for (int _i = 0; _i < 2; ++_i) \
;         __builtin_amdgcn_global_load_lds((const unsigned*)((const char*)(gbase) + (voff)[_i]), (PG8_LAS unsigned*)(lds + (bufoff) + ldsw + _i * 8192), 16, 0, 0); } while (0)
; #define PG8_LDA(dst, b, h) do { _Pragma("unroll") for (int m = 0; m < 4; ++m) _Pragma("unroll") for (int k = 0; k < 2; ++k) dst[m][k] = *(const PG8_LAS bf16x8*)(lds + PG8_SA(b, h) + aoff + m * 2048 + k * 1024); } while (0)
; #define PG8_LDB(dst, b, h) do { _Pragma("unroll") for (int n = 0; n < 2; ++n) _Pragma("unroll") for (int k = 0; k < 2; ++k) dst[n][k] = *(const PG8_LAS bf16x8*)(lds + PG8_SB(b, h) + boff + n * 2048 + k * 1024); } while (0)
; #define PG8_WAIT_V(n) asm volatile("s_waitcnt vmcnt(" #n ")" ::: "memory")
; #define PG8_WAIT_L(n) asm volatile("s_waitcnt lgkmcnt(" #n ")" ::: "memory")
; #define PG8_BAR __builtin_amdgcn_s_barrier()
; #define PG8_SCHED __builtin_amdgcn_sched_barrier(0)
; template <class Epi, class Sched, bool ALIGN_EPI = false, bool SP2 = false>
; __device__ __forceinline__ void gemm_phase(PG8_LAS unsigned char* lds, const Gemm g, const Sched& S, const Epi& E) {
;     ...
;         const bool has_next = S.next(ui + 1, nxt);
;         const char* nA = has_next ? (const char*)g.A + (size_t)nxt.pm * tstep : cA; const char* nB = has_next ? (const char*)g.Bt + (size_t)nxt.pn * tstep : cB;
;         for (int t = 0; t < nt; t += 2) {
;             const bool last = (t == nt - 2);
;             const char* a1 = cA + (size_t)(t + 1) * kstep;
;             const char* a2 = last ? nA : cA + (size_t)(t + 2) * kstep; const char* b2 = last ? nB : cB + (size_t)(t + 2) * kstep;
;             const char* a3 = a2 + kstep; const char* b3 = b2 + kstep;
;             if (last && has_next) S.a_ready(nxt, ui + 1);
;             if constexpr (SP2) {
;             PG8_LDB(B0, 0, 0); PG8_LDB(B1, 0, 1); PG8_SCHED; PG8_LDA(At, 0, 0); PG8_STAGE(PG8_SA(1, 1), a1 + hstep, voffA);
;             PG8_WAIT_V(8); PG8_WAIT_L(0); PG8_BAR; PG8_MMA(0, 0, At, B0); PG8_MMA(0, 1, At, B1); PG8_BAR; PG8_SCHED;
;             PG8_LDA(At, 0, 1); PG8_STAGE(PG8_SB(0, 0), b2, voffB); PG8_STAGE(PG8_SB(0, 1), b2 + hstep, voffB); PG8_STAGE(PG8_SA(0, 0), a2, voffA);
;             PG8_WAIT_V(8); PG8_WAIT_L(0); PG8_BAR; PG8_MMA(1, 0, At, B0); PG8_MMA(1, 1, At, B1); PG8_BAR; PG8_SCHED;
.LBB0_606:
	s_ashr_i32 s21, s20, 31
	s_lshl_b64 s[22:23], s[20:21], 19
	s_add_u32 s22, s36, s22
	s_addc_u32 s23, s37, s23
	s_and_b64 s[24:25], s[4:5], exec
	s_cselect_b32 s21, s23, s29
	s_cselect_b32 s55, s22, s28
	s_ashr_i32 s19, s18, 31
	s_lshl_b64 s[24:25], s[18:19], 19
	s_add_u32 s24, s48, s24
	s_addc_u32 s25, s49, s25
	s_and_b64 s[34:35], s[4:5], exec
	s_cselect_b32 s19, s25, s31
	s_cselect_b32 s56, s24, s30
	s_add_u32 s28, s28, 0x40080
	s_addc_u32 s29, s29, 0
	s_add_u32 s57, s30, 0x100
	s_addc_u32 s58, s31, 0
	s_mov_b32 s59, -2
	s_add_u32 s30, s28, 0xfffc0080
	s_addc_u32 s31, s29, -1
	s_cmp_eq_u32 s59, 12
	s_cselect_b32 s35, s21, s31
	s_cselect_b32 s34, s55, s30
	s_cselect_b32 s31, s19, s58
	s_cselect_b32 s30, s56, s57
	v_lshl_add_u64 v[160:161], s[28:29], 0, v[152:153]
	s_add_i32 m0, s38, 0xc000
	s_nop 0
	global_load_lds_dwordx4 v[160:161], off
	v_lshl_add_u64 v[160:161], s[28:29], 0, v[154:155]
	s_add_i32 m0, s38, 0xe000
	s_nop 0
	global_load_lds_dwordx4 v[160:161], off
	s_waitcnt vmcnt(8)
	s_waitcnt lgkmcnt(0)
	s_setprio 1
	s_barrier
	v_mfma_f32_16x16x32_bf16 v[124:127], v[128:131], v[198:201], 0
	v_mfma_f32_16x16x32_bf16 v[120:123], v[174:177], v[198:201], 0
	v_mfma_f32_16x16x32_bf16 v[116:119], v[128:131], v[206:209], 0
	v_mfma_f32_16x16x32_bf16 v[112:115], v[174:177], v[206:209], 0
	v_mfma_f32_16x16x32_bf16 v[108:111], v[128:131], v[214:217], 0
	v_mfma_f32_16x16x32_bf16 v[104:107], v[174:177], v[214:217], 0
	v_mfma_f32_16x16x32_bf16 v[100:103], v[128:131], v[222:225], 0
	v_mfma_f32_16x16x32_bf16 v[96:99], v[174:177], v[222:225], 0
	v_mfma_f32_16x16x32_bf16 v[124:127], v[132:135], v[202:205], v[124:127]
	v_mfma_f32_16x16x32_bf16 v[120:123], v[178:181], v[202:205], v[120:123]
	v_mfma_f32_16x16x32_bf16 v[116:119], v[132:135], v[210:213], v[116:119]
	v_mfma_f32_16x16x32_bf16 v[112:115], v[178:181], v[210:213], v[112:115]
	v_mfma_f32_16x16x32_bf16 v[108:111], v[132:135], v[218:221], v[108:111]
	v_mfma_f32_16x16x32_bf16 v[104:107], v[178:181], v[218:221], v[104:107]
	v_mfma_f32_16x16x32_bf16 v[100:103], v[132:135], v[226:229], v[100:103]
	v_mfma_f32_16x16x32_bf16 v[96:99], v[178:181], v[226:229], v[96:99]
	v_mfma_f32_16x16x32_bf16 v[60:63], v[182:185], v[198:201], 0
	v_mfma_f32_16x16x32_bf16 v[56:59], v[190:193], v[198:201], 0
	v_mfma_f32_16x16x32_bf16 v[52:55], v[182:185], v[206:209], 0
	v_mfma_f32_16x16x32_bf16 v[48:51], v[190:193], v[206:209], 0
	v_mfma_f32_16x16x32_bf16 v[44:47], v[182:185], v[214:217], 0
	v_mfma_f32_16x16x32_bf16 v[40:43], v[190:193], v[214:217], 0
	v_mfma_f32_16x16x32_bf16 v[36:39], v[182:185], v[222:225], 0
	v_mfma_f32_16x16x32_bf16 v[32:35], v[190:193], v[222:225], 0
	v_mfma_f32_16x16x32_bf16 v[60:63], v[186:189], v[202:205], v[60:63]
	v_mfma_f32_16x16x32_bf16 v[56:59], v[194:197], v[202:205], v[56:59]
	v_mfma_f32_16x16x32_bf16 v[52:55], v[186:189], v[210:213], v[52:55]
	v_mfma_f32_16x16x32_bf16 v[48:51], v[194:197], v[210:213], v[48:51]
	v_mfma_f32_16x16x32_bf16 v[44:47], v[186:189], v[218:221], v[44:47]
	v_mfma_f32_16x16x32_bf16 v[40:43], v[194:197], v[218:221], v[40:43]
	v_mfma_f32_16x16x32_bf16 v[36:39], v[186:189], v[226:229], v[36:39]
	s_setprio 0
	v_mfma_f32_16x16x32_bf16 v[32:35], v[194:197], v[226:229], v[32:35]
	s_barrier
	s_add_i32 s60, s45, s33
	v_lshl_add_u64 v[160:161], s[30:31], 0, v[138:139]
	s_mov_b32 m0, s60
	ds_read_b128 v[198:201], v172 offset:16384
	ds_read_b128 v[202:205], v172 offset:17408
	ds_read_b128 v[206:209], v172 offset:18432
	ds_read_b128 v[210:213], v172 offset:19456
	ds_read_b128 v[214:217], v172 offset:20480
	ds_read_b128 v[218:221], v172 offset:21504
	ds_read_b128 v[222:225], v172 offset:22528
	ds_read_b128 v[226:229], v172 offset:23552
	global_load_lds_dwordx4 v[160:161], off
	s_add_i32 m0, s60, 0x2000
	s_add_u32 s60, s30, 0x40000
	v_lshl_add_u64 v[230:231], s[30:31], 0, v[142:143]
	s_addc_u32 s61, s31, 0
	s_add_i32 s62, s50, s33
	global_load_lds_dwordx4 v[230:231], off
	v_lshl_add_u64 v[232:233], s[60:61], 0, v[138:139]
	s_mov_b32 m0, s62
	v_lshl_add_u64 v[234:235], s[34:35], 0, v[140:141]
	global_load_lds_dwordx4 v[232:233], off
	v_lshl_add_u64 v[232:233], s[60:61], 0, v[142:143]
	s_add_i32 m0, s62, 0x2000
	s_nop 0
	global_load_lds_dwordx4 v[232:233], off
	v_lshl_add_u64 v[232:233], s[34:35], 0, v[136:137]
	s_mov_b32 m0, s38
	s_nop 0
	global_load_lds_dwordx4 v[232:233], off
	s_mov_b32 m0, s39
	s_nop 0
	global_load_lds_dwordx4 v[234:235], off
	s_waitcnt vmcnt(8)
	s_waitcnt lgkmcnt(0)
	s_setprio 1
	s_barrier
	v_mfma_f32_16x16x32_bf16 v[92:95], v[128:131], v[198:201], 0
	v_mfma_f32_16x16x32_bf16 v[88:91], v[174:177], v[198:201], 0
	v_mfma_f32_16x16x32_bf16 v[84:87], v[128:131], v[206:209], 0
	v_mfma_f32_16x16x32_bf16 v[80:83], v[174:177], v[206:209], 0
	v_mfma_f32_16x16x32_bf16 v[76:79], v[128:131], v[214:217], 0
	v_mfma_f32_16x16x32_bf16 v[72:75], v[174:177], v[214:217], 0
	v_mfma_f32_16x16x32_bf16 v[68:71], v[128:131], v[222:225], 0
	v_mfma_f32_16x16x32_bf16 v[64:67], v[174:177], v[222:225], 0
	v_mfma_f32_16x16x32_bf16 v[92:95], v[132:135], v[202:205], v[92:95]
	v_mfma_f32_16x16x32_bf16 v[88:91], v[178:181], v[202:205], v[88:91]
	v_mfma_f32_16x16x32_bf16 v[84:87], v[132:135], v[210:213], v[84:87]
	v_mfma_f32_16x16x32_bf16 v[80:83], v[178:181], v[210:213], v[80:83]
	v_mfma_f32_16x16x32_bf16 v[76:79], v[132:135], v[218:221], v[76:79]
	v_mfma_f32_16x16x32_bf16 v[72:75], v[178:181], v[218:221], v[72:75]
	v_mfma_f32_16x16x32_bf16 v[68:71], v[132:135], v[226:229], v[68:71]
	v_mfma_f32_16x16x32_bf16 v[64:67], v[178:181], v[226:229], v[64:67]
	v_mfma_f32_16x16x32_bf16 v[28:31], v[182:185], v[198:201], 0
	v_mfma_f32_16x16x32_bf16 v[24:27], v[190:193], v[198:201], 0
	v_mfma_f32_16x16x32_bf16 v[20:23], v[182:185], v[206:209], 0
	v_mfma_f32_16x16x32_bf16 v[16:19], v[190:193], v[206:209], 0
	v_mfma_f32_16x16x32_bf16 v[12:15], v[182:185], v[214:217], 0
	v_mfma_f32_16x16x32_bf16 v[8:11], v[190:193], v[214:217], 0
	v_mfma_f32_16x16x32_bf16 v[4:7], v[182:185], v[222:225], 0
	v_mfma_f32_16x16x32_bf16 v[0:3], v[190:193], v[222:225], 0
	v_mfma_f32_16x16x32_bf16 v[28:31], v[186:189], v[202:205], v[28:31]
	v_mfma_f32_16x16x32_bf16 v[24:27], v[194:197], v[202:205], v[24:27]
	v_mfma_f32_16x16x32_bf16 v[20:23], v[186:189], v[210:213], v[20:23]
	v_mfma_f32_16x16x32_bf16 v[16:19], v[194:197], v[210:213], v[16:19]
	v_mfma_f32_16x16x32_bf16 v[12:15], v[186:189], v[218:221], v[12:15]
	v_mfma_f32_16x16x32_bf16 v[8:11], v[194:197], v[218:221], v[8:11]
	v_mfma_f32_16x16x32_bf16 v[4:7], v[186:189], v[226:229], v[4:7]
	s_setprio 0
	v_mfma_f32_16x16x32_bf16 v[0:3], v[194:197], v[226:229], v[0:3]
	s_barrier
; #define PG8_STAGE(bufoff, gbase, voff) do { _Pragma("unroll") for (int _i = 0; _i < 2; ++_i) \
;         __builtin_amdgcn_global_load_lds((const unsigned*)((const char*)(gbase) + (voff)[_i]), (PG8_LAS unsigned*)(lds + (bufoff) + ldsw + _i * 8192), 16, 0, 0); } while (0)
; #define PG8_LDA(dst, b, h) do { _Pragma("unroll") for (int m = 0; m < 4; ++m) _Pragma("unroll") for (int k = 0; k < 2; ++k) dst[m][k] = *(const PG8_LAS bf16x8*)(lds + PG8_SA(b, h) + aoff + m * 2048 + k * 1024); } while (0)
; #define PG8_LDB(dst, b, h) do { _Pragma("unroll") for (int n = 0; n < 2; ++n) _Pragma("unroll") for (int k = 0; k < 2; ++k) dst[n][k] = *(const PG8_LAS bf16x8*)(lds + PG8_SB(b, h) + boff + n * 2048 + k * 1024); } while (0)
; #define PG8_MMA(ai, bj, At, Bt) do { __builtin_amdgcn_s_setprio(1); _Pragma("unroll") for (int m = 0; m < 4; ++m) _Pragma("unroll") for (int n = 0; n < 2; ++n) _Pragma("unroll") for (int k = 0; k < 2; ++k) \
;         acc[ai][bj][m][n] = __builtin_amdgcn_mfma_f32_16x16x32_bf16(Bt[n][k], At[m][k], acc[ai][bj][m][n], 0, 0, 0); __builtin_amdgcn_s_setprio(0); } while (0)
; #define PG8_WAIT_V(n) asm volatile("s_waitcnt vmcnt(" #n ")" ::: "memory")
; #define PG8_WAIT_L(n) asm volatile("s_waitcnt lgkmcnt(" #n ")" ::: "memory")
; #define PG8_BAR __builtin_amdgcn_s_barrier()
; #define PG8_SCHED __builtin_amdgcn_sched_barrier(0)
; template <class Epi, class Sched, bool ALIGN_EPI = false, bool SP2 = false>
; __device__ __forceinline__ void gemm_phase(PG8_LAS unsigned char* lds, const Gemm g, const Sched& S, const Epi& E) {
;     ...
;         for (int t = 0; t < nt; t += 2) {
;             const bool last = (t == nt - 2);
;     ...
;             PG8_LDB(B0, 1, 0); PG8_LDB(B1, 1, 1); PG8_SCHED; PG8_LDA(At, 1, 0); PG8_STAGE(PG8_SA(0, 1), a2 + hstep, voffA);
;             PG8_WAIT_V(8); PG8_WAIT_L(0); PG8_BAR; PG8_MMA(0, 0, At, B0); PG8_MMA(0, 1, At, B1); PG8_BAR; PG8_SCHED;
;             PG8_LDA(At, 1, 1); PG8_STAGE(PG8_SB(1, 0), b3, voffB); PG8_STAGE(PG8_SB(1, 1), b3 + hstep, voffB); PG8_STAGE(PG8_SA(1, 0), a3, voffA);
;             PG8_WAIT_V(8); PG8_WAIT_L(0); PG8_BAR; PG8_MMA(1, 0, At, B0); PG8_MMA(1, 1, At, B1); PG8_BAR; PG8_SCHED;
	s_add_i32 s60, 0, 0x18000
	s_add_i32 s61, 0, 0x1c000
	v_add_u32_e32 v178, s60, v163
	v_add_u32_e32 v194, s61, v163
	ds_read_b128 v[128:131], v178
	ds_read_b128 v[132:135], v178 offset:1024
	ds_read_b128 v[174:177], v178 offset:2048
	ds_read_b128 v[178:181], v178 offset:3072
	ds_read_b128 v[182:185], v194
	ds_read_b128 v[186:189], v194 offset:1024
	ds_read_b128 v[190:193], v194 offset:2048
	ds_read_b128 v[194:197], v194 offset:3072
	s_add_u32 s34, s34, 0x40000
	s_addc_u32 s35, s35, 0
	s_mov_b32 m0, s40
	v_lshl_add_u64 v[236:237], s[34:35], 0, v[136:137]
	ds_read_b128 v[198:201], v172 offset:32768
	ds_read_b128 v[202:205], v172 offset:33792
	ds_read_b128 v[206:209], v172 offset:34816
	ds_read_b128 v[210:213], v172 offset:35840
	ds_read_b128 v[214:217], v172 offset:36864
	ds_read_b128 v[218:221], v172 offset:37888
	ds_read_b128 v[222:225], v172 offset:38912
	ds_read_b128 v[226:229], v172 offset:39936
	global_load_lds_dwordx4 v[236:237], off
	v_lshl_add_u64 v[236:237], s[34:35], 0, v[140:141]
	s_mov_b32 m0, s41
	s_nop 0
	global_load_lds_dwordx4 v[236:237], off
	s_waitcnt vmcnt(8)
	s_waitcnt lgkmcnt(0)
	s_setprio 1
	s_barrier
	v_mfma_f32_16x16x32_bf16 v[124:127], v[128:131], v[198:201], v[124:127]
	v_mfma_f32_16x16x32_bf16 v[120:123], v[174:177], v[198:201], v[120:123]
	v_mfma_f32_16x16x32_bf16 v[116:119], v[128:131], v[206:209], v[116:119]
	v_mfma_f32_16x16x32_bf16 v[112:115], v[174:177], v[206:209], v[112:115]
	v_mfma_f32_16x16x32_bf16 v[108:111], v[128:131], v[214:217], v[108:111]
	v_mfma_f32_16x16x32_bf16 v[104:107], v[174:177], v[214:217], v[104:107]
	v_mfma_f32_16x16x32_bf16 v[100:103], v[128:131], v[222:225], v[100:103]
	v_mfma_f32_16x16x32_bf16 v[96:99], v[174:177], v[222:225], v[96:99]
	v_mfma_f32_16x16x32_bf16 v[124:127], v[132:135], v[202:205], v[124:127]
	v_mfma_f32_16x16x32_bf16 v[120:123], v[178:181], v[202:205], v[120:123]
	v_mfma_f32_16x16x32_bf16 v[116:119], v[132:135], v[210:213], v[116:119]
	v_mfma_f32_16x16x32_bf16 v[112:115], v[178:181], v[210:213], v[112:115]
	v_mfma_f32_16x16x32_bf16 v[108:111], v[132:135], v[218:221], v[108:111]
	v_mfma_f32_16x16x32_bf16 v[104:107], v[178:181], v[218:221], v[104:107]
	v_mfma_f32_16x16x32_bf16 v[100:103], v[132:135], v[226:229], v[100:103]
	v_mfma_f32_16x16x32_bf16 v[96:99], v[178:181], v[226:229], v[96:99]
	v_mfma_f32_16x16x32_bf16 v[60:63], v[182:185], v[198:201], v[60:63]
	v_mfma_f32_16x16x32_bf16 v[56:59], v[190:193], v[198:201], v[56:59]
	v_mfma_f32_16x16x32_bf16 v[52:55], v[182:185], v[206:209], v[52:55]
	v_mfma_f32_16x16x32_bf16 v[48:51], v[190:193], v[206:209], v[48:51]
	v_mfma_f32_16x16x32_bf16 v[44:47], v[182:185], v[214:217], v[44:47]
	v_mfma_f32_16x16x32_bf16 v[40:43], v[190:193], v[214:217], v[40:43]
	v_mfma_f32_16x16x32_bf16 v[36:39], v[182:185], v[222:225], v[36:39]
	v_mfma_f32_16x16x32_bf16 v[32:35], v[190:193], v[222:225], v[32:35]
	v_mfma_f32_16x16x32_bf16 v[60:63], v[186:189], v[202:205], v[60:63]
	v_mfma_f32_16x16x32_bf16 v[56:59], v[194:197], v[202:205], v[56:59]
	v_mfma_f32_16x16x32_bf16 v[52:55], v[186:189], v[210:213], v[52:55]
	v_mfma_f32_16x16x32_bf16 v[48:51], v[194:197], v[210:213], v[48:51]
	v_mfma_f32_16x16x32_bf16 v[44:47], v[186:189], v[218:221], v[44:47]
	v_mfma_f32_16x16x32_bf16 v[40:43], v[194:197], v[218:221], v[40:43]
	v_mfma_f32_16x16x32_bf16 v[36:39], v[186:189], v[226:229], v[36:39]
	s_setprio 0
	v_mfma_f32_16x16x32_bf16 v[32:35], v[194:197], v[226:229], v[32:35]
	s_barrier
	s_add_i32 s34, s60, s33
	v_lshl_add_u64 v[160:161], v[160:161], 0, s[16:17]
	s_mov_b32 m0, s34
	ds_read_b128 v[198:201], v172 offset:49152
	ds_read_b128 v[202:205], v172 offset:50176
	ds_read_b128 v[206:209], v172 offset:51200
	ds_read_b128 v[210:213], v172 offset:52224
	ds_read_b128 v[214:217], v172 offset:53248
	ds_read_b128 v[218:221], v172 offset:54272
	ds_read_b128 v[222:225], v172 offset:55296
	ds_read_b128 v[226:229], v172 offset:56320
	global_load_lds_dwordx4 v[160:161], off
	s_add_i32 m0, s34, 0x2000
	s_add_u32 s30, s30, 0x40080
	v_lshl_add_u64 v[160:161], v[230:231], 0, s[16:17]
	s_addc_u32 s31, s31, 0
	s_add_i32 s34, s61, s33
	global_load_lds_dwordx4 v[160:161], off
	v_lshl_add_u64 v[160:161], s[30:31], 0, v[138:139]
	s_mov_b32 m0, s34
	s_nop 0
	global_load_lds_dwordx4 v[160:161], off
	v_lshl_add_u64 v[160:161], s[30:31], 0, v[142:143]
	s_add_i32 m0, s34, 0x2000
	s_nop 0
	global_load_lds_dwordx4 v[160:161], off
	v_lshl_add_u64 v[160:161], v[232:233], 0, s[16:17]
	s_mov_b32 m0, s42
	s_nop 0
	global_load_lds_dwordx4 v[160:161], off
	v_lshl_add_u64 v[160:161], v[234:235], 0, s[16:17]
	s_mov_b32 m0, s43
	s_nop 0
	global_load_lds_dwordx4 v[160:161], off
	s_waitcnt vmcnt(8)
	s_waitcnt lgkmcnt(0)
	s_setprio 1
	s_barrier
	v_mfma_f32_16x16x32_bf16 v[92:95], v[128:131], v[198:201], v[92:95]
	v_mfma_f32_16x16x32_bf16 v[88:91], v[174:177], v[198:201], v[88:91]
	v_mfma_f32_16x16x32_bf16 v[84:87], v[128:131], v[206:209], v[84:87]
	v_mfma_f32_16x16x32_bf16 v[80:83], v[174:177], v[206:209], v[80:83]
	v_mfma_f32_16x16x32_bf16 v[76:79], v[128:131], v[214:217], v[76:79]
	v_mfma_f32_16x16x32_bf16 v[72:75], v[174:177], v[214:217], v[72:75]
	v_mfma_f32_16x16x32_bf16 v[68:71], v[128:131], v[222:225], v[68:71]
	v_mfma_f32_16x16x32_bf16 v[64:67], v[174:177], v[222:225], v[64:67]
	v_mfma_f32_16x16x32_bf16 v[92:95], v[132:135], v[202:205], v[92:95]
	v_mfma_f32_16x16x32_bf16 v[88:91], v[178:181], v[202:205], v[88:91]
	v_mfma_f32_16x16x32_bf16 v[84:87], v[132:135], v[210:213], v[84:87]
	v_mfma_f32_16x16x32_bf16 v[80:83], v[178:181], v[210:213], v[80:83]
	v_mfma_f32_16x16x32_bf16 v[76:79], v[132:135], v[218:221], v[76:79]
	v_mfma_f32_16x16x32_bf16 v[72:75], v[178:181], v[218:221], v[72:75]
	v_mfma_f32_16x16x32_bf16 v[68:71], v[132:135], v[226:229], v[68:71]
	v_mfma_f32_16x16x32_bf16 v[64:67], v[178:181], v[226:229], v[64:67]
	v_mfma_f32_16x16x32_bf16 v[28:31], v[182:185], v[198:201], v[28:31]
	v_mfma_f32_16x16x32_bf16 v[24:27], v[190:193], v[198:201], v[24:27]
	v_mfma_f32_16x16x32_bf16 v[20:23], v[182:185], v[206:209], v[20:23]
	v_mfma_f32_16x16x32_bf16 v[16:19], v[190:193], v[206:209], v[16:19]
	v_mfma_f32_16x16x32_bf16 v[12:15], v[182:185], v[214:217], v[12:15]
	v_mfma_f32_16x16x32_bf16 v[8:11], v[190:193], v[214:217], v[8:11]
	v_mfma_f32_16x16x32_bf16 v[4:7], v[182:185], v[222:225], v[4:7]
	v_mfma_f32_16x16x32_bf16 v[0:3], v[190:193], v[222:225], v[0:3]
	v_mfma_f32_16x16x32_bf16 v[28:31], v[186:189], v[202:205], v[28:31]
	v_mfma_f32_16x16x32_bf16 v[24:27], v[194:197], v[202:205], v[24:27]
	v_mfma_f32_16x16x32_bf16 v[20:23], v[186:189], v[210:213], v[20:23]
	v_mfma_f32_16x16x32_bf16 v[16:19], v[194:197], v[210:213], v[16:19]
	v_mfma_f32_16x16x32_bf16 v[12:15], v[186:189], v[218:221], v[12:15]
	v_mfma_f32_16x16x32_bf16 v[8:11], v[194:197], v[218:221], v[8:11]
	v_mfma_f32_16x16x32_bf16 v[4:7], v[186:189], v[226:229], v[4:7]
	s_setprio 0
	v_mfma_f32_16x16x32_bf16 v[0:3], v[194:197], v[226:229], v[0:3]
	s_barrier
	s_add_i32 s59, s59, 2
	s_add_u32 s28, s28, 0x100
	s_addc_u32 s29, s29, 0
	s_add_u32 s57, s57, 0x100
	s_addc_u32 s58, s58, 0
	s_cmp_gt_u32 s59, 13
; #define PG8_STAGE(bufoff, gbase, voff) do { _Pragma("unroll") for (int _i = 0; _i < 2; ++_i) \
;         __builtin_amdgcn_global_load_lds((const unsigned*)((const char*)(gbase) + (voff)[_i]), (PG8_LAS unsigned*)(lds + (bufoff) + ldsw + _i * 8192), 16, 0, 0); } while (0)
; #define PG8_LDA(dst, b, h) do { _Pragma("unroll") for (int m = 0; m < 4; ++m) _Pragma("unroll") for (int k = 0; k < 2; ++k) dst[m][k] = *(const PG8_LAS bf16x8*)(lds + PG8_SA(b, h) + aoff + m * 2048 + k * 1024); } while (0)
; #define PG8_LDB(dst, b, h) do { _Pragma("unroll") for (int n = 0; n < 2; ++n) _Pragma("unroll") for (int k = 0; k < 2; ++k) dst[n][k] = *(const PG8_LAS bf16x8*)(lds + PG8_SB(b, h) + boff + n * 2048 + k * 1024); } while (0)
; #define PG8_MMA(ai, bj, At, Bt) do { __builtin_amdgcn_s_setprio(1); _Pragma("unroll") for (int m = 0; m < 4; ++m) _Pragma("unroll") for (int n = 0; n < 2; ++n) _Pragma("unroll") for (int k = 0; k < 2; ++k) \
;         acc[ai][bj][m][n] = __builtin_amdgcn_mfma_f32_16x16x32_bf16(Bt[n][k], At[m][k], acc[ai][bj][m][n], 0, 0, 0); __builtin_amdgcn_s_setprio(0); } while (0)
; #define PG8_WAIT_V(n) asm volatile("s_waitcnt vmcnt(" #n ")" ::: "memory")
; #define PG8_WAIT_L(n) asm volatile("s_waitcnt lgkmcnt(" #n ")" ::: "memory")
; #define PG8_BAR __builtin_amdgcn_s_barrier()
; #define PG8_SCHED __builtin_amdgcn_sched_barrier(0)
; template <class Epi, class Sched, bool ALIGN_EPI = false, bool SP2 = false>
; __device__ __forceinline__ void gemm_phase(PG8_LAS unsigned char* lds, const Gemm g, const Sched& S, const Epi& E) {
;     ...
;             PG8_LDB(B0, 0, 0); PG8_LDB(B1, 0, 1); PG8_SCHED; PG8_LDA(At, 0, 0); PG8_STAGE(PG8_SA(1, 1), a1 + hstep, voffA);
;             PG8_WAIT_V(8); PG8_WAIT_L(0); PG8_BAR; PG8_MMA(0, 0, At, B0); PG8_MMA(0, 1, At, B1); PG8_BAR; PG8_SCHED;
;             PG8_LDA(At, 0, 1); PG8_STAGE(PG8_SB(0, 0), b2, voffB); PG8_STAGE(PG8_SB(0, 1), b2 + hstep, voffB); PG8_STAGE(PG8_SA(0, 0), a2, voffA);
;             PG8_WAIT_V(8); PG8_WAIT_L(0); PG8_BAR; PG8_MMA(1, 0, At, B0); PG8_MMA(1, 1, At, B1); PG8_BAR; PG8_SCHED;
.LBB0_607:
	ds_read_b128 v[128:131], v170
	ds_read_b128 v[132:135], v170 offset:1024
	ds_read_b128 v[174:177], v170 offset:2048
	ds_read_b128 v[178:181], v170 offset:3072
	ds_read_b128 v[182:185], v171
	ds_read_b128 v[186:189], v171 offset:1024
	ds_read_b128 v[190:193], v171 offset:2048
	ds_read_b128 v[194:197], v171 offset:3072
	s_add_u32 s30, s28, 0xfffc0080
	s_addc_u32 s31, s29, -1
	s_cmp_eq_u32 s59, 12
	s_cselect_b32 s35, s21, s31
	s_cselect_b32 s34, s55, s30
	s_cselect_b32 s31, s19, s58
	s_cselect_b32 s30, s56, s57
	v_lshl_add_u64 v[160:161], s[28:29], 0, v[152:153]
	s_add_i32 m0, s38, 0xc000
	ds_read_b128 v[198:201], v172
	ds_read_b128 v[202:205], v172 offset:1024
	ds_read_b128 v[206:209], v172 offset:2048
	ds_read_b128 v[210:213], v172 offset:3072
	ds_read_b128 v[214:217], v172 offset:4096
	ds_read_b128 v[218:221], v172 offset:5120
	ds_read_b128 v[222:225], v172 offset:6144
	ds_read_b128 v[226:229], v172 offset:7168
	global_load_lds_dwordx4 v[160:161], off
	v_lshl_add_u64 v[160:161], s[28:29], 0, v[154:155]
	s_add_i32 m0, s38, 0xe000
	s_nop 0
	global_load_lds_dwordx4 v[160:161], off
	s_waitcnt vmcnt(8)
	s_waitcnt lgkmcnt(0)
	s_setprio 1
	s_barrier
	v_mfma_f32_16x16x32_bf16 v[124:127], v[128:131], v[198:201], v[124:127]
	v_mfma_f32_16x16x32_bf16 v[120:123], v[174:177], v[198:201], v[120:123]
	v_mfma_f32_16x16x32_bf16 v[116:119], v[128:131], v[206:209], v[116:119]
	v_mfma_f32_16x16x32_bf16 v[112:115], v[174:177], v[206:209], v[112:115]
	v_mfma_f32_16x16x32_bf16 v[108:111], v[128:131], v[214:217], v[108:111]
	v_mfma_f32_16x16x32_bf16 v[104:107], v[174:177], v[214:217], v[104:107]
	v_mfma_f32_16x16x32_bf16 v[100:103], v[128:131], v[222:225], v[100:103]
	v_mfma_f32_16x16x32_bf16 v[96:99], v[174:177], v[222:225], v[96:99]
	v_mfma_f32_16x16x32_bf16 v[124:127], v[132:135], v[202:205], v[124:127]
	v_mfma_f32_16x16x32_bf16 v[120:123], v[178:181], v[202:205], v[120:123]
	v_mfma_f32_16x16x32_bf16 v[116:119], v[132:135], v[210:213], v[116:119]
	v_mfma_f32_16x16x32_bf16 v[112:115], v[178:181], v[210:213], v[112:115]
	v_mfma_f32_16x16x32_bf16 v[108:111], v[132:135], v[218:221], v[108:111]
	v_mfma_f32_16x16x32_bf16 v[104:107], v[178:181], v[218:221], v[104:107]
	v_mfma_f32_16x16x32_bf16 v[100:103], v[132:135], v[226:229], v[100:103]
	v_mfma_f32_16x16x32_bf16 v[96:99], v[178:181], v[226:229], v[96:99]
	v_mfma_f32_16x16x32_bf16 v[60:63], v[182:185], v[198:201], v[60:63]
	v_mfma_f32_16x16x32_bf16 v[56:59], v[190:193], v[198:201], v[56:59]
	v_mfma_f32_16x16x32_bf16 v[52:55], v[182:185], v[206:209], v[52:55]
	v_mfma_f32_16x16x32_bf16 v[48:51], v[190:193], v[206:209], v[48:51]
	v_mfma_f32_16x16x32_bf16 v[44:47], v[182:185], v[214:217], v[44:47]
	v_mfma_f32_16x16x32_bf16 v[40:43], v[190:193], v[214:217], v[40:43]
	v_mfma_f32_16x16x32_bf16 v[36:39], v[182:185], v[222:225], v[36:39]
	v_mfma_f32_16x16x32_bf16 v[32:35], v[190:193], v[222:225], v[32:35]
	v_mfma_f32_16x16x32_bf16 v[60:63], v[186:189], v[202:205], v[60:63]
	v_mfma_f32_16x16x32_bf16 v[56:59], v[194:197], v[202:205], v[56:59]
	v_mfma_f32_16x16x32_bf16 v[52:55], v[186:189], v[210:213], v[52:55]
	v_mfma_f32_16x16x32_bf16 v[48:51], v[194:197], v[210:213], v[48:51]
	v_mfma_f32_16x16x32_bf16 v[44:47], v[186:189], v[218:221], v[44:47]
	v_mfma_f32_16x16x32_bf16 v[40:43], v[194:197], v[218:221], v[40:43]
	v_mfma_f32_16x16x32_bf16 v[36:39], v[186:189], v[226:229], v[36:39]
	s_setprio 0
	v_mfma_f32_16x16x32_bf16 v[32:35], v[194:197], v[226:229], v[32:35]
	s_barrier
	s_add_i32 s60, s45, s33
	v_lshl_add_u64 v[160:161], s[30:31], 0, v[138:139]
	s_mov_b32 m0, s60
	ds_read_b128 v[198:201], v172 offset:16384
	ds_read_b128 v[202:205], v172 offset:17408
	ds_read_b128 v[206:209], v172 offset:18432
	ds_read_b128 v[210:213], v172 offset:19456
	ds_read_b128 v[214:217], v172 offset:20480
	ds_read_b128 v[218:221], v172 offset:21504
	ds_read_b128 v[222:225], v172 offset:22528
	ds_read_b128 v[226:229], v172 offset:23552
	global_load_lds_dwordx4 v[160:161], off
	s_add_i32 m0, s60, 0x2000
	s_add_u32 s60, s30, 0x40000
	v_lshl_add_u64 v[230:231], s[30:31], 0, v[142:143]
	s_addc_u32 s61, s31, 0
	s_add_i32 s62, s50, s33
	global_load_lds_dwordx4 v[230:231], off
	v_lshl_add_u64 v[232:233], s[60:61], 0, v[138:139]
	s_mov_b32 m0, s62
	v_lshl_add_u64 v[234:235], s[34:35], 0, v[140:141]
	global_load_lds_dwordx4 v[232:233], off
	v_lshl_add_u64 v[232:233], s[60:61], 0, v[142:143]
	s_add_i32 m0, s62, 0x2000
	s_nop 0
	global_load_lds_dwordx4 v[232:233], off
	v_lshl_add_u64 v[232:233], s[34:35], 0, v[136:137]
	s_mov_b32 m0, s38
	s_nop 0
	global_load_lds_dwordx4 v[232:233], off
	s_mov_b32 m0, s39
	s_nop 0
	global_load_lds_dwordx4 v[234:235], off
	s_waitcnt vmcnt(8)
	s_waitcnt lgkmcnt(0)
	s_setprio 1
	s_barrier
; #define PG8_STAGE(bufoff, gbase, voff) do { _Pragma("unroll") for (int _i = 0; _i < 2; ++_i) \
;         __builtin_amdgcn_global_load_lds((const unsigned*)((const char*)(gbase) + (voff)[_i]), (PG8_LAS unsigned*)(lds + (bufoff) + ldsw + _i * 8192), 16, 0, 0); } while (0)
; #define PG8_LDA(dst, b, h) do { _Pragma("unroll") for (int m = 0; m < 4; ++m) _Pragma("unroll") for (int k = 0; k < 2; ++k) dst[m][k] = *(const PG8_LAS bf16x8*)(lds + PG8_SA(b, h) + aoff + m * 2048 + k * 1024); } while (0)
; #define PG8_LDB(dst, b, h) do { _Pragma("unroll") for (int n = 0; n < 2; ++n) _Pragma("unroll") for (int k = 0; k < 2; ++k) dst[n][k] = *(const PG8_LAS bf16x8*)(lds + PG8_SB(b, h) + boff + n * 2048 + k * 1024); } while (0)
; #define PG8_MMA(ai, bj, At, Bt) do { __builtin_amdgcn_s_setprio(1); _Pragma("unroll") for (int m = 0; m < 4; ++m) _Pragma("unroll") for (int n = 0; n < 2; ++n) _Pragma("unroll") for (int k = 0; k < 2; ++k) \
;         acc[ai][bj][m][n] = __builtin_amdgcn_mfma_f32_16x16x32_bf16(Bt[n][k], At[m][k], acc[ai][bj][m][n], 0, 0, 0); __builtin_amdgcn_s_setprio(0); } while (0)
; #define PG8_WAIT_V(n) asm volatile("s_waitcnt vmcnt(" #n ")" ::: "memory")
; #define PG8_WAIT_L(n) asm volatile("s_waitcnt lgkmcnt(" #n ")" ::: "memory")
; #define PG8_BAR __builtin_amdgcn_s_barrier()
; #define PG8_SCHED __builtin_amdgcn_sched_barrier(0)
; template <class Epi, class Sched, bool ALIGN_EPI = false, bool SP2 = false>
; __device__ __forceinline__ void gemm_phase(PG8_LAS unsigned char* lds, const Gemm g, const Sched& S, const Epi& E) {
;     ...
;             PG8_WAIT_V(8); PG8_WAIT_L(0); PG8_BAR; PG8_MMA(0, 0, At, B0); PG8_MMA(0, 1, At, B1); PG8_BAR; PG8_SCHED;
;             PG8_LDA(At, 0, 1); PG8_STAGE(PG8_SB(0, 0), b2, voffB); PG8_STAGE(PG8_SB(0, 1), b2 + hstep, voffB); PG8_STAGE(PG8_SA(0, 0), a2, voffA);
;             PG8_WAIT_V(8); PG8_WAIT_L(0); PG8_BAR; PG8_MMA(1, 0, At, B0); PG8_MMA(1, 1, At, B1); PG8_BAR; PG8_SCHED;
;             PG8_LDB(B0, 1, 0); PG8_LDB(B1, 1, 1); PG8_SCHED; PG8_LDA(At, 1, 0); PG8_STAGE(PG8_SA(0, 1), a2 + hstep, voffA);
;             PG8_WAIT_V(8); PG8_WAIT_L(0); PG8_BAR; PG8_MMA(0, 0, At, B0); PG8_MMA(0, 1, At, B1); PG8_BAR; PG8_SCHED;
	v_mfma_f32_16x16x32_bf16 v[92:95], v[128:131], v[198:201], v[92:95]
	v_mfma_f32_16x16x32_bf16 v[88:91], v[174:177], v[198:201], v[88:91]
	v_mfma_f32_16x16x32_bf16 v[84:87], v[128:131], v[206:209], v[84:87]
	v_mfma_f32_16x16x32_bf16 v[80:83], v[174:177], v[206:209], v[80:83]
	v_mfma_f32_16x16x32_bf16 v[76:79], v[128:131], v[214:217], v[76:79]
	v_mfma_f32_16x16x32_bf16 v[72:75], v[174:177], v[214:217], v[72:75]
	v_mfma_f32_16x16x32_bf16 v[68:71], v[128:131], v[222:225], v[68:71]
	v_mfma_f32_16x16x32_bf16 v[64:67], v[174:177], v[222:225], v[64:67]
	v_mfma_f32_16x16x32_bf16 v[92:95], v[132:135], v[202:205], v[92:95]
	v_mfma_f32_16x16x32_bf16 v[88:91], v[178:181], v[202:205], v[88:91]
	v_mfma_f32_16x16x32_bf16 v[84:87], v[132:135], v[210:213], v[84:87]
	v_mfma_f32_16x16x32_bf16 v[80:83], v[178:181], v[210:213], v[80:83]
	v_mfma_f32_16x16x32_bf16 v[76:79], v[132:135], v[218:221], v[76:79]
	v_mfma_f32_16x16x32_bf16 v[72:75], v[178:181], v[218:221], v[72:75]
	v_mfma_f32_16x16x32_bf16 v[68:71], v[132:135], v[226:229], v[68:71]
	v_mfma_f32_16x16x32_bf16 v[64:67], v[178:181], v[226:229], v[64:67]
	v_mfma_f32_16x16x32_bf16 v[28:31], v[182:185], v[198:201], v[28:31]
	v_mfma_f32_16x16x32_bf16 v[24:27], v[190:193], v[198:201], v[24:27]
	v_mfma_f32_16x16x32_bf16 v[20:23], v[182:185], v[206:209], v[20:23]
	v_mfma_f32_16x16x32_bf16 v[16:19], v[190:193], v[206:209], v[16:19]
	v_mfma_f32_16x16x32_bf16 v[12:15], v[182:185], v[214:217], v[12:15]
	v_mfma_f32_16x16x32_bf16 v[8:11], v[190:193], v[214:217], v[8:11]
	v_mfma_f32_16x16x32_bf16 v[4:7], v[182:185], v[222:225], v[4:7]
	v_mfma_f32_16x16x32_bf16 v[0:3], v[190:193], v[222:225], v[0:3]
	v_mfma_f32_16x16x32_bf16 v[28:31], v[186:189], v[202:205], v[28:31]
	v_mfma_f32_16x16x32_bf16 v[24:27], v[194:197], v[202:205], v[24:27]
	v_mfma_f32_16x16x32_bf16 v[20:23], v[186:189], v[210:213], v[20:23]
	v_mfma_f32_16x16x32_bf16 v[16:19], v[194:197], v[210:213], v[16:19]
	v_mfma_f32_16x16x32_bf16 v[12:15], v[186:189], v[218:221], v[12:15]
	v_mfma_f32_16x16x32_bf16 v[8:11], v[194:197], v[218:221], v[8:11]
	v_mfma_f32_16x16x32_bf16 v[4:7], v[186:189], v[226:229], v[4:7]
	s_setprio 0
	v_mfma_f32_16x16x32_bf16 v[0:3], v[194:197], v[226:229], v[0:3]
	s_barrier
	s_add_i32 s60, 0, 0x18000
	s_add_i32 s61, 0, 0x1c000
	v_add_u32_e32 v178, s60, v163
	v_add_u32_e32 v194, s61, v163
	ds_read_b128 v[128:131], v178
	ds_read_b128 v[132:135], v178 offset:1024
	ds_read_b128 v[174:177], v178 offset:2048
	ds_read_b128 v[178:181], v178 offset:3072
	ds_read_b128 v[182:185], v194
	ds_read_b128 v[186:189], v194 offset:1024
	ds_read_b128 v[190:193], v194 offset:2048
	ds_read_b128 v[194:197], v194 offset:3072
	s_add_u32 s34, s34, 0x40000
	s_addc_u32 s35, s35, 0
	s_mov_b32 m0, s40
	v_lshl_add_u64 v[236:237], s[34:35], 0, v[136:137]
	ds_read_b128 v[198:201], v172 offset:32768
	ds_read_b128 v[202:205], v172 offset:33792
	ds_read_b128 v[206:209], v172 offset:34816
	ds_read_b128 v[210:213], v172 offset:35840
	ds_read_b128 v[214:217], v172 offset:36864
	ds_read_b128 v[218:221], v172 offset:37888
	ds_read_b128 v[222:225], v172 offset:38912
	ds_read_b128 v[226:229], v172 offset:39936
	global_load_lds_dwordx4 v[236:237], off
	v_lshl_add_u64 v[236:237], s[34:35], 0, v[140:141]
	s_mov_b32 m0, s41
	s_nop 0
	global_load_lds_dwordx4 v[236:237], off
	s_waitcnt vmcnt(8)
	s_waitcnt lgkmcnt(0)
	s_setprio 1
	s_barrier
	v_mfma_f32_16x16x32_bf16 v[124:127], v[128:131], v[198:201], v[124:127]
	v_mfma_f32_16x16x32_bf16 v[120:123], v[174:177], v[198:201], v[120:123]
	v_mfma_f32_16x16x32_bf16 v[116:119], v[128:131], v[206:209], v[116:119]
	v_mfma_f32_16x16x32_bf16 v[112:115], v[174:177], v[206:209], v[112:115]
	v_mfma_f32_16x16x32_bf16 v[108:111], v[128:131], v[214:217], v[108:111]
	v_mfma_f32_16x16x32_bf16 v[104:107], v[174:177], v[214:217], v[104:107]
	v_mfma_f32_16x16x32_bf16 v[100:103], v[128:131], v[222:225], v[100:103]
	v_mfma_f32_16x16x32_bf16 v[96:99], v[174:177], v[222:225], v[96:99]
	v_mfma_f32_16x16x32_bf16 v[124:127], v[132:135], v[202:205], v[124:127]
	v_mfma_f32_16x16x32_bf16 v[120:123], v[178:181], v[202:205], v[120:123]
	v_mfma_f32_16x16x32_bf16 v[116:119], v[132:135], v[210:213], v[116:119]
	v_mfma_f32_16x16x32_bf16 v[112:115], v[178:181], v[210:213], v[112:115]
	v_mfma_f32_16x16x32_bf16 v[108:111], v[132:135], v[218:221], v[108:111]
	v_mfma_f32_16x16x32_bf16 v[104:107], v[178:181], v[218:221], v[104:107]
	v_mfma_f32_16x16x32_bf16 v[100:103], v[132:135], v[226:229], v[100:103]
	v_mfma_f32_16x16x32_bf16 v[96:99], v[178:181], v[226:229], v[96:99]
	v_mfma_f32_16x16x32_bf16 v[60:63], v[182:185], v[198:201], v[60:63]
	v_mfma_f32_16x16x32_bf16 v[56:59], v[190:193], v[198:201], v[56:59]
	v_mfma_f32_16x16x32_bf16 v[52:55], v[182:185], v[206:209], v[52:55]
	v_mfma_f32_16x16x32_bf16 v[48:51], v[190:193], v[206:209], v[48:51]
	v_mfma_f32_16x16x32_bf16 v[44:47], v[182:185], v[214:217], v[44:47]
	v_mfma_f32_16x16x32_bf16 v[40:43], v[190:193], v[214:217], v[40:43]
	v_mfma_f32_16x16x32_bf16 v[36:39], v[182:185], v[222:225], v[36:39]
	v_mfma_f32_16x16x32_bf16 v[32:35], v[190:193], v[222:225], v[32:35]
	v_mfma_f32_16x16x32_bf16 v[60:63], v[186:189], v[202:205], v[60:63]
	v_mfma_f32_16x16x32_bf16 v[56:59], v[194:197], v[202:205], v[56:59]
	v_mfma_f32_16x16x32_bf16 v[52:55], v[186:189], v[210:213], v[52:55]
	v_mfma_f32_16x16x32_bf16 v[48:51], v[194:197], v[210:213], v[48:51]
	v_mfma_f32_16x16x32_bf16 v[44:47], v[186:189], v[218:221], v[44:47]
	v_mfma_f32_16x16x32_bf16 v[40:43], v[194:197], v[218:221], v[40:43]
	v_mfma_f32_16x16x32_bf16 v[36:39], v[186:189], v[226:229], v[36:39]
	s_setprio 0
	v_mfma_f32_16x16x32_bf16 v[32:35], v[194:197], v[226:229], v[32:35]
	s_barrier
; #define PG8_STAGE(bufoff, gbase, voff) do { _Pragma("unroll") for (int _i = 0; _i < 2; ++_i) \
;         __builtin_amdgcn_global_load_lds((const unsigned*)((const char*)(gbase) + (voff)[_i]), (PG8_LAS unsigned*)(lds + (bufoff) + ldsw + _i * 8192), 16, 0, 0); } while (0)
; #define PG8_LDA(dst, b, h) do { _Pragma("unroll") for (int m = 0; m < 4; ++m) _Pragma("unroll") for (int k = 0; k < 2; ++k) dst[m][k] = *(const PG8_LAS bf16x8*)(lds + PG8_SA(b, h) + aoff + m * 2048 + k * 1024); } while (0)
; #define PG8_MMA(ai, bj, At, Bt) do { __builtin_amdgcn_s_setprio(1); _Pragma("unroll") for (int m = 0; m < 4; ++m) _Pragma("unroll") for (int n = 0; n < 2; ++n) _Pragma("unroll") for (int k = 0; k < 2; ++k) \
;         acc[ai][bj][m][n] = __builtin_amdgcn_mfma_f32_16x16x32_bf16(Bt[n][k], At[m][k], acc[ai][bj][m][n], 0, 0, 0); __builtin_amdgcn_s_setprio(0); } while (0)
; #define PG8_WAIT_V(n) asm volatile("s_waitcnt vmcnt(" #n ")" ::: "memory")
; #define PG8_WAIT_L(n) asm volatile("s_waitcnt lgkmcnt(" #n ")" ::: "memory")
; #define PG8_BAR __builtin_amdgcn_s_barrier()
; #define PG8_SCHED __builtin_amdgcn_sched_barrier(0)
; template <class Epi, class Sched, bool ALIGN_EPI = false, bool SP2 = false>
; __device__ __forceinline__ void gemm_phase(PG8_LAS unsigned char* lds, const Gemm g, const Sched& S, const Epi& E) {
;     ...
;             PG8_LDA(At, 1, 1); PG8_STAGE(PG8_SB(1, 0), b3, voffB); PG8_STAGE(PG8_SB(1, 1), b3 + hstep, voffB); PG8_STAGE(PG8_SA(1, 0), a3, voffA);
;             PG8_WAIT_V(8); PG8_WAIT_L(0); PG8_BAR; PG8_MMA(1, 0, At, B0); PG8_MMA(1, 1, At, B1); PG8_BAR; PG8_SCHED;
;     ...
;         if constexpr (ALIGN_EPI) { if (wr == 0) PG8_BAR; }
	s_add_i32 s34, s60, s33
	v_lshl_add_u64 v[160:161], v[160:161], 0, s[16:17]
	s_mov_b32 m0, s34
	ds_read_b128 v[198:201], v172 offset:49152
	ds_read_b128 v[202:205], v172 offset:50176
	ds_read_b128 v[206:209], v172 offset:51200
	ds_read_b128 v[210:213], v172 offset:52224
	ds_read_b128 v[214:217], v172 offset:53248
	ds_read_b128 v[218:221], v172 offset:54272
	ds_read_b128 v[222:225], v172 offset:55296
	ds_read_b128 v[226:229], v172 offset:56320
	global_load_lds_dwordx4 v[160:161], off
	s_add_i32 m0, s34, 0x2000
	s_add_u32 s30, s30, 0x40080
	v_lshl_add_u64 v[160:161], v[230:231], 0, s[16:17]
	s_addc_u32 s31, s31, 0
	s_add_i32 s34, s61, s33
	global_load_lds_dwordx4 v[160:161], off
	v_lshl_add_u64 v[160:161], s[30:31], 0, v[138:139]
	s_mov_b32 m0, s34
	s_nop 0
	global_load_lds_dwordx4 v[160:161], off
	v_lshl_add_u64 v[160:161], s[30:31], 0, v[142:143]
	s_add_i32 m0, s34, 0x2000
	s_nop 0
	global_load_lds_dwordx4 v[160:161], off
	v_lshl_add_u64 v[160:161], v[232:233], 0, s[16:17]
	s_mov_b32 m0, s42
	s_nop 0
	global_load_lds_dwordx4 v[160:161], off
	v_lshl_add_u64 v[160:161], v[234:235], 0, s[16:17]
	s_mov_b32 m0, s43
	s_nop 0
	global_load_lds_dwordx4 v[160:161], off
	s_waitcnt vmcnt(8)
	s_waitcnt lgkmcnt(0)
	s_setprio 1
	s_barrier
	v_mfma_f32_16x16x32_bf16 v[92:95], v[128:131], v[198:201], v[92:95]
	v_mfma_f32_16x16x32_bf16 v[88:91], v[174:177], v[198:201], v[88:91]
	v_mfma_f32_16x16x32_bf16 v[84:87], v[128:131], v[206:209], v[84:87]
	v_mfma_f32_16x16x32_bf16 v[80:83], v[174:177], v[206:209], v[80:83]
	v_mfma_f32_16x16x32_bf16 v[76:79], v[128:131], v[214:217], v[76:79]
	v_mfma_f32_16x16x32_bf16 v[72:75], v[174:177], v[214:217], v[72:75]
	v_mfma_f32_16x16x32_bf16 v[68:71], v[128:131], v[222:225], v[68:71]
	v_mfma_f32_16x16x32_bf16 v[64:67], v[174:177], v[222:225], v[64:67]
	v_mfma_f32_16x16x32_bf16 v[92:95], v[132:135], v[202:205], v[92:95]
	v_mfma_f32_16x16x32_bf16 v[88:91], v[178:181], v[202:205], v[88:91]
	v_mfma_f32_16x16x32_bf16 v[84:87], v[132:135], v[210:213], v[84:87]
	v_mfma_f32_16x16x32_bf16 v[80:83], v[178:181], v[210:213], v[80:83]
	v_mfma_f32_16x16x32_bf16 v[76:79], v[132:135], v[218:221], v[76:79]
	v_mfma_f32_16x16x32_bf16 v[72:75], v[178:181], v[218:221], v[72:75]
	v_mfma_f32_16x16x32_bf16 v[68:71], v[132:135], v[226:229], v[68:71]
	v_mfma_f32_16x16x32_bf16 v[64:67], v[178:181], v[226:229], v[64:67]
	v_mfma_f32_16x16x32_bf16 v[28:31], v[182:185], v[198:201], v[28:31]
	v_mfma_f32_16x16x32_bf16 v[24:27], v[190:193], v[198:201], v[24:27]
	v_mfma_f32_16x16x32_bf16 v[20:23], v[182:185], v[206:209], v[20:23]
	v_mfma_f32_16x16x32_bf16 v[16:19], v[190:193], v[206:209], v[16:19]
	v_mfma_f32_16x16x32_bf16 v[12:15], v[182:185], v[214:217], v[12:15]
	v_mfma_f32_16x16x32_bf16 v[8:11], v[190:193], v[214:217], v[8:11]
	v_mfma_f32_16x16x32_bf16 v[4:7], v[182:185], v[222:225], v[4:7]
	v_mfma_f32_16x16x32_bf16 v[0:3], v[190:193], v[222:225], v[0:3]
	v_mfma_f32_16x16x32_bf16 v[28:31], v[186:189], v[202:205], v[28:31]
	v_mfma_f32_16x16x32_bf16 v[24:27], v[194:197], v[202:205], v[24:27]
	v_mfma_f32_16x16x32_bf16 v[20:23], v[186:189], v[210:213], v[20:23]
	v_mfma_f32_16x16x32_bf16 v[16:19], v[194:197], v[210:213], v[16:19]
	v_mfma_f32_16x16x32_bf16 v[12:15], v[186:189], v[218:221], v[12:15]
	v_mfma_f32_16x16x32_bf16 v[8:11], v[194:197], v[218:221], v[8:11]
	v_mfma_f32_16x16x32_bf16 v[4:7], v[186:189], v[226:229], v[4:7]
	s_setprio 0
	v_mfma_f32_16x16x32_bf16 v[0:3], v[194:197], v[226:229], v[0:3]
	s_barrier
	s_add_i32 s59, s59, 2
	s_add_u32 s28, s28, 0x100
	s_addc_u32 s29, s29, 0
	s_add_u32 s57, s57, 0x100
	s_addc_u32 s58, s58, 0
	s_cmp_gt_u32 s59, 13
	s_cbranch_scc0 .LBB0_607
	s_and_b64 vcc, exec, s[0:1]
	s_cbranch_vccz .LBB0_610
	s_barrier

; #define PG8_STAGE(bufoff, gbase, voff) do { _Pragma("unroll") for (int _i = 0; _i < 2; ++_i) \
;         __builtin_amdgcn_global_load_lds((const unsigned*)((const char*)(gbase) + (voff)[_i]), (PG8_LAS unsigned*)(lds + (bufoff) + ldsw + _i * 8192), 16, 0, 0); } while (0)
; #define PG8_LDA(dst, b, h) do { _Pragma("unroll") for (int m = 0; m < 4; ++m) _Pragma("unroll") for (int k = 0; k < 2; ++k) dst[m][k] = *(const PG8_LAS bf16x8*)(lds + PG8_SA(b, h) + aoff + m * 2048 + k * 1024); } while (0)
; #define PG8_LDB(dst, b, h) do { _Pragma("unroll") for (int n = 0; n < 2; ++n) _Pragma("unroll") for (int k = 0; k < 2; ++k) dst[n][k] = *(const PG8_LAS bf16x8*)(lds + PG8_SB(b, h) + boff + n * 2048 + k * 1024); } while (0)
; #define PG8_WAIT_V(n) asm volatile("s_waitcnt vmcnt(" #n ")" ::: "memory")
; #define PG8_WAIT_L(n) asm volatile("s_waitcnt lgkmcnt(" #n ")" ::: "memory")
; #define PG8_BAR __builtin_amdgcn_s_barrier()
; #define PG8_SCHED __builtin_amdgcn_sched_barrier(0)
; template <class Epi, class Sched, bool ALIGN_EPI = false, bool SP2 = false>
; __device__ __forceinline__ void gemm_phase(PG8_LAS unsigned char* lds, const Gemm g, const Sched& S, const Epi& E) {
;     ...
;         const bool has_next = S.next(ui + 1, nxt);
;         const char* nA = has_next ? (const char*)g.A + (size_t)nxt.pm * tstep : cA; const char* nB = has_next ? (const char*)g.Bt + (size_t)nxt.pn * tstep : cB;
;         for (int t = 0; t < nt; t += 2) {
;             const bool last = (t == nt - 2);
;             const char* a1 = cA + (size_t)(t + 1) * kstep;
;             const char* a2 = last ? nA : cA + (size_t)(t + 2) * kstep; const char* b2 = last ? nB : cB + (size_t)(t + 2) * kstep;
;             const char* a3 = a2 + kstep; const char* b3 = b2 + kstep;
;             if (last && has_next) S.a_ready(nxt, ui + 1);
;             if constexpr (SP2) {
;             PG8_LDB(B0, 0, 0); PG8_LDB(B1, 0, 1); PG8_SCHED; PG8_LDA(At, 0, 0); PG8_STAGE(PG8_SA(1, 1), a1 + hstep, voffA);
;             PG8_WAIT_V(8); PG8_WAIT_L(0); PG8_BAR; PG8_MMA(0, 0, At, B0); PG8_MMA(0, 1, At, B1); PG8_BAR; PG8_SCHED;
;             PG8_LDA(At, 0, 1); PG8_STAGE(PG8_SB(0, 0), b2, voffB); PG8_STAGE(PG8_SB(0, 1), b2 + hstep, voffB); PG8_STAGE(PG8_SA(0, 0), a2, voffA);
;             PG8_WAIT_V(8); PG8_WAIT_L(0); PG8_BAR; PG8_MMA(1, 0, At, B0); PG8_MMA(1, 1, At, B1); PG8_BAR; PG8_SCHED;
.LBB0_959:
	s_ashr_i32 s23, s22, 31
	s_lshl_b64 s[24:25], s[22:23], 19
	s_add_u32 s24, s3, s24
	s_addc_u32 s25, s33, s25
	s_and_b64 s[26:27], s[4:5], exec
	s_cselect_b32 s23, s25, s31
	s_cselect_b32 s29, s24, s30
	s_ashr_i32 s21, s20, 31
	s_lshl_b64 s[26:27], s[20:21], 19
	s_add_u32 s26, s38, s26
	s_addc_u32 s27, s39, s27
	s_and_b64 s[36:37], s[4:5], exec
	s_cselect_b32 s21, s27, s35
	s_cselect_b32 s54, s26, s34
	s_add_u32 s30, s30, 0x40080
	s_addc_u32 s31, s31, 0
	s_add_u32 s55, s34, 0x100
	s_addc_u32 s56, s35, 0
	s_mov_b32 s57, -2
	s_add_u32 s34, s30, 0xfffc0080
	s_addc_u32 s35, s31, -1
	s_cmp_eq_u32 s57, 12
	s_cselect_b32 s37, s23, s35
	s_cselect_b32 s36, s29, s34
	s_cselect_b32 s35, s21, s56
	s_cselect_b32 s34, s54, s55
	s_add_i32 m0, s41, 0xc000
	s_nop 0
	global_load_lds_dwordx4 v200, s[30:31]
	s_add_i32 m0, s41, 0xe000
	s_nop 0
	global_load_lds_dwordx4 v202, s[30:31]
	s_waitcnt vmcnt(8)
	s_waitcnt lgkmcnt(0)
	s_setprio 1
	s_barrier
	v_mfma_f32_16x16x32_bf16 v[132:135], v[120:123], v[160:163], 0
	v_mfma_f32_16x16x32_bf16 v[124:127], v[136:139], v[160:163], 0
	v_mfma_f32_16x16x32_bf16 v[108:111], v[120:123], v[168:171], 0
	v_mfma_f32_16x16x32_bf16 v[104:107], v[136:139], v[168:171], 0
	v_mfma_f32_16x16x32_bf16 v[92:95], v[120:123], v[176:179], 0
	v_mfma_f32_16x16x32_bf16 v[88:91], v[136:139], v[176:179], 0
	v_mfma_f32_16x16x32_bf16 v[76:79], v[120:123], v[184:187], 0
	v_mfma_f32_16x16x32_bf16 v[72:75], v[136:139], v[184:187], 0
	v_mfma_f32_16x16x32_bf16 v[132:135], v[128:131], v[164:167], v[132:135]
	v_mfma_f32_16x16x32_bf16 v[124:127], v[140:143], v[164:167], v[124:127]
	v_mfma_f32_16x16x32_bf16 v[108:111], v[128:131], v[172:175], v[108:111]
	v_mfma_f32_16x16x32_bf16 v[104:107], v[140:143], v[172:175], v[104:107]
	v_mfma_f32_16x16x32_bf16 v[92:95], v[128:131], v[180:183], v[92:95]
	v_mfma_f32_16x16x32_bf16 v[88:91], v[140:143], v[180:183], v[88:91]
	v_mfma_f32_16x16x32_bf16 v[76:79], v[128:131], v[188:191], v[76:79]
	v_mfma_f32_16x16x32_bf16 v[72:75], v[140:143], v[188:191], v[72:75]
	v_mfma_f32_16x16x32_bf16 v[116:119], v[144:147], v[160:163], 0
	v_mfma_f32_16x16x32_bf16 v[112:115], v[152:155], v[160:163], 0
	v_mfma_f32_16x16x32_bf16 v[100:103], v[144:147], v[168:171], 0
	v_mfma_f32_16x16x32_bf16 v[96:99], v[152:155], v[168:171], 0
	v_mfma_f32_16x16x32_bf16 v[84:87], v[144:147], v[176:179], 0
	v_mfma_f32_16x16x32_bf16 v[80:83], v[152:155], v[176:179], 0
	v_mfma_f32_16x16x32_bf16 v[68:71], v[144:147], v[184:187], 0
	v_mfma_f32_16x16x32_bf16 v[64:67], v[152:155], v[184:187], 0
	v_mfma_f32_16x16x32_bf16 v[116:119], v[148:151], v[164:167], v[116:119]
	v_mfma_f32_16x16x32_bf16 v[112:115], v[156:159], v[164:167], v[112:115]
	v_mfma_f32_16x16x32_bf16 v[100:103], v[148:151], v[172:175], v[100:103]
	v_mfma_f32_16x16x32_bf16 v[96:99], v[156:159], v[172:175], v[96:99]
	v_mfma_f32_16x16x32_bf16 v[84:87], v[148:151], v[180:183], v[84:87]
	v_mfma_f32_16x16x32_bf16 v[80:83], v[156:159], v[180:183], v[80:83]
	v_mfma_f32_16x16x32_bf16 v[68:71], v[148:151], v[188:191], v[68:71]
	s_setprio 0
	v_mfma_f32_16x16x32_bf16 v[64:67], v[156:159], v[188:191], v[64:67]
	s_barrier
	s_add_i32 s58, s51, s40
	v_lshl_add_u64 v[204:205], s[34:35], 0, v[194:195]
	s_mov_b32 m0, s58
	ds_read_b128 v[160:163], v247 offset:16384
	ds_read_b128 v[164:167], v247 offset:17408
	ds_read_b128 v[168:171], v247 offset:18432
	ds_read_b128 v[172:175], v247 offset:19456
	ds_read_b128 v[176:179], v247 offset:20480
	ds_read_b128 v[180:183], v247 offset:21504
	ds_read_b128 v[184:187], v247 offset:22528
	ds_read_b128 v[188:191], v247 offset:23552
	global_load_lds_dwordx4 v[204:205], off
	s_add_i32 m0, s58, 0x2000
	s_add_u32 s58, s34, 0x40000
	v_lshl_add_u64 v[206:207], s[34:35], 0, v[198:199]
	s_addc_u32 s59, s35, 0
	s_add_i32 s60, s52, s40
	global_load_lds_dwordx4 v[206:207], off
	s_mov_b32 m0, s60
	v_lshl_add_u64 v[210:211], s[36:37], 0, v[196:197]
	global_load_lds_dwordx4 v194, s[58:59]
	s_add_i32 m0, s60, 0x2000
	s_nop 0
	global_load_lds_dwordx4 v198, s[58:59]
	v_lshl_add_u64 v[208:209], s[36:37], 0, v[192:193]
	s_mov_b32 m0, s41
	s_nop 0
	global_load_lds_dwordx4 v[208:209], off
	s_mov_b32 m0, s42
	s_nop 0
	global_load_lds_dwordx4 v[210:211], off
	s_waitcnt vmcnt(8)
	s_waitcnt lgkmcnt(0)
	s_setprio 1
	s_barrier
	v_mfma_f32_16x16x32_bf16 v[60:63], v[120:123], v[160:163], 0
	v_mfma_f32_16x16x32_bf16 v[56:59], v[136:139], v[160:163], 0
	v_mfma_f32_16x16x32_bf16 v[44:47], v[120:123], v[168:171], 0
	v_mfma_f32_16x16x32_bf16 v[40:43], v[136:139], v[168:171], 0
	v_mfma_f32_16x16x32_bf16 v[28:31], v[120:123], v[176:179], 0
	v_mfma_f32_16x16x32_bf16 v[24:27], v[136:139], v[176:179], 0
	v_mfma_f32_16x16x32_bf16 v[12:15], v[120:123], v[184:187], 0
	v_mfma_f32_16x16x32_bf16 v[8:11], v[136:139], v[184:187], 0
	v_mfma_f32_16x16x32_bf16 v[60:63], v[128:131], v[164:167], v[60:63]
	v_mfma_f32_16x16x32_bf16 v[56:59], v[140:143], v[164:167], v[56:59]
	v_mfma_f32_16x16x32_bf16 v[44:47], v[128:131], v[172:175], v[44:47]
	v_mfma_f32_16x16x32_bf16 v[40:43], v[140:143], v[172:175], v[40:43]
	v_mfma_f32_16x16x32_bf16 v[28:31], v[128:131], v[180:183], v[28:31]
	v_mfma_f32_16x16x32_bf16 v[24:27], v[140:143], v[180:183], v[24:27]
	v_mfma_f32_16x16x32_bf16 v[12:15], v[128:131], v[188:191], v[12:15]
	v_mfma_f32_16x16x32_bf16 v[8:11], v[140:143], v[188:191], v[8:11]
	v_mfma_f32_16x16x32_bf16 v[52:55], v[144:147], v[160:163], 0
	v_mfma_f32_16x16x32_bf16 v[48:51], v[152:155], v[160:163], 0
	v_mfma_f32_16x16x32_bf16 v[36:39], v[144:147], v[168:171], 0
	v_mfma_f32_16x16x32_bf16 v[32:35], v[152:155], v[168:171], 0
	v_mfma_f32_16x16x32_bf16 v[20:23], v[144:147], v[176:179], 0
	v_mfma_f32_16x16x32_bf16 v[16:19], v[152:155], v[176:179], 0
	v_mfma_f32_16x16x32_bf16 v[4:7], v[144:147], v[184:187], 0
	v_mfma_f32_16x16x32_bf16 v[0:3], v[152:155], v[184:187], 0
	v_mfma_f32_16x16x32_bf16 v[52:55], v[148:151], v[164:167], v[52:55]
	v_mfma_f32_16x16x32_bf16 v[48:51], v[156:159], v[164:167], v[48:51]
	v_mfma_f32_16x16x32_bf16 v[36:39], v[148:151], v[172:175], v[36:39]
	v_mfma_f32_16x16x32_bf16 v[32:35], v[156:159], v[172:175], v[32:35]
	v_mfma_f32_16x16x32_bf16 v[20:23], v[148:151], v[180:183], v[20:23]
	v_mfma_f32_16x16x32_bf16 v[16:19], v[156:159], v[180:183], v[16:19]
	v_mfma_f32_16x16x32_bf16 v[4:7], v[148:151], v[188:191], v[4:7]
	s_setprio 0
	v_mfma_f32_16x16x32_bf16 v[0:3], v[156:159], v[188:191], v[0:3]
	s_barrier
; #define PG8_STAGE(bufoff, gbase, voff) do { _Pragma("unroll") for (int _i = 0; _i < 2; ++_i) \
;         __builtin_amdgcn_global_load_lds((const unsigned*)((const char*)(gbase) + (voff)[_i]), (PG8_LAS unsigned*)(lds + (bufoff) + ldsw + _i * 8192), 16, 0, 0); } while (0)
; #define PG8_LDA(dst, b, h) do { _Pragma("unroll") for (int m = 0; m < 4; ++m) _Pragma("unroll") for (int k = 0; k < 2; ++k) dst[m][k] = *(const PG8_LAS bf16x8*)(lds + PG8_SA(b, h) + aoff + m * 2048 + k * 1024); } while (0)
; #define PG8_LDB(dst, b, h) do { _Pragma("unroll") for (int n = 0; n < 2; ++n) _Pragma("unroll") for (int k = 0; k < 2; ++k) dst[n][k] = *(const PG8_LAS bf16x8*)(lds + PG8_SB(b, h) + boff + n * 2048 + k * 1024); } while (0)
; #define PG8_MMA(ai, bj, At, Bt) do { __builtin_amdgcn_s_setprio(1); _Pragma("unroll") for (int m = 0; m < 4; ++m) _Pragma("unroll") for (int n = 0; n < 2; ++n) _Pragma("unroll") for (int k = 0; k < 2; ++k) \
;         acc[ai][bj][m][n] = __builtin_amdgcn_mfma_f32_16x16x32_bf16(Bt[n][k], At[m][k], acc[ai][bj][m][n], 0, 0, 0); __builtin_amdgcn_s_setprio(0); } while (0)
; #define PG8_WAIT_V(n) asm volatile("s_waitcnt vmcnt(" #n ")" ::: "memory")
; #define PG8_WAIT_L(n) asm volatile("s_waitcnt lgkmcnt(" #n ")" ::: "memory")
; #define PG8_BAR __builtin_amdgcn_s_barrier()
; #define PG8_SCHED __builtin_amdgcn_sched_barrier(0)
; template <class Epi, class Sched, bool ALIGN_EPI = false, bool SP2 = false>
; __device__ __forceinline__ void gemm_phase(PG8_LAS unsigned char* lds, const Gemm g, const Sched& S, const Epi& E) {
;     ...
;         for (int t = 0; t < nt; t += 2) {
;             const bool last = (t == nt - 2);
;     ...
;             PG8_LDB(B0, 1, 0); PG8_LDB(B1, 1, 1); PG8_SCHED; PG8_LDA(At, 1, 0); PG8_STAGE(PG8_SA(0, 1), a2 + hstep, voffA);
;             PG8_WAIT_V(8); PG8_WAIT_L(0); PG8_BAR; PG8_MMA(0, 0, At, B0); PG8_MMA(0, 1, At, B1); PG8_BAR; PG8_SCHED;
;             PG8_LDA(At, 1, 1); PG8_STAGE(PG8_SB(1, 0), b3, voffB); PG8_STAGE(PG8_SB(1, 1), b3 + hstep, voffB); PG8_STAGE(PG8_SA(1, 0), a3, voffA);
;             PG8_WAIT_V(8); PG8_WAIT_L(0); PG8_BAR; PG8_MMA(1, 0, At, B0); PG8_MMA(1, 1, At, B1); PG8_BAR; PG8_SCHED;
	s_add_i32 s58, 0, 0x18000
	s_add_i32 s59, 0, 0x1c000
	v_add_u32_e32 v140, s58, v243
	v_add_u32_e32 v156, s59, v243
	ds_read_b128 v[120:123], v140
	ds_read_b128 v[128:131], v140 offset:1024
	ds_read_b128 v[136:139], v140 offset:2048
	ds_read_b128 v[140:143], v140 offset:3072
	ds_read_b128 v[144:147], v156
	ds_read_b128 v[148:151], v156 offset:1024
	ds_read_b128 v[152:155], v156 offset:2048
	ds_read_b128 v[156:159], v156 offset:3072
	s_add_u32 s36, s36, 0x40000
	s_addc_u32 s37, s37, 0
	s_mov_b32 m0, s43
	ds_read_b128 v[160:163], v247 offset:32768
	ds_read_b128 v[164:167], v247 offset:33792
	ds_read_b128 v[168:171], v247 offset:34816
	ds_read_b128 v[172:175], v247 offset:35840
	ds_read_b128 v[176:179], v247 offset:36864
	ds_read_b128 v[180:183], v247 offset:37888
	ds_read_b128 v[184:187], v247 offset:38912
	ds_read_b128 v[188:191], v247 offset:39936
	global_load_lds_dwordx4 v192, s[36:37]
	s_mov_b32 m0, s44
	s_nop 0
	global_load_lds_dwordx4 v196, s[36:37]
	s_waitcnt vmcnt(8)
	s_waitcnt lgkmcnt(0)
	s_setprio 1
	s_barrier
	v_mfma_f32_16x16x32_bf16 v[132:135], v[120:123], v[160:163], v[132:135]
	v_mfma_f32_16x16x32_bf16 v[124:127], v[136:139], v[160:163], v[124:127]
	v_mfma_f32_16x16x32_bf16 v[108:111], v[120:123], v[168:171], v[108:111]
	v_mfma_f32_16x16x32_bf16 v[104:107], v[136:139], v[168:171], v[104:107]
	v_mfma_f32_16x16x32_bf16 v[92:95], v[120:123], v[176:179], v[92:95]
	v_mfma_f32_16x16x32_bf16 v[88:91], v[136:139], v[176:179], v[88:91]
	v_mfma_f32_16x16x32_bf16 v[76:79], v[120:123], v[184:187], v[76:79]
	v_mfma_f32_16x16x32_bf16 v[72:75], v[136:139], v[184:187], v[72:75]
	v_mfma_f32_16x16x32_bf16 v[132:135], v[128:131], v[164:167], v[132:135]
	v_mfma_f32_16x16x32_bf16 v[124:127], v[140:143], v[164:167], v[124:127]
	v_mfma_f32_16x16x32_bf16 v[108:111], v[128:131], v[172:175], v[108:111]
	v_mfma_f32_16x16x32_bf16 v[104:107], v[140:143], v[172:175], v[104:107]
	v_mfma_f32_16x16x32_bf16 v[92:95], v[128:131], v[180:183], v[92:95]
	v_mfma_f32_16x16x32_bf16 v[88:91], v[140:143], v[180:183], v[88:91]
	v_mfma_f32_16x16x32_bf16 v[76:79], v[128:131], v[188:191], v[76:79]
	v_mfma_f32_16x16x32_bf16 v[72:75], v[140:143], v[188:191], v[72:75]
	v_mfma_f32_16x16x32_bf16 v[116:119], v[144:147], v[160:163], v[116:119]
	v_mfma_f32_16x16x32_bf16 v[112:115], v[152:155], v[160:163], v[112:115]
	v_mfma_f32_16x16x32_bf16 v[100:103], v[144:147], v[168:171], v[100:103]
	v_mfma_f32_16x16x32_bf16 v[96:99], v[152:155], v[168:171], v[96:99]
	v_mfma_f32_16x16x32_bf16 v[84:87], v[144:147], v[176:179], v[84:87]
	v_mfma_f32_16x16x32_bf16 v[80:83], v[152:155], v[176:179], v[80:83]
	v_mfma_f32_16x16x32_bf16 v[68:71], v[144:147], v[184:187], v[68:71]
	v_mfma_f32_16x16x32_bf16 v[64:67], v[152:155], v[184:187], v[64:67]
	v_mfma_f32_16x16x32_bf16 v[116:119], v[148:151], v[164:167], v[116:119]
	v_mfma_f32_16x16x32_bf16 v[112:115], v[156:159], v[164:167], v[112:115]
	v_mfma_f32_16x16x32_bf16 v[100:103], v[148:151], v[172:175], v[100:103]
	v_mfma_f32_16x16x32_bf16 v[96:99], v[156:159], v[172:175], v[96:99]
	v_mfma_f32_16x16x32_bf16 v[84:87], v[148:151], v[180:183], v[84:87]
	v_mfma_f32_16x16x32_bf16 v[80:83], v[156:159], v[180:183], v[80:83]
	v_mfma_f32_16x16x32_bf16 v[68:71], v[148:151], v[188:191], v[68:71]
	s_setprio 0
	v_mfma_f32_16x16x32_bf16 v[64:67], v[156:159], v[188:191], v[64:67]
	s_barrier
	s_add_i32 s36, s58, s40
	v_lshl_add_u64 v[204:205], v[204:205], 0, s[16:17]
	s_mov_b32 m0, s36
	ds_read_b128 v[160:163], v247 offset:49152
	ds_read_b128 v[164:167], v247 offset:50176
	ds_read_b128 v[168:171], v247 offset:51200
	ds_read_b128 v[172:175], v247 offset:52224
	ds_read_b128 v[176:179], v247 offset:53248
	ds_read_b128 v[180:183], v247 offset:54272
	ds_read_b128 v[184:187], v247 offset:55296
	ds_read_b128 v[188:191], v247 offset:56320
	global_load_lds_dwordx4 v[204:205], off
	s_add_i32 m0, s36, 0x2000
	s_add_u32 s34, s34, 0x40080
	v_lshl_add_u64 v[204:205], v[206:207], 0, s[16:17]
	s_addc_u32 s35, s35, 0
	s_add_i32 s36, s59, s40
	global_load_lds_dwordx4 v[204:205], off
	s_mov_b32 m0, s36
	s_nop 0
	global_load_lds_dwordx4 v194, s[34:35]
	s_add_i32 m0, s36, 0x2000
	s_nop 0
	global_load_lds_dwordx4 v198, s[34:35]
	v_lshl_add_u64 v[204:205], v[208:209], 0, s[16:17]
	s_mov_b32 m0, s46
	s_nop 0
	global_load_lds_dwordx4 v[204:205], off
	v_lshl_add_u64 v[204:205], v[210:211], 0, s[16:17]
	s_mov_b32 m0, s47
	s_nop 0
	global_load_lds_dwordx4 v[204:205], off
	s_waitcnt vmcnt(8)
	s_waitcnt lgkmcnt(0)
	s_setprio 1
	s_barrier
	v_mfma_f32_16x16x32_bf16 v[60:63], v[120:123], v[160:163], v[60:63]
	v_mfma_f32_16x16x32_bf16 v[56:59], v[136:139], v[160:163], v[56:59]
	v_mfma_f32_16x16x32_bf16 v[44:47], v[120:123], v[168:171], v[44:47]
	v_mfma_f32_16x16x32_bf16 v[40:43], v[136:139], v[168:171], v[40:43]
	v_mfma_f32_16x16x32_bf16 v[28:31], v[120:123], v[176:179], v[28:31]
	v_mfma_f32_16x16x32_bf16 v[24:27], v[136:139], v[176:179], v[24:27]
	v_mfma_f32_16x16x32_bf16 v[12:15], v[120:123], v[184:187], v[12:15]
	v_mfma_f32_16x16x32_bf16 v[8:11], v[136:139], v[184:187], v[8:11]
	v_mfma_f32_16x16x32_bf16 v[60:63], v[128:131], v[164:167], v[60:63]
	v_mfma_f32_16x16x32_bf16 v[56:59], v[140:143], v[164:167], v[56:59]
	v_mfma_f32_16x16x32_bf16 v[44:47], v[128:131], v[172:175], v[44:47]
	v_mfma_f32_16x16x32_bf16 v[40:43], v[140:143], v[172:175], v[40:43]
	v_mfma_f32_16x16x32_bf16 v[28:31], v[128:131], v[180:183], v[28:31]
	v_mfma_f32_16x16x32_bf16 v[24:27], v[140:143], v[180:183], v[24:27]
	v_mfma_f32_16x16x32_bf16 v[12:15], v[128:131], v[188:191], v[12:15]
	v_mfma_f32_16x16x32_bf16 v[8:11], v[140:143], v[188:191], v[8:11]
	v_mfma_f32_16x16x32_bf16 v[52:55], v[144:147], v[160:163], v[52:55]
	v_mfma_f32_16x16x32_bf16 v[48:51], v[152:155], v[160:163], v[48:51]
	v_mfma_f32_16x16x32_bf16 v[36:39], v[144:147], v[168:171], v[36:39]
	v_mfma_f32_16x16x32_bf16 v[32:35], v[152:155], v[168:171], v[32:35]
	v_mfma_f32_16x16x32_bf16 v[20:23], v[144:147], v[176:179], v[20:23]
	v_mfma_f32_16x16x32_bf16 v[16:19], v[152:155], v[176:179], v[16:19]
	v_mfma_f32_16x16x32_bf16 v[4:7], v[144:147], v[184:187], v[4:7]
	v_mfma_f32_16x16x32_bf16 v[0:3], v[152:155], v[184:187], v[0:3]
	v_mfma_f32_16x16x32_bf16 v[52:55], v[148:151], v[164:167], v[52:55]
	v_mfma_f32_16x16x32_bf16 v[48:51], v[156:159], v[164:167], v[48:51]
	v_mfma_f32_16x16x32_bf16 v[36:39], v[148:151], v[172:175], v[36:39]
	v_mfma_f32_16x16x32_bf16 v[32:35], v[156:159], v[172:175], v[32:35]
	v_mfma_f32_16x16x32_bf16 v[20:23], v[148:151], v[180:183], v[20:23]
	v_mfma_f32_16x16x32_bf16 v[16:19], v[156:159], v[180:183], v[16:19]
	v_mfma_f32_16x16x32_bf16 v[4:7], v[148:151], v[188:191], v[4:7]
	s_setprio 0
	v_mfma_f32_16x16x32_bf16 v[0:3], v[156:159], v[188:191], v[0:3]
	s_barrier
	s_add_i32 s57, s57, 2
	s_add_u32 s30, s30, 0x100
	s_addc_u32 s31, s31, 0
	s_add_u32 s55, s55, 0x100
	s_addc_u32 s56, s56, 0
	s_cmp_gt_u32 s57, 13
; #define PG8_STAGE(bufoff, gbase, voff) do { _Pragma("unroll") for (int _i = 0; _i < 2; ++_i) \
;         __builtin_amdgcn_global_load_lds((const unsigned*)((const char*)(gbase) + (voff)[_i]), (PG8_LAS unsigned*)(lds + (bufoff) + ldsw + _i * 8192), 16, 0, 0); } while (0)
; #define PG8_LDA(dst, b, h) do { _Pragma("unroll") for (int m = 0; m < 4; ++m) _Pragma("unroll") for (int k = 0; k < 2; ++k) dst[m][k] = *(const PG8_LAS bf16x8*)(lds + PG8_SA(b, h) + aoff + m * 2048 + k * 1024); } while (0)
; #define PG8_LDB(dst, b, h) do { _Pragma("unroll") for (int n = 0; n < 2; ++n) _Pragma("unroll") for (int k = 0; k < 2; ++k) dst[n][k] = *(const PG8_LAS bf16x8*)(lds + PG8_SB(b, h) + boff + n * 2048 + k * 1024); } while (0)
; #define PG8_MMA(ai, bj, At, Bt) do { __builtin_amdgcn_s_setprio(1); _Pragma("unroll") for (int m = 0; m < 4; ++m) _Pragma("unroll") for (int n = 0; n < 2; ++n) _Pragma("unroll") for (int k = 0; k < 2; ++k) \
;         acc[ai][bj][m][n] = __builtin_amdgcn_mfma_f32_16x16x32_bf16(Bt[n][k], At[m][k], acc[ai][bj][m][n], 0, 0, 0); __builtin_amdgcn_s_setprio(0); } while (0)
; #define PG8_WAIT_V(n) asm volatile("s_waitcnt vmcnt(" #n ")" ::: "memory")
; #define PG8_WAIT_L(n) asm volatile("s_waitcnt lgkmcnt(" #n ")" ::: "memory")
; #define PG8_BAR __builtin_amdgcn_s_barrier()
; #define PG8_SCHED __builtin_amdgcn_sched_barrier(0)
; template <class Epi, class Sched, bool ALIGN_EPI = false, bool SP2 = false>
; __device__ __forceinline__ void gemm_phase(PG8_LAS unsigned char* lds, const Gemm g, const Sched& S, const Epi& E) {
;     ...
;             PG8_LDB(B0, 0, 0); PG8_LDB(B1, 0, 1); PG8_SCHED; PG8_LDA(At, 0, 0); PG8_STAGE(PG8_SA(1, 1), a1 + hstep, voffA);
;             PG8_WAIT_V(8); PG8_WAIT_L(0); PG8_BAR; PG8_MMA(0, 0, At, B0); PG8_MMA(0, 1, At, B1); PG8_BAR; PG8_SCHED;
;             PG8_LDA(At, 0, 1); PG8_STAGE(PG8_SB(0, 0), b2, voffB); PG8_STAGE(PG8_SB(0, 1), b2 + hstep, voffB); PG8_STAGE(PG8_SA(0, 0), a2, voffA);
;             PG8_WAIT_V(8); PG8_WAIT_L(0); PG8_BAR; PG8_MMA(1, 0, At, B0); PG8_MMA(1, 1, At, B1); PG8_BAR; PG8_SCHED;
.LBB0_960:
	ds_read_b128 v[120:123], v245
	ds_read_b128 v[128:131], v245 offset:1024
	ds_read_b128 v[136:139], v245 offset:2048
	ds_read_b128 v[140:143], v245 offset:3072
	ds_read_b128 v[144:147], v246
	ds_read_b128 v[148:151], v246 offset:1024
	ds_read_b128 v[152:155], v246 offset:2048
	ds_read_b128 v[156:159], v246 offset:3072
	s_add_u32 s34, s30, 0xfffc0080
	s_addc_u32 s35, s31, -1
	s_cmp_eq_u32 s57, 12
	s_cselect_b32 s37, s23, s35
	s_cselect_b32 s36, s29, s34
	s_cselect_b32 s35, s21, s56
	s_cselect_b32 s34, s54, s55
	s_add_i32 m0, s41, 0xc000
	ds_read_b128 v[160:163], v247
	ds_read_b128 v[164:167], v247 offset:1024
	ds_read_b128 v[168:171], v247 offset:2048
	ds_read_b128 v[172:175], v247 offset:3072
	ds_read_b128 v[176:179], v247 offset:4096
	ds_read_b128 v[180:183], v247 offset:5120
	ds_read_b128 v[184:187], v247 offset:6144
	ds_read_b128 v[188:191], v247 offset:7168
	global_load_lds_dwordx4 v200, s[30:31]
	s_add_i32 m0, s41, 0xe000
	s_nop 0
	global_load_lds_dwordx4 v202, s[30:31]
	s_waitcnt vmcnt(8)
	s_waitcnt lgkmcnt(0)
	s_setprio 1
	s_barrier
	v_mfma_f32_16x16x32_bf16 v[132:135], v[120:123], v[160:163], v[132:135]
	v_mfma_f32_16x16x32_bf16 v[124:127], v[136:139], v[160:163], v[124:127]
	v_mfma_f32_16x16x32_bf16 v[108:111], v[120:123], v[168:171], v[108:111]
	v_mfma_f32_16x16x32_bf16 v[104:107], v[136:139], v[168:171], v[104:107]
	v_mfma_f32_16x16x32_bf16 v[92:95], v[120:123], v[176:179], v[92:95]
	v_mfma_f32_16x16x32_bf16 v[88:91], v[136:139], v[176:179], v[88:91]
	v_mfma_f32_16x16x32_bf16 v[76:79], v[120:123], v[184:187], v[76:79]
	v_mfma_f32_16x16x32_bf16 v[72:75], v[136:139], v[184:187], v[72:75]
	v_mfma_f32_16x16x32_bf16 v[132:135], v[128:131], v[164:167], v[132:135]
	v_mfma_f32_16x16x32_bf16 v[124:127], v[140:143], v[164:167], v[124:127]
	v_mfma_f32_16x16x32_bf16 v[108:111], v[128:131], v[172:175], v[108:111]
	v_mfma_f32_16x16x32_bf16 v[104:107], v[140:143], v[172:175], v[104:107]
	v_mfma_f32_16x16x32_bf16 v[92:95], v[128:131], v[180:183], v[92:95]
	v_mfma_f32_16x16x32_bf16 v[88:91], v[140:143], v[180:183], v[88:91]
	v_mfma_f32_16x16x32_bf16 v[76:79], v[128:131], v[188:191], v[76:79]
	v_mfma_f32_16x16x32_bf16 v[72:75], v[140:143], v[188:191], v[72:75]
	v_mfma_f32_16x16x32_bf16 v[116:119], v[144:147], v[160:163], v[116:119]
	v_mfma_f32_16x16x32_bf16 v[112:115], v[152:155], v[160:163], v[112:115]
	v_mfma_f32_16x16x32_bf16 v[100:103], v[144:147], v[168:171], v[100:103]
	v_mfma_f32_16x16x32_bf16 v[96:99], v[152:155], v[168:171], v[96:99]
	v_mfma_f32_16x16x32_bf16 v[84:87], v[144:147], v[176:179], v[84:87]
	v_mfma_f32_16x16x32_bf16 v[80:83], v[152:155], v[176:179], v[80:83]
	v_mfma_f32_16x16x32_bf16 v[68:71], v[144:147], v[184:187], v[68:71]
	v_mfma_f32_16x16x32_bf16 v[64:67], v[152:155], v[184:187], v[64:67]
	v_mfma_f32_16x16x32_bf16 v[116:119], v[148:151], v[164:167], v[116:119]
	v_mfma_f32_16x16x32_bf16 v[112:115], v[156:159], v[164:167], v[112:115]
	v_mfma_f32_16x16x32_bf16 v[100:103], v[148:151], v[172:175], v[100:103]
	v_mfma_f32_16x16x32_bf16 v[96:99], v[156:159], v[172:175], v[96:99]
	v_mfma_f32_16x16x32_bf16 v[84:87], v[148:151], v[180:183], v[84:87]
	v_mfma_f32_16x16x32_bf16 v[80:83], v[156:159], v[180:183], v[80:83]
	v_mfma_f32_16x16x32_bf16 v[68:71], v[148:151], v[188:191], v[68:71]
	s_setprio 0
	v_mfma_f32_16x16x32_bf16 v[64:67], v[156:159], v[188:191], v[64:67]
	s_barrier
	s_add_i32 s58, s51, s40
	v_lshl_add_u64 v[204:205], s[34:35], 0, v[194:195]
	s_mov_b32 m0, s58
	ds_read_b128 v[160:163], v247 offset:16384
	ds_read_b128 v[164:167], v247 offset:17408
	ds_read_b128 v[168:171], v247 offset:18432
	ds_read_b128 v[172:175], v247 offset:19456
	ds_read_b128 v[176:179], v247 offset:20480
	ds_read_b128 v[180:183], v247 offset:21504
	ds_read_b128 v[184:187], v247 offset:22528
	ds_read_b128 v[188:191], v247 offset:23552
	global_load_lds_dwordx4 v[204:205], off
	s_add_i32 m0, s58, 0x2000
	s_add_u32 s58, s34, 0x40000
	v_lshl_add_u64 v[206:207], s[34:35], 0, v[198:199]
	s_addc_u32 s59, s35, 0
	s_add_i32 s60, s52, s40
	global_load_lds_dwordx4 v[206:207], off
	s_mov_b32 m0, s60
	v_lshl_add_u64 v[210:211], s[36:37], 0, v[196:197]
	global_load_lds_dwordx4 v194, s[58:59]
	s_add_i32 m0, s60, 0x2000
	s_nop 0
	global_load_lds_dwordx4 v198, s[58:59]
	v_lshl_add_u64 v[208:209], s[36:37], 0, v[192:193]
	s_mov_b32 m0, s41
	s_nop 0
	global_load_lds_dwordx4 v[208:209], off
	s_mov_b32 m0, s42
	s_nop 0
	global_load_lds_dwordx4 v[210:211], off
	s_waitcnt vmcnt(8)
	s_waitcnt lgkmcnt(0)
	s_setprio 1
	s_barrier
	v_mfma_f32_16x16x32_bf16 v[60:63], v[120:123], v[160:163], v[60:63]
	v_mfma_f32_16x16x32_bf16 v[56:59], v[136:139], v[160:163], v[56:59]
	v_mfma_f32_16x16x32_bf16 v[44:47], v[120:123], v[168:171], v[44:47]
	v_mfma_f32_16x16x32_bf16 v[40:43], v[136:139], v[168:171], v[40:43]
	v_mfma_f32_16x16x32_bf16 v[28:31], v[120:123], v[176:179], v[28:31]
	v_mfma_f32_16x16x32_bf16 v[24:27], v[136:139], v[176:179], v[24:27]
	v_mfma_f32_16x16x32_bf16 v[12:15], v[120:123], v[184:187], v[12:15]
	v_mfma_f32_16x16x32_bf16 v[8:11], v[136:139], v[184:187], v[8:11]
	v_mfma_f32_16x16x32_bf16 v[60:63], v[128:131], v[164:167], v[60:63]
	v_mfma_f32_16x16x32_bf16 v[56:59], v[140:143], v[164:167], v[56:59]
	v_mfma_f32_16x16x32_bf16 v[44:47], v[128:131], v[172:175], v[44:47]
	v_mfma_f32_16x16x32_bf16 v[40:43], v[140:143], v[172:175], v[40:43]
	v_mfma_f32_16x16x32_bf16 v[28:31], v[128:131], v[180:183], v[28:31]
	v_mfma_f32_16x16x32_bf16 v[24:27], v[140:143], v[180:183], v[24:27]
	v_mfma_f32_16x16x32_bf16 v[12:15], v[128:131], v[188:191], v[12:15]
	v_mfma_f32_16x16x32_bf16 v[8:11], v[140:143], v[188:191], v[8:11]
	v_mfma_f32_16x16x32_bf16 v[52:55], v[144:147], v[160:163], v[52:55]
	v_mfma_f32_16x16x32_bf16 v[48:51], v[152:155], v[160:163], v[48:51]
	v_mfma_f32_16x16x32_bf16 v[36:39], v[144:147], v[168:171], v[36:39]
	v_mfma_f32_16x16x32_bf16 v[32:35], v[152:155], v[168:171], v[32:35]
	v_mfma_f32_16x16x32_bf16 v[20:23], v[144:147], v[176:179], v[20:23]
	v_mfma_f32_16x16x32_bf16 v[16:19], v[152:155], v[176:179], v[16:19]
	v_mfma_f32_16x16x32_bf16 v[4:7], v[144:147], v[184:187], v[4:7]
	v_mfma_f32_16x16x32_bf16 v[0:3], v[152:155], v[184:187], v[0:3]
	v_mfma_f32_16x16x32_bf16 v[52:55], v[148:151], v[164:167], v[52:55]
	v_mfma_f32_16x16x32_bf16 v[48:51], v[156:159], v[164:167], v[48:51]
	v_mfma_f32_16x16x32_bf16 v[36:39], v[148:151], v[172:175], v[36:39]
	v_mfma_f32_16x16x32_bf16 v[32:35], v[156:159], v[172:175], v[32:35]
	v_mfma_f32_16x16x32_bf16 v[20:23], v[148:151], v[180:183], v[20:23]
	v_mfma_f32_16x16x32_bf16 v[16:19], v[156:159], v[180:183], v[16:19]
	v_mfma_f32_16x16x32_bf16 v[4:7], v[148:151], v[188:191], v[4:7]
	s_setprio 0
	v_mfma_f32_16x16x32_bf16 v[0:3], v[156:159], v[188:191], v[0:3]
	s_barrier
; #define PG8_STAGE(bufoff, gbase, voff) do { _Pragma("unroll") for (int _i = 0; _i < 2; ++_i) \
;         __builtin_amdgcn_global_load_lds((const unsigned*)((const char*)(gbase) + (voff)[_i]), (PG8_LAS unsigned*)(lds + (bufoff) + ldsw + _i * 8192), 16, 0, 0); } while (0)
; #define PG8_LDA(dst, b, h) do { _Pragma("unroll") for (int m = 0; m < 4; ++m) _Pragma("unroll") for (int k = 0; k < 2; ++k) dst[m][k] = *(const PG8_LAS bf16x8*)(lds + PG8_SA(b, h) + aoff + m * 2048 + k * 1024); } while (0)
; #define PG8_LDB(dst, b, h) do { _Pragma("unroll") for (int n = 0; n < 2; ++n) _Pragma("unroll") for (int k = 0; k < 2; ++k) dst[n][k] = *(const PG8_LAS bf16x8*)(lds + PG8_SB(b, h) + boff + n * 2048 + k * 1024); } while (0)
; #define PG8_MMA(ai, bj, At, Bt) do { __builtin_amdgcn_s_setprio(1); _Pragma("unroll") for (int m = 0; m < 4; ++m) _Pragma("unroll") for (int n = 0; n < 2; ++n) _Pragma("unroll") for (int k = 0; k < 2; ++k) \
;         acc[ai][bj][m][n] = __builtin_amdgcn_mfma_f32_16x16x32_bf16(Bt[n][k], At[m][k], acc[ai][bj][m][n], 0, 0, 0); __builtin_amdgcn_s_setprio(0); } while (0)
; #define PG8_WAIT_V(n) asm volatile("s_waitcnt vmcnt(" #n ")" ::: "memory")
; #define PG8_WAIT_L(n) asm volatile("s_waitcnt lgkmcnt(" #n ")" ::: "memory")
; #define PG8_BAR __builtin_amdgcn_s_barrier()
; #define PG8_SCHED __builtin_amdgcn_sched_barrier(0)
; template <class Epi, class Sched, bool ALIGN_EPI = false, bool SP2 = false>
; __device__ __forceinline__ void gemm_phase(PG8_LAS unsigned char* lds, const Gemm g, const Sched& S, const Epi& E) {
;     ...
;         for (int t = 0; t < nt; t += 2) {
;             const bool last = (t == nt - 2);
;     ...
;             PG8_LDB(B0, 1, 0); PG8_LDB(B1, 1, 1); PG8_SCHED; PG8_LDA(At, 1, 0); PG8_STAGE(PG8_SA(0, 1), a2 + hstep, voffA);
;             PG8_WAIT_V(8); PG8_WAIT_L(0); PG8_BAR; PG8_MMA(0, 0, At, B0); PG8_MMA(0, 1, At, B1); PG8_BAR; PG8_SCHED;
;             PG8_LDA(At, 1, 1); PG8_STAGE(PG8_SB(1, 0), b3, voffB); PG8_STAGE(PG8_SB(1, 1), b3 + hstep, voffB); PG8_STAGE(PG8_SA(1, 0), a3, voffA);
;             PG8_WAIT_V(8); PG8_WAIT_L(0); PG8_BAR; PG8_MMA(1, 0, At, B0); PG8_MMA(1, 1, At, B1); PG8_BAR; PG8_SCHED;
	s_add_i32 s58, 0, 0x18000
	s_add_i32 s59, 0, 0x1c000
	v_add_u32_e32 v140, s58, v243
	v_add_u32_e32 v156, s59, v243
	ds_read_b128 v[120:123], v140
	ds_read_b128 v[128:131], v140 offset:1024
	ds_read_b128 v[136:139], v140 offset:2048
	ds_read_b128 v[140:143], v140 offset:3072
	ds_read_b128 v[144:147], v156
	ds_read_b128 v[148:151], v156 offset:1024
	ds_read_b128 v[152:155], v156 offset:2048
	ds_read_b128 v[156:159], v156 offset:3072
	s_add_u32 s36, s36, 0x40000
	s_addc_u32 s37, s37, 0
	s_mov_b32 m0, s43
	ds_read_b128 v[160:163], v247 offset:32768
	ds_read_b128 v[164:167], v247 offset:33792
	ds_read_b128 v[168:171], v247 offset:34816
	ds_read_b128 v[172:175], v247 offset:35840
	ds_read_b128 v[176:179], v247 offset:36864
	ds_read_b128 v[180:183], v247 offset:37888
	ds_read_b128 v[184:187], v247 offset:38912
	ds_read_b128 v[188:191], v247 offset:39936
	global_load_lds_dwordx4 v192, s[36:37]
	v_lshl_add_u64 v[212:213], s[36:37], 0, v[196:197]
	s_mov_b32 m0, s44
	s_nop 0
	global_load_lds_dwordx4 v[212:213], off
	s_waitcnt vmcnt(8)
	s_waitcnt lgkmcnt(0)
	s_setprio 1
	s_barrier
	v_mfma_f32_16x16x32_bf16 v[132:135], v[120:123], v[160:163], v[132:135]
	v_mfma_f32_16x16x32_bf16 v[124:127], v[136:139], v[160:163], v[124:127]
	v_mfma_f32_16x16x32_bf16 v[108:111], v[120:123], v[168:171], v[108:111]
	v_mfma_f32_16x16x32_bf16 v[104:107], v[136:139], v[168:171], v[104:107]
	v_mfma_f32_16x16x32_bf16 v[92:95], v[120:123], v[176:179], v[92:95]
	v_mfma_f32_16x16x32_bf16 v[88:91], v[136:139], v[176:179], v[88:91]
	v_mfma_f32_16x16x32_bf16 v[76:79], v[120:123], v[184:187], v[76:79]
	v_mfma_f32_16x16x32_bf16 v[72:75], v[136:139], v[184:187], v[72:75]
	v_mfma_f32_16x16x32_bf16 v[132:135], v[128:131], v[164:167], v[132:135]
	v_mfma_f32_16x16x32_bf16 v[124:127], v[140:143], v[164:167], v[124:127]
	v_mfma_f32_16x16x32_bf16 v[108:111], v[128:131], v[172:175], v[108:111]
	v_mfma_f32_16x16x32_bf16 v[104:107], v[140:143], v[172:175], v[104:107]
	v_mfma_f32_16x16x32_bf16 v[92:95], v[128:131], v[180:183], v[92:95]
	v_mfma_f32_16x16x32_bf16 v[88:91], v[140:143], v[180:183], v[88:91]
	v_mfma_f32_16x16x32_bf16 v[76:79], v[128:131], v[188:191], v[76:79]
	v_mfma_f32_16x16x32_bf16 v[72:75], v[140:143], v[188:191], v[72:75]
	v_mfma_f32_16x16x32_bf16 v[116:119], v[144:147], v[160:163], v[116:119]
	v_mfma_f32_16x16x32_bf16 v[112:115], v[152:155], v[160:163], v[112:115]
	v_mfma_f32_16x16x32_bf16 v[100:103], v[144:147], v[168:171], v[100:103]
	v_mfma_f32_16x16x32_bf16 v[96:99], v[152:155], v[168:171], v[96:99]
	v_mfma_f32_16x16x32_bf16 v[84:87], v[144:147], v[176:179], v[84:87]
	v_mfma_f32_16x16x32_bf16 v[80:83], v[152:155], v[176:179], v[80:83]
	v_mfma_f32_16x16x32_bf16 v[68:71], v[144:147], v[184:187], v[68:71]
	v_mfma_f32_16x16x32_bf16 v[64:67], v[152:155], v[184:187], v[64:67]
	v_mfma_f32_16x16x32_bf16 v[116:119], v[148:151], v[164:167], v[116:119]
	v_mfma_f32_16x16x32_bf16 v[112:115], v[156:159], v[164:167], v[112:115]
	v_mfma_f32_16x16x32_bf16 v[100:103], v[148:151], v[172:175], v[100:103]
	v_mfma_f32_16x16x32_bf16 v[96:99], v[156:159], v[172:175], v[96:99]
	v_mfma_f32_16x16x32_bf16 v[84:87], v[148:151], v[180:183], v[84:87]
	v_mfma_f32_16x16x32_bf16 v[80:83], v[156:159], v[180:183], v[80:83]
	v_mfma_f32_16x16x32_bf16 v[68:71], v[148:151], v[188:191], v[68:71]
	s_setprio 0
	v_mfma_f32_16x16x32_bf16 v[64:67], v[156:159], v[188:191], v[64:67]
	s_barrier
	s_add_i32 s36, s58, s40
	v_lshl_add_u64 v[204:205], v[204:205], 0, s[16:17]
	s_mov_b32 m0, s36
	ds_read_b128 v[160:163], v247 offset:49152
	ds_read_b128 v[164:167], v247 offset:50176
	ds_read_b128 v[168:171], v247 offset:51200
	ds_read_b128 v[172:175], v247 offset:52224
	ds_read_b128 v[176:179], v247 offset:53248
	ds_read_b128 v[180:183], v247 offset:54272
	ds_read_b128 v[184:187], v247 offset:55296
	ds_read_b128 v[188:191], v247 offset:56320
	global_load_lds_dwordx4 v[204:205], off
	s_add_i32 m0, s36, 0x2000
	s_add_u32 s34, s34, 0x40080
	v_lshl_add_u64 v[204:205], v[206:207], 0, s[16:17]
	s_addc_u32 s35, s35, 0
	s_add_i32 s36, s59, s40
	global_load_lds_dwordx4 v[204:205], off
	s_mov_b32 m0, s36
	s_nop 0
	global_load_lds_dwordx4 v194, s[34:35]
	s_add_i32 m0, s36, 0x2000
	s_nop 0
	global_load_lds_dwordx4 v198, s[34:35]
	v_lshl_add_u64 v[204:205], v[208:209], 0, s[16:17]
	s_mov_b32 m0, s46
	s_nop 0
	global_load_lds_dwordx4 v[204:205], off
	v_lshl_add_u64 v[204:205], v[210:211], 0, s[16:17]
	s_mov_b32 m0, s47
	s_nop 0
	global_load_lds_dwordx4 v[204:205], off
	s_waitcnt vmcnt(8)
	s_waitcnt lgkmcnt(0)
	s_setprio 1
	s_barrier
	v_mfma_f32_16x16x32_bf16 v[60:63], v[120:123], v[160:163], v[60:63]
	v_mfma_f32_16x16x32_bf16 v[56:59], v[136:139], v[160:163], v[56:59]
	v_mfma_f32_16x16x32_bf16 v[44:47], v[120:123], v[168:171], v[44:47]
	v_mfma_f32_16x16x32_bf16 v[40:43], v[136:139], v[168:171], v[40:43]
	v_mfma_f32_16x16x32_bf16 v[28:31], v[120:123], v[176:179], v[28:31]
	v_mfma_f32_16x16x32_bf16 v[24:27], v[136:139], v[176:179], v[24:27]
	v_mfma_f32_16x16x32_bf16 v[12:15], v[120:123], v[184:187], v[12:15]
	v_mfma_f32_16x16x32_bf16 v[8:11], v[136:139], v[184:187], v[8:11]
	v_mfma_f32_16x16x32_bf16 v[60:63], v[128:131], v[164:167], v[60:63]
	v_mfma_f32_16x16x32_bf16 v[56:59], v[140:143], v[164:167], v[56:59]
	v_mfma_f32_16x16x32_bf16 v[44:47], v[128:131], v[172:175], v[44:47]
	v_mfma_f32_16x16x32_bf16 v[40:43], v[140:143], v[172:175], v[40:43]
	v_mfma_f32_16x16x32_bf16 v[28:31], v[128:131], v[180:183], v[28:31]
	v_mfma_f32_16x16x32_bf16 v[24:27], v[140:143], v[180:183], v[24:27]
	v_mfma_f32_16x16x32_bf16 v[12:15], v[128:131], v[188:191], v[12:15]
	v_mfma_f32_16x16x32_bf16 v[8:11], v[140:143], v[188:191], v[8:11]
	v_mfma_f32_16x16x32_bf16 v[52:55], v[144:147], v[160:163], v[52:55]
	v_mfma_f32_16x16x32_bf16 v[48:51], v[152:155], v[160:163], v[48:51]
	v_mfma_f32_16x16x32_bf16 v[36:39], v[144:147], v[168:171], v[36:39]
	v_mfma_f32_16x16x32_bf16 v[32:35], v[152:155], v[168:171], v[32:35]
	v_mfma_f32_16x16x32_bf16 v[20:23], v[144:147], v[176:179], v[20:23]
	v_mfma_f32_16x16x32_bf16 v[16:19], v[152:155], v[176:179], v[16:19]
	v_mfma_f32_16x16x32_bf16 v[4:7], v[144:147], v[184:187], v[4:7]
	v_mfma_f32_16x16x32_bf16 v[0:3], v[152:155], v[184:187], v[0:3]
	v_mfma_f32_16x16x32_bf16 v[52:55], v[148:151], v[164:167], v[52:55]
	v_mfma_f32_16x16x32_bf16 v[48:51], v[156:159], v[164:167], v[48:51]
	v_mfma_f32_16x16x32_bf16 v[36:39], v[148:151], v[172:175], v[36:39]
	v_mfma_f32_16x16x32_bf16 v[32:35], v[156:159], v[172:175], v[32:35]
	v_mfma_f32_16x16x32_bf16 v[20:23], v[148:151], v[180:183], v[20:23]
	v_mfma_f32_16x16x32_bf16 v[16:19], v[156:159], v[180:183], v[16:19]
	v_mfma_f32_16x16x32_bf16 v[4:7], v[148:151], v[188:191], v[4:7]
	s_setprio 0
	v_mfma_f32_16x16x32_bf16 v[0:3], v[156:159], v[188:191], v[0:3]
	s_barrier
	s_add_i32 s57, s57, 2
	s_add_u32 s30, s30, 0x100
	s_addc_u32 s31, s31, 0
	s_add_u32 s55, s55, 0x100
	s_addc_u32 s56, s56, 0
	s_cmp_gt_u32 s57, 13
	s_cbranch_scc0 .LBB0_960
	s_and_b64 vcc, exec, s[18:19]
	s_cbranch_vccz .LBB0_963
	s_barrier

; #define PG8_STAGE(bufoff, gbase, voff) do { _Pragma("unroll") for (int _i = 0; _i < 2; ++_i) \
;         __builtin_amdgcn_global_load_lds((const unsigned*)((const char*)(gbase) + (voff)[_i]), (PG8_LAS unsigned*)(lds + (bufoff) + ldsw + _i * 8192), 16, 0, 0); } while (0)
; #define PG8_LDA(dst, b, h) do { _Pragma("unroll") for (int m = 0; m < 4; ++m) _Pragma("unroll") for (int k = 0; k < 2; ++k) dst[m][k] = *(const PG8_LAS bf16x8*)(lds + PG8_SA(b, h) + aoff + m * 2048 + k * 1024); } while (0)
; #define PG8_LDB(dst, b, h) do { _Pragma("unroll") for (int n = 0; n < 2; ++n) _Pragma("unroll") for (int k = 0; k < 2; ++k) dst[n][k] = *(const PG8_LAS bf16x8*)(lds + PG8_SB(b, h) + boff + n * 2048 + k * 1024); } while (0)
; #define PG8_WAIT_V(n) asm volatile("s_waitcnt vmcnt(" #n ")" ::: "memory")
; #define PG8_WAIT_L(n) asm volatile("s_waitcnt lgkmcnt(" #n ")" ::: "memory")
; #define PG8_BAR __builtin_amdgcn_s_barrier()
; #define PG8_SCHED __builtin_amdgcn_sched_barrier(0)
; template <class Epi, class Sched, bool ALIGN_EPI = false, bool SP2 = false>
; __device__ __forceinline__ void gemm_phase(PG8_LAS unsigned char* lds, const Gemm g, const Sched& S, const Epi& E) {
;     ...
;         const bool has_next = S.next(ui + 1, nxt);
;         const char* nA = has_next ? (const char*)g.A + (size_t)nxt.pm * tstep : cA; const char* nB = has_next ? (const char*)g.Bt + (size_t)nxt.pn * tstep : cB;
;         for (int t = 0; t < nt; t += 2) {
;             const bool last = (t == nt - 2);
;             const char* a1 = cA + (size_t)(t + 1) * kstep;
;             const char* a2 = last ? nA : cA + (size_t)(t + 2) * kstep; const char* b2 = last ? nB : cB + (size_t)(t + 2) * kstep;
;             const char* a3 = a2 + kstep; const char* b3 = b2 + kstep;
;             if (last && has_next) S.a_ready(nxt, ui + 1);
;             if constexpr (SP2) {
;             PG8_LDB(B0, 0, 0); PG8_LDB(B1, 0, 1); PG8_SCHED; PG8_LDA(At, 0, 0); PG8_STAGE(PG8_SA(1, 1), a1 + hstep, voffA);
;             PG8_WAIT_V(8); PG8_WAIT_L(0); PG8_BAR; PG8_MMA(0, 0, At, B0); PG8_MMA(0, 1, At, B1); PG8_BAR; PG8_SCHED;
;             PG8_LDA(At, 0, 1); PG8_STAGE(PG8_SB(0, 0), b2, voffB); PG8_STAGE(PG8_SB(0, 1), b2 + hstep, voffB); PG8_STAGE(PG8_SA(0, 0), a2, voffA);
;             PG8_WAIT_V(8); PG8_WAIT_L(0); PG8_BAR; PG8_MMA(1, 0, At, B0); PG8_MMA(1, 1, At, B1); PG8_BAR; PG8_SCHED;
.LBB0_1048:
	s_ashr_i32 s17, s16, 31
	s_lshl_b64 s[18:19], s[16:17], 19
	s_add_u32 s18, s34, s18
	s_addc_u32 s19, s35, s19
	s_and_b64 s[20:21], s[0:1], exec
	s_cselect_b32 s17, s19, s25
	s_cselect_b32 s50, s18, s24
	s_ashr_i32 s15, s14, 31
	s_lshl_b64 s[20:21], s[14:15], 19
	s_add_u32 s20, s36, s20
	s_addc_u32 s21, s37, s21
	s_and_b64 s[28:29], s[0:1], exec
	s_cselect_b32 s15, s21, s27
	s_cselect_b32 s51, s20, s26
	s_add_u32 s24, s24, 0x40080
	s_addc_u32 s25, s25, 0
	s_add_u32 s52, s26, 0x100
	s_addc_u32 s53, s27, 0
	s_mov_b32 s54, -2
	s_add_u32 s26, s24, 0xfffc0080
	s_addc_u32 s27, s25, -1
	s_cmp_eq_u32 s54, 12
	s_cselect_b32 s29, s17, s27
	s_cselect_b32 s28, s50, s26
	s_cselect_b32 s27, s15, s53
	s_cselect_b32 s26, s51, s52
	s_add_i32 m0, s23, 0xc000
	s_nop 0
	global_load_lds_dwordx4 v136, s[24:25]
	s_add_i32 m0, s23, 0xe000
	s_nop 0
	global_load_lds_dwordx4 v138, s[24:25]
	s_waitcnt vmcnt(8)
	s_waitcnt lgkmcnt(0)
	s_setprio 1
	s_barrier
	v_mfma_f32_16x16x32_bf16 v[124:127], v[152:155], v[184:187], 0
	v_mfma_f32_16x16x32_bf16 v[120:123], v[160:163], v[184:187], 0
	v_mfma_f32_16x16x32_bf16 v[108:111], v[152:155], v[192:195], 0
	v_mfma_f32_16x16x32_bf16 v[104:107], v[160:163], v[192:195], 0
	v_mfma_f32_16x16x32_bf16 v[92:95], v[152:155], v[200:203], 0
	v_mfma_f32_16x16x32_bf16 v[88:91], v[160:163], v[200:203], 0
	v_mfma_f32_16x16x32_bf16 v[76:79], v[152:155], v[208:211], 0
	v_mfma_f32_16x16x32_bf16 v[72:75], v[160:163], v[208:211], 0
	v_mfma_f32_16x16x32_bf16 v[124:127], v[156:159], v[188:191], v[124:127]
	v_mfma_f32_16x16x32_bf16 v[120:123], v[164:167], v[188:191], v[120:123]
	v_mfma_f32_16x16x32_bf16 v[108:111], v[156:159], v[196:199], v[108:111]
	v_mfma_f32_16x16x32_bf16 v[104:107], v[164:167], v[196:199], v[104:107]
	v_mfma_f32_16x16x32_bf16 v[92:95], v[156:159], v[204:207], v[92:95]
	v_mfma_f32_16x16x32_bf16 v[88:91], v[164:167], v[204:207], v[88:91]
	v_mfma_f32_16x16x32_bf16 v[76:79], v[156:159], v[212:215], v[76:79]
	v_mfma_f32_16x16x32_bf16 v[72:75], v[164:167], v[212:215], v[72:75]
	v_mfma_f32_16x16x32_bf16 v[116:119], v[168:171], v[184:187], 0
	v_mfma_f32_16x16x32_bf16 v[112:115], v[176:179], v[184:187], 0
	v_mfma_f32_16x16x32_bf16 v[100:103], v[168:171], v[192:195], 0
	v_mfma_f32_16x16x32_bf16 v[96:99], v[176:179], v[192:195], 0
	v_mfma_f32_16x16x32_bf16 v[84:87], v[168:171], v[200:203], 0
	v_mfma_f32_16x16x32_bf16 v[80:83], v[176:179], v[200:203], 0
	v_mfma_f32_16x16x32_bf16 v[68:71], v[168:171], v[208:211], 0
	v_mfma_f32_16x16x32_bf16 v[64:67], v[176:179], v[208:211], 0
	v_mfma_f32_16x16x32_bf16 v[116:119], v[172:175], v[188:191], v[116:119]
	v_mfma_f32_16x16x32_bf16 v[112:115], v[180:183], v[188:191], v[112:115]
	v_mfma_f32_16x16x32_bf16 v[100:103], v[172:175], v[196:199], v[100:103]
	v_mfma_f32_16x16x32_bf16 v[96:99], v[180:183], v[196:199], v[96:99]
	v_mfma_f32_16x16x32_bf16 v[84:87], v[172:175], v[204:207], v[84:87]
	v_mfma_f32_16x16x32_bf16 v[80:83], v[180:183], v[204:207], v[80:83]
	v_mfma_f32_16x16x32_bf16 v[68:71], v[172:175], v[212:215], v[68:71]
	s_setprio 0
	v_mfma_f32_16x16x32_bf16 v[64:67], v[180:183], v[212:215], v[64:67]
	s_barrier
	s_add_i32 s55, s44, s33
	v_lshl_add_u64 v[216:217], s[26:27], 0, v[132:133]
	s_mov_b32 m0, s55
	ds_read_b128 v[184:187], v150 offset:16384
	ds_read_b128 v[188:191], v150 offset:17408
	ds_read_b128 v[192:195], v150 offset:18432
	ds_read_b128 v[196:199], v150 offset:19456
	ds_read_b128 v[200:203], v150 offset:20480
	ds_read_b128 v[204:207], v150 offset:21504
	ds_read_b128 v[208:211], v150 offset:22528
	ds_read_b128 v[212:215], v150 offset:23552
	global_load_lds_dwordx4 v[216:217], off
	s_add_i32 m0, s55, 0x2000
	s_add_u32 s56, s26, 0x40000
	v_lshl_add_u64 v[218:219], s[26:27], 0, v[128:129]
	s_addc_u32 s57, s27, 0
	s_add_i32 s55, s45, s33
	global_load_lds_dwordx4 v[218:219], off
	s_mov_b32 m0, s55
	v_lshl_add_u64 v[222:223], s[28:29], 0, v[130:131]
	global_load_lds_dwordx4 v132, s[56:57]
	s_add_i32 m0, s55, 0x2000
	s_nop 0
	global_load_lds_dwordx4 v128, s[56:57]
	v_lshl_add_u64 v[220:221], s[28:29], 0, v[134:135]
	s_mov_b32 m0, s23
	s_nop 0
	global_load_lds_dwordx4 v[220:221], off
	s_mov_b32 m0, s39
	s_nop 0
	global_load_lds_dwordx4 v[222:223], off
	s_waitcnt vmcnt(8)
	s_waitcnt lgkmcnt(0)
	s_setprio 1
	s_barrier
	v_mfma_f32_16x16x32_bf16 v[60:63], v[152:155], v[184:187], 0
	v_mfma_f32_16x16x32_bf16 v[56:59], v[160:163], v[184:187], 0
	v_mfma_f32_16x16x32_bf16 v[44:47], v[152:155], v[192:195], 0
	v_mfma_f32_16x16x32_bf16 v[40:43], v[160:163], v[192:195], 0
	v_mfma_f32_16x16x32_bf16 v[28:31], v[152:155], v[200:203], 0
	v_mfma_f32_16x16x32_bf16 v[24:27], v[160:163], v[200:203], 0
	v_mfma_f32_16x16x32_bf16 v[12:15], v[152:155], v[208:211], 0
	v_mfma_f32_16x16x32_bf16 v[8:11], v[160:163], v[208:211], 0
	v_mfma_f32_16x16x32_bf16 v[60:63], v[156:159], v[188:191], v[60:63]
	v_mfma_f32_16x16x32_bf16 v[56:59], v[164:167], v[188:191], v[56:59]
	v_mfma_f32_16x16x32_bf16 v[44:47], v[156:159], v[196:199], v[44:47]
	v_mfma_f32_16x16x32_bf16 v[40:43], v[164:167], v[196:199], v[40:43]
	v_mfma_f32_16x16x32_bf16 v[28:31], v[156:159], v[204:207], v[28:31]
	v_mfma_f32_16x16x32_bf16 v[24:27], v[164:167], v[204:207], v[24:27]
	v_mfma_f32_16x16x32_bf16 v[12:15], v[156:159], v[212:215], v[12:15]
	v_mfma_f32_16x16x32_bf16 v[8:11], v[164:167], v[212:215], v[8:11]
	v_mfma_f32_16x16x32_bf16 v[52:55], v[168:171], v[184:187], 0
	v_mfma_f32_16x16x32_bf16 v[48:51], v[176:179], v[184:187], 0
	v_mfma_f32_16x16x32_bf16 v[36:39], v[168:171], v[192:195], 0
	v_mfma_f32_16x16x32_bf16 v[32:35], v[176:179], v[192:195], 0
	v_mfma_f32_16x16x32_bf16 v[20:23], v[168:171], v[200:203], 0
	v_mfma_f32_16x16x32_bf16 v[16:19], v[176:179], v[200:203], 0
	v_mfma_f32_16x16x32_bf16 v[4:7], v[168:171], v[208:211], 0
	v_mfma_f32_16x16x32_bf16 v[0:3], v[176:179], v[208:211], 0
	v_mfma_f32_16x16x32_bf16 v[52:55], v[172:175], v[188:191], v[52:55]
	v_mfma_f32_16x16x32_bf16 v[48:51], v[180:183], v[188:191], v[48:51]
	v_mfma_f32_16x16x32_bf16 v[36:39], v[172:175], v[196:199], v[36:39]
	v_mfma_f32_16x16x32_bf16 v[32:35], v[180:183], v[196:199], v[32:35]
	v_mfma_f32_16x16x32_bf16 v[20:23], v[172:175], v[204:207], v[20:23]
	v_mfma_f32_16x16x32_bf16 v[16:19], v[180:183], v[204:207], v[16:19]
	v_mfma_f32_16x16x32_bf16 v[4:7], v[172:175], v[212:215], v[4:7]
	s_setprio 0
	v_mfma_f32_16x16x32_bf16 v[0:3], v[180:183], v[212:215], v[0:3]
	s_barrier
; #define PG8_STAGE(bufoff, gbase, voff) do { _Pragma("unroll") for (int _i = 0; _i < 2; ++_i) \
;         __builtin_amdgcn_global_load_lds((const unsigned*)((const char*)(gbase) + (voff)[_i]), (PG8_LAS unsigned*)(lds + (bufoff) + ldsw + _i * 8192), 16, 0, 0); } while (0)
; #define PG8_LDA(dst, b, h) do { _Pragma("unroll") for (int m = 0; m < 4; ++m) _Pragma("unroll") for (int k = 0; k < 2; ++k) dst[m][k] = *(const PG8_LAS bf16x8*)(lds + PG8_SA(b, h) + aoff + m * 2048 + k * 1024); } while (0)
; #define PG8_LDB(dst, b, h) do { _Pragma("unroll") for (int n = 0; n < 2; ++n) _Pragma("unroll") for (int k = 0; k < 2; ++k) dst[n][k] = *(const PG8_LAS bf16x8*)(lds + PG8_SB(b, h) + boff + n * 2048 + k * 1024); } while (0)
; #define PG8_MMA(ai, bj, At, Bt) do { __builtin_amdgcn_s_setprio(1); _Pragma("unroll") for (int m = 0; m < 4; ++m) _Pragma("unroll") for (int n = 0; n < 2; ++n) _Pragma("unroll") for (int k = 0; k < 2; ++k) \
;         acc[ai][bj][m][n] = __builtin_amdgcn_mfma_f32_16x16x32_bf16(Bt[n][k], At[m][k], acc[ai][bj][m][n], 0, 0, 0); __builtin_amdgcn_s_setprio(0); } while (0)
; #define PG8_WAIT_V(n) asm volatile("s_waitcnt vmcnt(" #n ")" ::: "memory")
; #define PG8_WAIT_L(n) asm volatile("s_waitcnt lgkmcnt(" #n ")" ::: "memory")
; #define PG8_BAR __builtin_amdgcn_s_barrier()
; #define PG8_SCHED __builtin_amdgcn_sched_barrier(0)
; template <class Epi, class Sched, bool ALIGN_EPI = false, bool SP2 = false>
; __device__ __forceinline__ void gemm_phase(PG8_LAS unsigned char* lds, const Gemm g, const Sched& S, const Epi& E) {
;     ...
;         for (int t = 0; t < nt; t += 2) {
;             const bool last = (t == nt - 2);
;     ...
;             PG8_LDB(B0, 1, 0); PG8_LDB(B1, 1, 1); PG8_SCHED; PG8_LDA(At, 1, 0); PG8_STAGE(PG8_SA(0, 1), a2 + hstep, voffA);
;             PG8_WAIT_V(8); PG8_WAIT_L(0); PG8_BAR; PG8_MMA(0, 0, At, B0); PG8_MMA(0, 1, At, B1); PG8_BAR; PG8_SCHED;
;             PG8_LDA(At, 1, 1); PG8_STAGE(PG8_SB(1, 0), b3, voffB); PG8_STAGE(PG8_SB(1, 1), b3 + hstep, voffB); PG8_STAGE(PG8_SA(1, 0), a3, voffA);
;             PG8_WAIT_V(8); PG8_WAIT_L(0); PG8_BAR; PG8_MMA(1, 0, At, B0); PG8_MMA(1, 1, At, B1); PG8_BAR; PG8_SCHED;
	s_add_i32 s55, 0, 0x18000
	v_add_u32_e32 v151, s55, v145
	s_add_i32 s56, 0, 0x1c000
	ds_read_b128 v[152:155], v151
	ds_read_b128 v[156:159], v151 offset:1024
	ds_read_b128 v[160:163], v151 offset:2048
	ds_read_b128 v[164:167], v151 offset:3072
	v_add_u32_e32 v151, s56, v145
	ds_read_b128 v[168:171], v151
	ds_read_b128 v[172:175], v151 offset:1024
	ds_read_b128 v[176:179], v151 offset:2048
	ds_read_b128 v[180:183], v151 offset:3072
	s_add_u32 s28, s28, 0x40000
	s_addc_u32 s29, s29, 0
	s_mov_b32 m0, s40
	ds_read_b128 v[184:187], v150 offset:32768
	ds_read_b128 v[188:191], v150 offset:33792
	ds_read_b128 v[192:195], v150 offset:34816
	ds_read_b128 v[196:199], v150 offset:35840
	ds_read_b128 v[200:203], v150 offset:36864
	ds_read_b128 v[204:207], v150 offset:37888
	ds_read_b128 v[208:211], v150 offset:38912
	ds_read_b128 v[212:215], v150 offset:39936
	global_load_lds_dwordx4 v134, s[28:29]
	s_mov_b32 m0, s41
	s_nop 0
	global_load_lds_dwordx4 v130, s[28:29]
	s_waitcnt vmcnt(8)
	s_waitcnt lgkmcnt(0)
	s_setprio 1
	s_barrier
	v_mfma_f32_16x16x32_bf16 v[124:127], v[152:155], v[184:187], v[124:127]
	v_mfma_f32_16x16x32_bf16 v[120:123], v[160:163], v[184:187], v[120:123]
	v_mfma_f32_16x16x32_bf16 v[108:111], v[152:155], v[192:195], v[108:111]
	v_mfma_f32_16x16x32_bf16 v[104:107], v[160:163], v[192:195], v[104:107]
	v_mfma_f32_16x16x32_bf16 v[92:95], v[152:155], v[200:203], v[92:95]
	v_mfma_f32_16x16x32_bf16 v[88:91], v[160:163], v[200:203], v[88:91]
	v_mfma_f32_16x16x32_bf16 v[76:79], v[152:155], v[208:211], v[76:79]
	v_mfma_f32_16x16x32_bf16 v[72:75], v[160:163], v[208:211], v[72:75]
	v_mfma_f32_16x16x32_bf16 v[124:127], v[156:159], v[188:191], v[124:127]
	v_mfma_f32_16x16x32_bf16 v[120:123], v[164:167], v[188:191], v[120:123]
	v_mfma_f32_16x16x32_bf16 v[108:111], v[156:159], v[196:199], v[108:111]
	v_mfma_f32_16x16x32_bf16 v[104:107], v[164:167], v[196:199], v[104:107]
	v_mfma_f32_16x16x32_bf16 v[92:95], v[156:159], v[204:207], v[92:95]
	v_mfma_f32_16x16x32_bf16 v[88:91], v[164:167], v[204:207], v[88:91]
	v_mfma_f32_16x16x32_bf16 v[76:79], v[156:159], v[212:215], v[76:79]
	v_mfma_f32_16x16x32_bf16 v[72:75], v[164:167], v[212:215], v[72:75]
	v_mfma_f32_16x16x32_bf16 v[116:119], v[168:171], v[184:187], v[116:119]
	v_mfma_f32_16x16x32_bf16 v[112:115], v[176:179], v[184:187], v[112:115]
	v_mfma_f32_16x16x32_bf16 v[100:103], v[168:171], v[192:195], v[100:103]
	v_mfma_f32_16x16x32_bf16 v[96:99], v[176:179], v[192:195], v[96:99]
	v_mfma_f32_16x16x32_bf16 v[84:87], v[168:171], v[200:203], v[84:87]
	v_mfma_f32_16x16x32_bf16 v[80:83], v[176:179], v[200:203], v[80:83]
	v_mfma_f32_16x16x32_bf16 v[68:71], v[168:171], v[208:211], v[68:71]
	v_mfma_f32_16x16x32_bf16 v[64:67], v[176:179], v[208:211], v[64:67]
	v_mfma_f32_16x16x32_bf16 v[116:119], v[172:175], v[188:191], v[116:119]
	v_mfma_f32_16x16x32_bf16 v[112:115], v[180:183], v[188:191], v[112:115]
	v_mfma_f32_16x16x32_bf16 v[100:103], v[172:175], v[196:199], v[100:103]
	v_mfma_f32_16x16x32_bf16 v[96:99], v[180:183], v[196:199], v[96:99]
	v_mfma_f32_16x16x32_bf16 v[84:87], v[172:175], v[204:207], v[84:87]
	v_mfma_f32_16x16x32_bf16 v[80:83], v[180:183], v[204:207], v[80:83]
	v_mfma_f32_16x16x32_bf16 v[68:71], v[172:175], v[212:215], v[68:71]
	s_setprio 0
	v_mfma_f32_16x16x32_bf16 v[64:67], v[180:183], v[212:215], v[64:67]
	s_barrier
	s_add_i32 s28, s55, s33
	v_lshl_add_u64 v[216:217], v[216:217], 0, s[8:9]
	s_mov_b32 m0, s28
	ds_read_b128 v[184:187], v150 offset:49152
	ds_read_b128 v[188:191], v150 offset:50176
	ds_read_b128 v[192:195], v150 offset:51200
	ds_read_b128 v[196:199], v150 offset:52224
	ds_read_b128 v[200:203], v150 offset:53248
	ds_read_b128 v[204:207], v150 offset:54272
	ds_read_b128 v[208:211], v150 offset:55296
	ds_read_b128 v[212:215], v150 offset:56320
	global_load_lds_dwordx4 v[216:217], off
	s_add_i32 m0, s28, 0x2000
	s_add_u32 s26, s26, 0x40080
	v_lshl_add_u64 v[216:217], v[218:219], 0, s[8:9]
	s_addc_u32 s27, s27, 0
	s_add_i32 s28, s56, s33
	global_load_lds_dwordx4 v[216:217], off
	s_mov_b32 m0, s28
	s_nop 0
	global_load_lds_dwordx4 v132, s[26:27]
	s_add_i32 m0, s28, 0x2000
	s_nop 0
	global_load_lds_dwordx4 v128, s[26:27]
	v_lshl_add_u64 v[216:217], v[220:221], 0, s[8:9]
	s_mov_b32 m0, s42
	s_nop 0
	global_load_lds_dwordx4 v[216:217], off
	v_lshl_add_u64 v[216:217], v[222:223], 0, s[8:9]
	s_mov_b32 m0, s43
	s_nop 0
	global_load_lds_dwordx4 v[216:217], off
	s_waitcnt vmcnt(8)
	s_waitcnt lgkmcnt(0)
	s_setprio 1
	s_barrier
	v_mfma_f32_16x16x32_bf16 v[60:63], v[152:155], v[184:187], v[60:63]
	v_mfma_f32_16x16x32_bf16 v[56:59], v[160:163], v[184:187], v[56:59]
	v_mfma_f32_16x16x32_bf16 v[44:47], v[152:155], v[192:195], v[44:47]
	v_mfma_f32_16x16x32_bf16 v[40:43], v[160:163], v[192:195], v[40:43]
	v_mfma_f32_16x16x32_bf16 v[28:31], v[152:155], v[200:203], v[28:31]
	v_mfma_f32_16x16x32_bf16 v[24:27], v[160:163], v[200:203], v[24:27]
	v_mfma_f32_16x16x32_bf16 v[12:15], v[152:155], v[208:211], v[12:15]
	v_mfma_f32_16x16x32_bf16 v[8:11], v[160:163], v[208:211], v[8:11]
	v_mfma_f32_16x16x32_bf16 v[60:63], v[156:159], v[188:191], v[60:63]
	v_mfma_f32_16x16x32_bf16 v[56:59], v[164:167], v[188:191], v[56:59]
	v_mfma_f32_16x16x32_bf16 v[44:47], v[156:159], v[196:199], v[44:47]
	v_mfma_f32_16x16x32_bf16 v[40:43], v[164:167], v[196:199], v[40:43]
	v_mfma_f32_16x16x32_bf16 v[28:31], v[156:159], v[204:207], v[28:31]
	v_mfma_f32_16x16x32_bf16 v[24:27], v[164:167], v[204:207], v[24:27]
	v_mfma_f32_16x16x32_bf16 v[12:15], v[156:159], v[212:215], v[12:15]
	v_mfma_f32_16x16x32_bf16 v[8:11], v[164:167], v[212:215], v[8:11]
	v_mfma_f32_16x16x32_bf16 v[52:55], v[168:171], v[184:187], v[52:55]
	v_mfma_f32_16x16x32_bf16 v[48:51], v[176:179], v[184:187], v[48:51]
	v_mfma_f32_16x16x32_bf16 v[36:39], v[168:171], v[192:195], v[36:39]
	v_mfma_f32_16x16x32_bf16 v[32:35], v[176:179], v[192:195], v[32:35]
	v_mfma_f32_16x16x32_bf16 v[20:23], v[168:171], v[200:203], v[20:23]
	v_mfma_f32_16x16x32_bf16 v[16:19], v[176:179], v[200:203], v[16:19]
	v_mfma_f32_16x16x32_bf16 v[4:7], v[168:171], v[208:211], v[4:7]
	v_mfma_f32_16x16x32_bf16 v[0:3], v[176:179], v[208:211], v[0:3]
	v_mfma_f32_16x16x32_bf16 v[52:55], v[172:175], v[188:191], v[52:55]
	v_mfma_f32_16x16x32_bf16 v[48:51], v[180:183], v[188:191], v[48:51]
	v_mfma_f32_16x16x32_bf16 v[36:39], v[172:175], v[196:199], v[36:39]
	v_mfma_f32_16x16x32_bf16 v[32:35], v[180:183], v[196:199], v[32:35]
	v_mfma_f32_16x16x32_bf16 v[20:23], v[172:175], v[204:207], v[20:23]
	v_mfma_f32_16x16x32_bf16 v[16:19], v[180:183], v[204:207], v[16:19]
	v_mfma_f32_16x16x32_bf16 v[4:7], v[172:175], v[212:215], v[4:7]
	s_setprio 0
	v_mfma_f32_16x16x32_bf16 v[0:3], v[180:183], v[212:215], v[0:3]
	s_barrier
	s_add_i32 s54, s54, 2
	s_add_u32 s24, s24, 0x100
	s_addc_u32 s25, s25, 0
	s_add_u32 s52, s52, 0x100
	s_addc_u32 s53, s53, 0
	s_cmp_gt_u32 s54, 13

; #define PG8_STAGE(bufoff, gbase, voff) do { _Pragma("unroll") for (int _i = 0; _i < 2; ++_i) \
;         __builtin_amdgcn_global_load_lds((const unsigned*)((const char*)(gbase) + (voff)[_i]), (PG8_LAS unsigned*)(lds + (bufoff) + ldsw + _i * 8192), 16, 0, 0); } while (0)
; #define PG8_LDA(dst, b, h) do { _Pragma("unroll") for (int m = 0; m < 4; ++m) _Pragma("unroll") for (int k = 0; k < 2; ++k) dst[m][k] = *(const PG8_LAS bf16x8*)(lds + PG8_SA(b, h) + aoff + m * 2048 + k * 1024); } while (0)
; #define PG8_LDB(dst, b, h) do { _Pragma("unroll") for (int n = 0; n < 2; ++n) _Pragma("unroll") for (int k = 0; k < 2; ++k) dst[n][k] = *(const PG8_LAS bf16x8*)(lds + PG8_SB(b, h) + boff + n * 2048 + k * 1024); } while (0)
; #define PG8_MMA(ai, bj, At, Bt) do { __builtin_amdgcn_s_setprio(1); _Pragma("unroll") for (int m = 0; m < 4; ++m) _Pragma("unroll") for (int n = 0; n < 2; ++n) _Pragma("unroll") for (int k = 0; k < 2; ++k) \
;         acc[ai][bj][m][n] = __builtin_amdgcn_mfma_f32_16x16x32_bf16(Bt[n][k], At[m][k], acc[ai][bj][m][n], 0, 0, 0); __builtin_amdgcn_s_setprio(0); } while (0)
; #define PG8_WAIT_V(n) asm volatile("s_waitcnt vmcnt(" #n ")" ::: "memory")
; #define PG8_WAIT_L(n) asm volatile("s_waitcnt lgkmcnt(" #n ")" ::: "memory")
; #define PG8_BAR __builtin_amdgcn_s_barrier()
; template <class Epi, class Sched, bool ALIGN_EPI = false, bool SP2 = false>
; __device__ __forceinline__ void gemm_phase(PG8_LAS unsigned char* lds, const Gemm g, const Sched& S, const Epi& E) {
;     ...
;             const char* a1 = cA + (size_t)(t + 1) * kstep;
;             const char* a2 = last ? nA : cA + (size_t)(t + 2) * kstep; const char* b2 = last ? nB : cB + (size_t)(t + 2) * kstep;
;             const char* a3 = a2 + kstep; const char* b3 = b2 + kstep;
;             if (last && has_next) S.a_ready(nxt, ui + 1);
;             if constexpr (SP2) {
;             PG8_LDB(B0, 0, 0); PG8_LDB(B1, 0, 1); PG8_SCHED; PG8_LDA(At, 0, 0); PG8_STAGE(PG8_SA(1, 1), a1 + hstep, voffA);
;             PG8_WAIT_V(8); PG8_WAIT_L(0); PG8_BAR; PG8_MMA(0, 0, At, B0); PG8_MMA(0, 1, At, B1); PG8_BAR; PG8_SCHED;
;             PG8_LDA(At, 0, 1); PG8_STAGE(PG8_SB(0, 0), b2, voffB); PG8_STAGE(PG8_SB(0, 1), b2 + hstep, voffB); PG8_STAGE(PG8_SA(0, 0), a2, voffA);
;             PG8_WAIT_V(8); PG8_WAIT_L(0); PG8_BAR; PG8_MMA(1, 0, At, B0); PG8_MMA(1, 1, At, B1); PG8_BAR; PG8_SCHED;
.LBB0_1129:
	s_add_u32 s24, s24, 0xb0080
	s_addc_u32 s25, s25, 0
	s_add_u32 s51, s26, 0x100
	s_addc_u32 s52, s27, 0
	s_mov_b32 s53, -2
	s_add_u32 s26, s24, 0xfff50080
	s_addc_u32 s27, s25, -1
	s_cmp_eq_u32 s53, 40
	s_cselect_b32 s29, s7, s27
	s_cselect_b32 s28, s6, s26
	s_cselect_b32 s27, s23, s52
	s_cselect_b32 s26, s22, s51
	s_add_i32 m0, s35, 0xc000
	s_nop 0
	global_load_lds_dwordx4 v200, s[24:25]
	s_add_i32 m0, s35, 0xe000
	s_nop 0
	global_load_lds_dwordx4 v202, s[24:25]
	s_waitcnt vmcnt(8)
	s_waitcnt lgkmcnt(0)
	s_setprio 1
	s_barrier
	v_mfma_f32_16x16x32_bf16 v[132:135], v[120:123], v[160:163], 0
	v_mfma_f32_16x16x32_bf16 v[124:127], v[136:139], v[160:163], 0
	v_mfma_f32_16x16x32_bf16 v[108:111], v[120:123], v[168:171], 0
	v_mfma_f32_16x16x32_bf16 v[104:107], v[136:139], v[168:171], 0
	v_mfma_f32_16x16x32_bf16 v[92:95], v[120:123], v[176:179], 0
	v_mfma_f32_16x16x32_bf16 v[88:91], v[136:139], v[176:179], 0
	v_mfma_f32_16x16x32_bf16 v[76:79], v[120:123], v[184:187], 0
	v_mfma_f32_16x16x32_bf16 v[72:75], v[136:139], v[184:187], 0
	v_mfma_f32_16x16x32_bf16 v[132:135], v[128:131], v[164:167], v[132:135]
	v_mfma_f32_16x16x32_bf16 v[124:127], v[140:143], v[164:167], v[124:127]
	v_mfma_f32_16x16x32_bf16 v[108:111], v[128:131], v[172:175], v[108:111]
	v_mfma_f32_16x16x32_bf16 v[104:107], v[140:143], v[172:175], v[104:107]
	v_mfma_f32_16x16x32_bf16 v[92:95], v[128:131], v[180:183], v[92:95]
	v_mfma_f32_16x16x32_bf16 v[88:91], v[140:143], v[180:183], v[88:91]
	v_mfma_f32_16x16x32_bf16 v[76:79], v[128:131], v[188:191], v[76:79]
	v_mfma_f32_16x16x32_bf16 v[72:75], v[140:143], v[188:191], v[72:75]
	v_mfma_f32_16x16x32_bf16 v[116:119], v[144:147], v[160:163], 0
	v_mfma_f32_16x16x32_bf16 v[112:115], v[152:155], v[160:163], 0
	v_mfma_f32_16x16x32_bf16 v[100:103], v[144:147], v[168:171], 0
	v_mfma_f32_16x16x32_bf16 v[96:99], v[152:155], v[168:171], 0
	v_mfma_f32_16x16x32_bf16 v[84:87], v[144:147], v[176:179], 0
	v_mfma_f32_16x16x32_bf16 v[80:83], v[152:155], v[176:179], 0
	v_mfma_f32_16x16x32_bf16 v[68:71], v[144:147], v[184:187], 0
	v_mfma_f32_16x16x32_bf16 v[64:67], v[152:155], v[184:187], 0
	v_mfma_f32_16x16x32_bf16 v[116:119], v[148:151], v[164:167], v[116:119]
	v_mfma_f32_16x16x32_bf16 v[112:115], v[156:159], v[164:167], v[112:115]
	v_mfma_f32_16x16x32_bf16 v[100:103], v[148:151], v[172:175], v[100:103]
	v_mfma_f32_16x16x32_bf16 v[96:99], v[156:159], v[172:175], v[96:99]
	v_mfma_f32_16x16x32_bf16 v[84:87], v[148:151], v[180:183], v[84:87]
	v_mfma_f32_16x16x32_bf16 v[80:83], v[156:159], v[180:183], v[80:83]
	v_mfma_f32_16x16x32_bf16 v[68:71], v[148:151], v[188:191], v[68:71]
	s_setprio 0
	v_mfma_f32_16x16x32_bf16 v[64:67], v[156:159], v[188:191], v[64:67]
	s_barrier
	s_add_i32 s54, s45, s34
	v_lshl_add_u64 v[204:205], s[26:27], 0, v[194:195]
	s_mov_b32 m0, s54
	ds_read_b128 v[160:163], v247 offset:16384
	ds_read_b128 v[164:167], v247 offset:17408
	ds_read_b128 v[168:171], v247 offset:18432
	ds_read_b128 v[172:175], v247 offset:19456
	ds_read_b128 v[176:179], v247 offset:20480
	ds_read_b128 v[180:183], v247 offset:21504
	ds_read_b128 v[184:187], v247 offset:22528
	ds_read_b128 v[188:191], v247 offset:23552
	global_load_lds_dwordx4 v[204:205], off
	s_add_i32 m0, s54, 0x2000
	s_add_u32 s54, s26, 0xb0000
	v_lshl_add_u64 v[206:207], s[26:27], 0, v[198:199]
	s_addc_u32 s55, s27, 0
	s_add_i32 s56, s46, s34
	global_load_lds_dwordx4 v[206:207], off
	s_mov_b32 m0, s56
	v_lshl_add_u64 v[210:211], s[28:29], 0, v[196:197]
	global_load_lds_dwordx4 v194, s[54:55]
	s_add_i32 m0, s56, 0x2000
	s_nop 0
	global_load_lds_dwordx4 v198, s[54:55]
	v_lshl_add_u64 v[208:209], s[28:29], 0, v[192:193]
	s_mov_b32 m0, s35
	s_nop 0
	global_load_lds_dwordx4 v[208:209], off
	s_mov_b32 m0, s36
	s_nop 0
	global_load_lds_dwordx4 v[210:211], off
	s_waitcnt vmcnt(8)
	s_waitcnt lgkmcnt(0)
	s_setprio 1
	s_barrier
	v_mfma_f32_16x16x32_bf16 v[60:63], v[120:123], v[160:163], 0
	v_mfma_f32_16x16x32_bf16 v[56:59], v[136:139], v[160:163], 0
	v_mfma_f32_16x16x32_bf16 v[44:47], v[120:123], v[168:171], 0
	v_mfma_f32_16x16x32_bf16 v[40:43], v[136:139], v[168:171], 0
	v_mfma_f32_16x16x32_bf16 v[28:31], v[120:123], v[176:179], 0
	v_mfma_f32_16x16x32_bf16 v[24:27], v[136:139], v[176:179], 0
	v_mfma_f32_16x16x32_bf16 v[12:15], v[120:123], v[184:187], 0
	v_mfma_f32_16x16x32_bf16 v[8:11], v[136:139], v[184:187], 0
	v_mfma_f32_16x16x32_bf16 v[60:63], v[128:131], v[164:167], v[60:63]
	v_mfma_f32_16x16x32_bf16 v[56:59], v[140:143], v[164:167], v[56:59]
	v_mfma_f32_16x16x32_bf16 v[44:47], v[128:131], v[172:175], v[44:47]
	v_mfma_f32_16x16x32_bf16 v[40:43], v[140:143], v[172:175], v[40:43]
	v_mfma_f32_16x16x32_bf16 v[28:31], v[128:131], v[180:183], v[28:31]
	v_mfma_f32_16x16x32_bf16 v[24:27], v[140:143], v[180:183], v[24:27]
	v_mfma_f32_16x16x32_bf16 v[12:15], v[128:131], v[188:191], v[12:15]
	v_mfma_f32_16x16x32_bf16 v[8:11], v[140:143], v[188:191], v[8:11]
	v_mfma_f32_16x16x32_bf16 v[52:55], v[144:147], v[160:163], 0
	v_mfma_f32_16x16x32_bf16 v[48:51], v[152:155], v[160:163], 0
	v_mfma_f32_16x16x32_bf16 v[36:39], v[144:147], v[168:171], 0
	v_mfma_f32_16x16x32_bf16 v[32:35], v[152:155], v[168:171], 0
	v_mfma_f32_16x16x32_bf16 v[20:23], v[144:147], v[176:179], 0
	v_mfma_f32_16x16x32_bf16 v[16:19], v[152:155], v[176:179], 0
	v_mfma_f32_16x16x32_bf16 v[4:7], v[144:147], v[184:187], 0
	v_mfma_f32_16x16x32_bf16 v[0:3], v[152:155], v[184:187], 0
	v_mfma_f32_16x16x32_bf16 v[52:55], v[148:151], v[164:167], v[52:55]
	v_mfma_f32_16x16x32_bf16 v[48:51], v[156:159], v[164:167], v[48:51]
	v_mfma_f32_16x16x32_bf16 v[36:39], v[148:151], v[172:175], v[36:39]
	v_mfma_f32_16x16x32_bf16 v[32:35], v[156:159], v[172:175], v[32:35]
	v_mfma_f32_16x16x32_bf16 v[20:23], v[148:151], v[180:183], v[20:23]
	v_mfma_f32_16x16x32_bf16 v[16:19], v[156:159], v[180:183], v[16:19]
	v_mfma_f32_16x16x32_bf16 v[4:7], v[148:151], v[188:191], v[4:7]
	s_setprio 0
	v_mfma_f32_16x16x32_bf16 v[0:3], v[156:159], v[188:191], v[0:3]
	s_barrier
; #define PG8_STAGE(bufoff, gbase, voff) do { _Pragma("unroll") for (int _i = 0; _i < 2; ++_i) \
;         __builtin_amdgcn_global_load_lds((const unsigned*)((const char*)(gbase) + (voff)[_i]), (PG8_LAS unsigned*)(lds + (bufoff) + ldsw + _i * 8192), 16, 0, 0); } while (0)
; #define PG8_LDA(dst, b, h) do { _Pragma("unroll") for (int m = 0; m < 4; ++m) _Pragma("unroll") for (int k = 0; k < 2; ++k) dst[m][k] = *(const PG8_LAS bf16x8*)(lds + PG8_SA(b, h) + aoff + m * 2048 + k * 1024); } while (0)
; #define PG8_LDB(dst, b, h) do { _Pragma("unroll") for (int n = 0; n < 2; ++n) _Pragma("unroll") for (int k = 0; k < 2; ++k) dst[n][k] = *(const PG8_LAS bf16x8*)(lds + PG8_SB(b, h) + boff + n * 2048 + k * 1024); } while (0)
; #define PG8_MMA(ai, bj, At, Bt) do { __builtin_amdgcn_s_setprio(1); _Pragma("unroll") for (int m = 0; m < 4; ++m) _Pragma("unroll") for (int n = 0; n < 2; ++n) _Pragma("unroll") for (int k = 0; k < 2; ++k) \
;         acc[ai][bj][m][n] = __builtin_amdgcn_mfma_f32_16x16x32_bf16(Bt[n][k], At[m][k], acc[ai][bj][m][n], 0, 0, 0); __builtin_amdgcn_s_setprio(0); } while (0)
; #define PG8_WAIT_V(n) asm volatile("s_waitcnt vmcnt(" #n ")" ::: "memory")
; #define PG8_WAIT_L(n) asm volatile("s_waitcnt lgkmcnt(" #n ")" ::: "memory")
; #define PG8_BAR __builtin_amdgcn_s_barrier()
; #define PG8_SCHED __builtin_amdgcn_sched_barrier(0)
; template <class Epi, class Sched, bool ALIGN_EPI = false, bool SP2 = false>
; __device__ __forceinline__ void gemm_phase(PG8_LAS unsigned char* lds, const Gemm g, const Sched& S, const Epi& E) {
;     ...
;         for (int t = 0; t < nt; t += 2) {
;             const bool last = (t == nt - 2);
;     ...
;             PG8_LDB(B0, 1, 0); PG8_LDB(B1, 1, 1); PG8_SCHED; PG8_LDA(At, 1, 0); PG8_STAGE(PG8_SA(0, 1), a2 + hstep, voffA);
;             PG8_WAIT_V(8); PG8_WAIT_L(0); PG8_BAR; PG8_MMA(0, 0, At, B0); PG8_MMA(0, 1, At, B1); PG8_BAR; PG8_SCHED;
;             PG8_LDA(At, 1, 1); PG8_STAGE(PG8_SB(1, 0), b3, voffB); PG8_STAGE(PG8_SB(1, 1), b3 + hstep, voffB); PG8_STAGE(PG8_SA(1, 0), a3, voffA);
;             PG8_WAIT_V(8); PG8_WAIT_L(0); PG8_BAR; PG8_MMA(1, 0, At, B0); PG8_MMA(1, 1, At, B1); PG8_BAR; PG8_SCHED;
	s_add_i32 s54, 0, 0x18000
	s_add_i32 s55, 0, 0x1c000
	v_add_u32_e32 v140, s54, v243
	v_add_u32_e32 v156, s55, v243
	ds_read_b128 v[120:123], v140
	ds_read_b128 v[128:131], v140 offset:1024
	ds_read_b128 v[136:139], v140 offset:2048
	ds_read_b128 v[140:143], v140 offset:3072
	ds_read_b128 v[144:147], v156
	ds_read_b128 v[148:151], v156 offset:1024
	ds_read_b128 v[152:155], v156 offset:2048
	ds_read_b128 v[156:159], v156 offset:3072
	s_add_u32 s28, s28, 0xb0000
	s_addc_u32 s29, s29, 0
	s_mov_b32 m0, s37
	ds_read_b128 v[160:163], v247 offset:32768
	ds_read_b128 v[164:167], v247 offset:33792
	ds_read_b128 v[168:171], v247 offset:34816
	ds_read_b128 v[172:175], v247 offset:35840
	ds_read_b128 v[176:179], v247 offset:36864
	ds_read_b128 v[180:183], v247 offset:37888
	ds_read_b128 v[184:187], v247 offset:38912
	ds_read_b128 v[188:191], v247 offset:39936
	global_load_lds_dwordx4 v192, s[28:29]
	s_mov_b32 m0, s38
	s_nop 0
	global_load_lds_dwordx4 v196, s[28:29]
	s_waitcnt vmcnt(8)
	s_waitcnt lgkmcnt(0)
	s_setprio 1
	s_barrier
	v_mfma_f32_16x16x32_bf16 v[132:135], v[120:123], v[160:163], v[132:135]
	v_mfma_f32_16x16x32_bf16 v[124:127], v[136:139], v[160:163], v[124:127]
	v_mfma_f32_16x16x32_bf16 v[108:111], v[120:123], v[168:171], v[108:111]
	v_mfma_f32_16x16x32_bf16 v[104:107], v[136:139], v[168:171], v[104:107]
	v_mfma_f32_16x16x32_bf16 v[92:95], v[120:123], v[176:179], v[92:95]
	v_mfma_f32_16x16x32_bf16 v[88:91], v[136:139], v[176:179], v[88:91]
	v_mfma_f32_16x16x32_bf16 v[76:79], v[120:123], v[184:187], v[76:79]
	v_mfma_f32_16x16x32_bf16 v[72:75], v[136:139], v[184:187], v[72:75]
	v_mfma_f32_16x16x32_bf16 v[132:135], v[128:131], v[164:167], v[132:135]
	v_mfma_f32_16x16x32_bf16 v[124:127], v[140:143], v[164:167], v[124:127]
	v_mfma_f32_16x16x32_bf16 v[108:111], v[128:131], v[172:175], v[108:111]
	v_mfma_f32_16x16x32_bf16 v[104:107], v[140:143], v[172:175], v[104:107]
	v_mfma_f32_16x16x32_bf16 v[92:95], v[128:131], v[180:183], v[92:95]
	v_mfma_f32_16x16x32_bf16 v[88:91], v[140:143], v[180:183], v[88:91]
	v_mfma_f32_16x16x32_bf16 v[76:79], v[128:131], v[188:191], v[76:79]
	v_mfma_f32_16x16x32_bf16 v[72:75], v[140:143], v[188:191], v[72:75]
	v_mfma_f32_16x16x32_bf16 v[116:119], v[144:147], v[160:163], v[116:119]
	v_mfma_f32_16x16x32_bf16 v[112:115], v[152:155], v[160:163], v[112:115]
	v_mfma_f32_16x16x32_bf16 v[100:103], v[144:147], v[168:171], v[100:103]
	v_mfma_f32_16x16x32_bf16 v[96:99], v[152:155], v[168:171], v[96:99]
	v_mfma_f32_16x16x32_bf16 v[84:87], v[144:147], v[176:179], v[84:87]
	v_mfma_f32_16x16x32_bf16 v[80:83], v[152:155], v[176:179], v[80:83]
	v_mfma_f32_16x16x32_bf16 v[68:71], v[144:147], v[184:187], v[68:71]
	v_mfma_f32_16x16x32_bf16 v[64:67], v[152:155], v[184:187], v[64:67]
	v_mfma_f32_16x16x32_bf16 v[116:119], v[148:151], v[164:167], v[116:119]
	v_mfma_f32_16x16x32_bf16 v[112:115], v[156:159], v[164:167], v[112:115]
	v_mfma_f32_16x16x32_bf16 v[100:103], v[148:151], v[172:175], v[100:103]
	v_mfma_f32_16x16x32_bf16 v[96:99], v[156:159], v[172:175], v[96:99]
	v_mfma_f32_16x16x32_bf16 v[84:87], v[148:151], v[180:183], v[84:87]
	v_mfma_f32_16x16x32_bf16 v[80:83], v[156:159], v[180:183], v[80:83]
	v_mfma_f32_16x16x32_bf16 v[68:71], v[148:151], v[188:191], v[68:71]
	s_setprio 0
	v_mfma_f32_16x16x32_bf16 v[64:67], v[156:159], v[188:191], v[64:67]
	s_barrier
	s_add_i32 s28, s54, s34
	v_lshl_add_u64 v[204:205], v[204:205], 0, s[18:19]
	s_mov_b32 m0, s28
	ds_read_b128 v[160:163], v247 offset:49152
	ds_read_b128 v[164:167], v247 offset:50176
	ds_read_b128 v[168:171], v247 offset:51200
	ds_read_b128 v[172:175], v247 offset:52224
	ds_read_b128 v[176:179], v247 offset:53248
	ds_read_b128 v[180:183], v247 offset:54272
	ds_read_b128 v[184:187], v247 offset:55296
	ds_read_b128 v[188:191], v247 offset:56320
	global_load_lds_dwordx4 v[204:205], off
	s_add_i32 m0, s28, 0x2000
	s_add_u32 s26, s26, 0xb0080
	v_lshl_add_u64 v[204:205], v[206:207], 0, s[18:19]
	s_addc_u32 s27, s27, 0
	s_add_i32 s28, s55, s34
	global_load_lds_dwordx4 v[204:205], off
	s_mov_b32 m0, s28
	s_nop 0
	global_load_lds_dwordx4 v194, s[26:27]
	s_add_i32 m0, s28, 0x2000
	s_nop 0
	global_load_lds_dwordx4 v198, s[26:27]
	v_lshl_add_u64 v[204:205], v[208:209], 0, s[18:19]
	s_mov_b32 m0, s40
	s_nop 0
	global_load_lds_dwordx4 v[204:205], off
	v_lshl_add_u64 v[204:205], v[210:211], 0, s[18:19]
	s_mov_b32 m0, s41
	s_nop 0
	global_load_lds_dwordx4 v[204:205], off
	s_waitcnt vmcnt(8)
	s_waitcnt lgkmcnt(0)
	s_setprio 1
	s_barrier
	v_mfma_f32_16x16x32_bf16 v[60:63], v[120:123], v[160:163], v[60:63]
	v_mfma_f32_16x16x32_bf16 v[56:59], v[136:139], v[160:163], v[56:59]
	v_mfma_f32_16x16x32_bf16 v[44:47], v[120:123], v[168:171], v[44:47]
	v_mfma_f32_16x16x32_bf16 v[40:43], v[136:139], v[168:171], v[40:43]
	v_mfma_f32_16x16x32_bf16 v[28:31], v[120:123], v[176:179], v[28:31]
	v_mfma_f32_16x16x32_bf16 v[24:27], v[136:139], v[176:179], v[24:27]
	v_mfma_f32_16x16x32_bf16 v[12:15], v[120:123], v[184:187], v[12:15]
	v_mfma_f32_16x16x32_bf16 v[8:11], v[136:139], v[184:187], v[8:11]
	v_mfma_f32_16x16x32_bf16 v[60:63], v[128:131], v[164:167], v[60:63]
	v_mfma_f32_16x16x32_bf16 v[56:59], v[140:143], v[164:167], v[56:59]
	v_mfma_f32_16x16x32_bf16 v[44:47], v[128:131], v[172:175], v[44:47]
	v_mfma_f32_16x16x32_bf16 v[40:43], v[140:143], v[172:175], v[40:43]
	v_mfma_f32_16x16x32_bf16 v[28:31], v[128:131], v[180:183], v[28:31]
	v_mfma_f32_16x16x32_bf16 v[24:27], v[140:143], v[180:183], v[24:27]
	v_mfma_f32_16x16x32_bf16 v[12:15], v[128:131], v[188:191], v[12:15]
	v_mfma_f32_16x16x32_bf16 v[8:11], v[140:143], v[188:191], v[8:11]
	v_mfma_f32_16x16x32_bf16 v[52:55], v[144:147], v[160:163], v[52:55]
	v_mfma_f32_16x16x32_bf16 v[48:51], v[152:155], v[160:163], v[48:51]
	v_mfma_f32_16x16x32_bf16 v[36:39], v[144:147], v[168:171], v[36:39]
	v_mfma_f32_16x16x32_bf16 v[32:35], v[152:155], v[168:171], v[32:35]
	v_mfma_f32_16x16x32_bf16 v[20:23], v[144:147], v[176:179], v[20:23]
	v_mfma_f32_16x16x32_bf16 v[16:19], v[152:155], v[176:179], v[16:19]
	v_mfma_f32_16x16x32_bf16 v[4:7], v[144:147], v[184:187], v[4:7]
	v_mfma_f32_16x16x32_bf16 v[0:3], v[152:155], v[184:187], v[0:3]
	v_mfma_f32_16x16x32_bf16 v[52:55], v[148:151], v[164:167], v[52:55]
	v_mfma_f32_16x16x32_bf16 v[48:51], v[156:159], v[164:167], v[48:51]
	v_mfma_f32_16x16x32_bf16 v[36:39], v[148:151], v[172:175], v[36:39]
	v_mfma_f32_16x16x32_bf16 v[32:35], v[156:159], v[172:175], v[32:35]
	v_mfma_f32_16x16x32_bf16 v[20:23], v[148:151], v[180:183], v[20:23]
	v_mfma_f32_16x16x32_bf16 v[16:19], v[156:159], v[180:183], v[16:19]
	v_mfma_f32_16x16x32_bf16 v[4:7], v[148:151], v[188:191], v[4:7]
	s_setprio 0
	v_mfma_f32_16x16x32_bf16 v[0:3], v[156:159], v[188:191], v[0:3]
	s_barrier
	s_add_i32 s53, s53, 2
	s_add_u32 s24, s24, 0x100
	s_addc_u32 s25, s25, 0
	s_add_u32 s51, s51, 0x100
	s_addc_u32 s52, s52, 0
	s_cmp_gt_u32 s53, 41

; #define PG8_STAGE(bufoff, gbase, voff) do { _Pragma("unroll") for (int _i = 0; _i < 2; ++_i) \
;         __builtin_amdgcn_global_load_lds((const unsigned*)((const char*)(gbase) + (voff)[_i]), (PG8_LAS unsigned*)(lds + (bufoff) + ldsw + _i * 8192), 16, 0, 0); } while (0)
; #define PG8_LDA(dst, b, h) do { _Pragma("unroll") for (int m = 0; m < 4; ++m) _Pragma("unroll") for (int k = 0; k < 2; ++k) dst[m][k] = *(const PG8_LAS bf16x8*)(lds + PG8_SA(b, h) + aoff + m * 2048 + k * 1024); } while (0)
; #define PG8_LDB(dst, b, h) do { _Pragma("unroll") for (int n = 0; n < 2; ++n) _Pragma("unroll") for (int k = 0; k < 2; ++k) dst[n][k] = *(const PG8_LAS bf16x8*)(lds + PG8_SB(b, h) + boff + n * 2048 + k * 1024); } while (0)
; #define PG8_WAIT_V(n) asm volatile("s_waitcnt vmcnt(" #n ")" ::: "memory")
; #define PG8_WAIT_L(n) asm volatile("s_waitcnt lgkmcnt(" #n ")" ::: "memory")
; #define PG8_BAR __builtin_amdgcn_s_barrier()
; #define PG8_SCHED __builtin_amdgcn_sched_barrier(0)
; template <class Epi, class Sched, bool ALIGN_EPI = false, bool SP2 = false>
; __device__ __forceinline__ void gemm_phase(PG8_LAS unsigned char* lds, const Gemm g, const Sched& S, const Epi& E) {
;     ...
;         const bool has_next = S.next(ui + 1, nxt);
;         const char* nA = has_next ? (const char*)g.A + (size_t)nxt.pm * tstep : cA; const char* nB = has_next ? (const char*)g.Bt + (size_t)nxt.pn * tstep : cB;
;         for (int t = 0; t < nt; t += 2) {
;             const bool last = (t == nt - 2);
;             const char* a1 = cA + (size_t)(t + 1) * kstep;
;             const char* a2 = last ? nA : cA + (size_t)(t + 2) * kstep; const char* b2 = last ? nB : cB + (size_t)(t + 2) * kstep;
;             const char* a3 = a2 + kstep; const char* b3 = b2 + kstep;
;             if (last && has_next) S.a_ready(nxt, ui + 1);
;             if constexpr (SP2) {
;             PG8_LDB(B0, 0, 0); PG8_LDB(B1, 0, 1); PG8_SCHED; PG8_LDA(At, 0, 0); PG8_STAGE(PG8_SA(1, 1), a1 + hstep, voffA);
;             PG8_WAIT_V(8); PG8_WAIT_L(0); PG8_BAR; PG8_MMA(0, 0, At, B0); PG8_MMA(0, 1, At, B1); PG8_BAR; PG8_SCHED;
;             PG8_LDA(At, 0, 1); PG8_STAGE(PG8_SB(0, 0), b2, voffB); PG8_STAGE(PG8_SB(0, 1), b2 + hstep, voffB); PG8_STAGE(PG8_SA(0, 0), a2, voffA);
;             PG8_WAIT_V(8); PG8_WAIT_L(0); PG8_BAR; PG8_MMA(1, 0, At, B0); PG8_MMA(1, 1, At, B1); PG8_BAR; PG8_SCHED;
.LBB0_1218:
	s_ashr_i32 s17, s16, 31
	s_lshl_b64 s[18:19], s[16:17], 19
	s_add_u32 s18, s36, s18
	s_addc_u32 s19, s37, s19
	s_and_b64 s[20:21], s[0:1], exec
	s_cselect_b32 s17, s19, s25
	s_cselect_b32 s50, s18, s24
	s_ashr_i32 s15, s14, 31
	s_lshl_b64 s[20:21], s[14:15], 19
	s_add_u32 s20, s34, s20
	s_addc_u32 s21, s35, s21
	s_and_b64 s[28:29], s[0:1], exec
	s_cselect_b32 s15, s21, s27
	s_cselect_b32 s51, s20, s26
	s_add_u32 s24, s24, 0x40080
	s_addc_u32 s25, s25, 0
	s_add_u32 s52, s26, 0x100
	s_addc_u32 s53, s27, 0
	s_mov_b32 s54, -2
	s_add_u32 s26, s24, 0xfffc0080
	s_addc_u32 s27, s25, -1
	s_cmp_eq_u32 s54, 12
	s_cselect_b32 s29, s17, s27
	s_cselect_b32 s28, s50, s26
	s_cselect_b32 s27, s15, s53
	s_cselect_b32 s26, s51, s52
	s_add_i32 m0, s23, 0xc000
	s_nop 0
	global_load_lds_dwordx4 v136, s[24:25]
	s_add_i32 m0, s23, 0xe000
	s_nop 0
	global_load_lds_dwordx4 v138, s[24:25]
	s_waitcnt vmcnt(8)
	s_waitcnt lgkmcnt(0)
	s_setprio 1
	s_barrier
	v_mfma_f32_16x16x32_bf16 v[124:127], v[152:155], v[184:187], 0
	v_mfma_f32_16x16x32_bf16 v[120:123], v[160:163], v[184:187], 0
	v_mfma_f32_16x16x32_bf16 v[108:111], v[152:155], v[192:195], 0
	v_mfma_f32_16x16x32_bf16 v[104:107], v[160:163], v[192:195], 0
	v_mfma_f32_16x16x32_bf16 v[92:95], v[152:155], v[200:203], 0
	v_mfma_f32_16x16x32_bf16 v[88:91], v[160:163], v[200:203], 0
	v_mfma_f32_16x16x32_bf16 v[76:79], v[152:155], v[208:211], 0
	v_mfma_f32_16x16x32_bf16 v[72:75], v[160:163], v[208:211], 0
	v_mfma_f32_16x16x32_bf16 v[124:127], v[156:159], v[188:191], v[124:127]
	v_mfma_f32_16x16x32_bf16 v[120:123], v[164:167], v[188:191], v[120:123]
	v_mfma_f32_16x16x32_bf16 v[108:111], v[156:159], v[196:199], v[108:111]
	v_mfma_f32_16x16x32_bf16 v[104:107], v[164:167], v[196:199], v[104:107]
	v_mfma_f32_16x16x32_bf16 v[92:95], v[156:159], v[204:207], v[92:95]
	v_mfma_f32_16x16x32_bf16 v[88:91], v[164:167], v[204:207], v[88:91]
	v_mfma_f32_16x16x32_bf16 v[76:79], v[156:159], v[212:215], v[76:79]
	v_mfma_f32_16x16x32_bf16 v[72:75], v[164:167], v[212:215], v[72:75]
	v_mfma_f32_16x16x32_bf16 v[116:119], v[168:171], v[184:187], 0
	v_mfma_f32_16x16x32_bf16 v[112:115], v[176:179], v[184:187], 0
	v_mfma_f32_16x16x32_bf16 v[100:103], v[168:171], v[192:195], 0
	v_mfma_f32_16x16x32_bf16 v[96:99], v[176:179], v[192:195], 0
	v_mfma_f32_16x16x32_bf16 v[84:87], v[168:171], v[200:203], 0
	v_mfma_f32_16x16x32_bf16 v[80:83], v[176:179], v[200:203], 0
	v_mfma_f32_16x16x32_bf16 v[68:71], v[168:171], v[208:211], 0
	v_mfma_f32_16x16x32_bf16 v[64:67], v[176:179], v[208:211], 0
	v_mfma_f32_16x16x32_bf16 v[116:119], v[172:175], v[188:191], v[116:119]
	v_mfma_f32_16x16x32_bf16 v[112:115], v[180:183], v[188:191], v[112:115]
	v_mfma_f32_16x16x32_bf16 v[100:103], v[172:175], v[196:199], v[100:103]
	v_mfma_f32_16x16x32_bf16 v[96:99], v[180:183], v[196:199], v[96:99]
	v_mfma_f32_16x16x32_bf16 v[84:87], v[172:175], v[204:207], v[84:87]
	v_mfma_f32_16x16x32_bf16 v[80:83], v[180:183], v[204:207], v[80:83]
	v_mfma_f32_16x16x32_bf16 v[68:71], v[172:175], v[212:215], v[68:71]
	s_setprio 0
	v_mfma_f32_16x16x32_bf16 v[64:67], v[180:183], v[212:215], v[64:67]
	s_barrier
	s_add_i32 s55, s44, s33
	v_lshl_add_u64 v[216:217], s[26:27], 0, v[132:133]
	s_mov_b32 m0, s55
	ds_read_b128 v[184:187], v150 offset:16384
	ds_read_b128 v[188:191], v150 offset:17408
	ds_read_b128 v[192:195], v150 offset:18432
	ds_read_b128 v[196:199], v150 offset:19456
	ds_read_b128 v[200:203], v150 offset:20480
	ds_read_b128 v[204:207], v150 offset:21504
	ds_read_b128 v[208:211], v150 offset:22528
	ds_read_b128 v[212:215], v150 offset:23552
	global_load_lds_dwordx4 v[216:217], off
	s_add_i32 m0, s55, 0x2000
	s_add_u32 s56, s26, 0x40000
	v_lshl_add_u64 v[218:219], s[26:27], 0, v[128:129]
	s_addc_u32 s57, s27, 0
	s_add_i32 s55, s45, s33
	global_load_lds_dwordx4 v[218:219], off
	s_mov_b32 m0, s55
	v_lshl_add_u64 v[222:223], s[28:29], 0, v[130:131]
	global_load_lds_dwordx4 v132, s[56:57]
	s_add_i32 m0, s55, 0x2000
	s_nop 0
	global_load_lds_dwordx4 v128, s[56:57]
	v_lshl_add_u64 v[220:221], s[28:29], 0, v[134:135]
	s_mov_b32 m0, s23
	s_nop 0
	global_load_lds_dwordx4 v[220:221], off
	s_mov_b32 m0, s39
	s_nop 0
	global_load_lds_dwordx4 v[222:223], off
	s_waitcnt vmcnt(8)
	s_waitcnt lgkmcnt(0)
	s_setprio 1
	s_barrier
	v_mfma_f32_16x16x32_bf16 v[60:63], v[152:155], v[184:187], 0
	v_mfma_f32_16x16x32_bf16 v[56:59], v[160:163], v[184:187], 0
	v_mfma_f32_16x16x32_bf16 v[44:47], v[152:155], v[192:195], 0
	v_mfma_f32_16x16x32_bf16 v[40:43], v[160:163], v[192:195], 0
	v_mfma_f32_16x16x32_bf16 v[28:31], v[152:155], v[200:203], 0
	v_mfma_f32_16x16x32_bf16 v[24:27], v[160:163], v[200:203], 0
	v_mfma_f32_16x16x32_bf16 v[12:15], v[152:155], v[208:211], 0
	v_mfma_f32_16x16x32_bf16 v[8:11], v[160:163], v[208:211], 0
	v_mfma_f32_16x16x32_bf16 v[60:63], v[156:159], v[188:191], v[60:63]
	v_mfma_f32_16x16x32_bf16 v[56:59], v[164:167], v[188:191], v[56:59]
	v_mfma_f32_16x16x32_bf16 v[44:47], v[156:159], v[196:199], v[44:47]
	v_mfma_f32_16x16x32_bf16 v[40:43], v[164:167], v[196:199], v[40:43]
	v_mfma_f32_16x16x32_bf16 v[28:31], v[156:159], v[204:207], v[28:31]
	v_mfma_f32_16x16x32_bf16 v[24:27], v[164:167], v[204:207], v[24:27]
	v_mfma_f32_16x16x32_bf16 v[12:15], v[156:159], v[212:215], v[12:15]
	v_mfma_f32_16x16x32_bf16 v[8:11], v[164:167], v[212:215], v[8:11]
	v_mfma_f32_16x16x32_bf16 v[52:55], v[168:171], v[184:187], 0
	v_mfma_f32_16x16x32_bf16 v[48:51], v[176:179], v[184:187], 0
	v_mfma_f32_16x16x32_bf16 v[36:39], v[168:171], v[192:195], 0
	v_mfma_f32_16x16x32_bf16 v[32:35], v[176:179], v[192:195], 0
	v_mfma_f32_16x16x32_bf16 v[20:23], v[168:171], v[200:203], 0
	v_mfma_f32_16x16x32_bf16 v[16:19], v[176:179], v[200:203], 0
	v_mfma_f32_16x16x32_bf16 v[4:7], v[168:171], v[208:211], 0
	v_mfma_f32_16x16x32_bf16 v[0:3], v[176:179], v[208:211], 0
	v_mfma_f32_16x16x32_bf16 v[52:55], v[172:175], v[188:191], v[52:55]
	v_mfma_f32_16x16x32_bf16 v[48:51], v[180:183], v[188:191], v[48:51]
	v_mfma_f32_16x16x32_bf16 v[36:39], v[172:175], v[196:199], v[36:39]
	v_mfma_f32_16x16x32_bf16 v[32:35], v[180:183], v[196:199], v[32:35]
	v_mfma_f32_16x16x32_bf16 v[20:23], v[172:175], v[204:207], v[20:23]
	v_mfma_f32_16x16x32_bf16 v[16:19], v[180:183], v[204:207], v[16:19]
	v_mfma_f32_16x16x32_bf16 v[4:7], v[172:175], v[212:215], v[4:7]
	s_setprio 0
	v_mfma_f32_16x16x32_bf16 v[0:3], v[180:183], v[212:215], v[0:3]
	s_barrier
; #define PG8_STAGE(bufoff, gbase, voff) do { _Pragma("unroll") for (int _i = 0; _i < 2; ++_i) \
;         __builtin_amdgcn_global_load_lds((const unsigned*)((const char*)(gbase) + (voff)[_i]), (PG8_LAS unsigned*)(lds + (bufoff) + ldsw + _i * 8192), 16, 0, 0); } while (0)
; #define PG8_LDA(dst, b, h) do { _Pragma("unroll") for (int m = 0; m < 4; ++m) _Pragma("unroll") for (int k = 0; k < 2; ++k) dst[m][k] = *(const PG8_LAS bf16x8*)(lds + PG8_SA(b, h) + aoff + m * 2048 + k * 1024); } while (0)
; #define PG8_LDB(dst, b, h) do { _Pragma("unroll") for (int n = 0; n < 2; ++n) _Pragma("unroll") for (int k = 0; k < 2; ++k) dst[n][k] = *(const PG8_LAS bf16x8*)(lds + PG8_SB(b, h) + boff + n * 2048 + k * 1024); } while (0)
; #define PG8_MMA(ai, bj, At, Bt) do { __builtin_amdgcn_s_setprio(1); _Pragma("unroll") for (int m = 0; m < 4; ++m) _Pragma("unroll") for (int n = 0; n < 2; ++n) _Pragma("unroll") for (int k = 0; k < 2; ++k) \
;         acc[ai][bj][m][n] = __builtin_amdgcn_mfma_f32_16x16x32_bf16(Bt[n][k], At[m][k], acc[ai][bj][m][n], 0, 0, 0); __builtin_amdgcn_s_setprio(0); } while (0)
; #define PG8_WAIT_V(n) asm volatile("s_waitcnt vmcnt(" #n ")" ::: "memory")
; #define PG8_WAIT_L(n) asm volatile("s_waitcnt lgkmcnt(" #n ")" ::: "memory")
; #define PG8_BAR __builtin_amdgcn_s_barrier()
; #define PG8_SCHED __builtin_amdgcn_sched_barrier(0)
; template <class Epi, class Sched, bool ALIGN_EPI = false, bool SP2 = false>
; __device__ __forceinline__ void gemm_phase(PG8_LAS unsigned char* lds, const Gemm g, const Sched& S, const Epi& E) {
;     ...
;         for (int t = 0; t < nt; t += 2) {
;             const bool last = (t == nt - 2);
;     ...
;             PG8_LDB(B0, 1, 0); PG8_LDB(B1, 1, 1); PG8_SCHED; PG8_LDA(At, 1, 0); PG8_STAGE(PG8_SA(0, 1), a2 + hstep, voffA);
;             PG8_WAIT_V(8); PG8_WAIT_L(0); PG8_BAR; PG8_MMA(0, 0, At, B0); PG8_MMA(0, 1, At, B1); PG8_BAR; PG8_SCHED;
;             PG8_LDA(At, 1, 1); PG8_STAGE(PG8_SB(1, 0), b3, voffB); PG8_STAGE(PG8_SB(1, 1), b3 + hstep, voffB); PG8_STAGE(PG8_SA(1, 0), a3, voffA);
;             PG8_WAIT_V(8); PG8_WAIT_L(0); PG8_BAR; PG8_MMA(1, 0, At, B0); PG8_MMA(1, 1, At, B1); PG8_BAR; PG8_SCHED;
	s_add_i32 s55, 0, 0x18000
	v_add_u32_e32 v151, s55, v145
	s_add_i32 s56, 0, 0x1c000
	ds_read_b128 v[152:155], v151
	ds_read_b128 v[156:159], v151 offset:1024
	ds_read_b128 v[160:163], v151 offset:2048
	ds_read_b128 v[164:167], v151 offset:3072
	v_add_u32_e32 v151, s56, v145
	ds_read_b128 v[168:171], v151
	ds_read_b128 v[172:175], v151 offset:1024
	ds_read_b128 v[176:179], v151 offset:2048
	ds_read_b128 v[180:183], v151 offset:3072
	s_add_u32 s28, s28, 0x40000
	s_addc_u32 s29, s29, 0
	s_mov_b32 m0, s40
	ds_read_b128 v[184:187], v150 offset:32768
	ds_read_b128 v[188:191], v150 offset:33792
	ds_read_b128 v[192:195], v150 offset:34816
	ds_read_b128 v[196:199], v150 offset:35840
	ds_read_b128 v[200:203], v150 offset:36864
	ds_read_b128 v[204:207], v150 offset:37888
	ds_read_b128 v[208:211], v150 offset:38912
	ds_read_b128 v[212:215], v150 offset:39936
	global_load_lds_dwordx4 v134, s[28:29]
	s_mov_b32 m0, s41
	s_nop 0
	global_load_lds_dwordx4 v130, s[28:29]
	s_waitcnt vmcnt(8)
	s_waitcnt lgkmcnt(0)
	s_setprio 1
	s_barrier
	v_mfma_f32_16x16x32_bf16 v[124:127], v[152:155], v[184:187], v[124:127]
	v_mfma_f32_16x16x32_bf16 v[120:123], v[160:163], v[184:187], v[120:123]
	v_mfma_f32_16x16x32_bf16 v[108:111], v[152:155], v[192:195], v[108:111]
	v_mfma_f32_16x16x32_bf16 v[104:107], v[160:163], v[192:195], v[104:107]
	v_mfma_f32_16x16x32_bf16 v[92:95], v[152:155], v[200:203], v[92:95]
	v_mfma_f32_16x16x32_bf16 v[88:91], v[160:163], v[200:203], v[88:91]
	v_mfma_f32_16x16x32_bf16 v[76:79], v[152:155], v[208:211], v[76:79]
	v_mfma_f32_16x16x32_bf16 v[72:75], v[160:163], v[208:211], v[72:75]
	v_mfma_f32_16x16x32_bf16 v[124:127], v[156:159], v[188:191], v[124:127]
	v_mfma_f32_16x16x32_bf16 v[120:123], v[164:167], v[188:191], v[120:123]
	v_mfma_f32_16x16x32_bf16 v[108:111], v[156:159], v[196:199], v[108:111]
	v_mfma_f32_16x16x32_bf16 v[104:107], v[164:167], v[196:199], v[104:107]
	v_mfma_f32_16x16x32_bf16 v[92:95], v[156:159], v[204:207], v[92:95]
	v_mfma_f32_16x16x32_bf16 v[88:91], v[164:167], v[204:207], v[88:91]
	v_mfma_f32_16x16x32_bf16 v[76:79], v[156:159], v[212:215], v[76:79]
	v_mfma_f32_16x16x32_bf16 v[72:75], v[164:167], v[212:215], v[72:75]
	v_mfma_f32_16x16x32_bf16 v[116:119], v[168:171], v[184:187], v[116:119]
	v_mfma_f32_16x16x32_bf16 v[112:115], v[176:179], v[184:187], v[112:115]
	v_mfma_f32_16x16x32_bf16 v[100:103], v[168:171], v[192:195], v[100:103]
	v_mfma_f32_16x16x32_bf16 v[96:99], v[176:179], v[192:195], v[96:99]
	v_mfma_f32_16x16x32_bf16 v[84:87], v[168:171], v[200:203], v[84:87]
	v_mfma_f32_16x16x32_bf16 v[80:83], v[176:179], v[200:203], v[80:83]
	v_mfma_f32_16x16x32_bf16 v[68:71], v[168:171], v[208:211], v[68:71]
	v_mfma_f32_16x16x32_bf16 v[64:67], v[176:179], v[208:211], v[64:67]
	v_mfma_f32_16x16x32_bf16 v[116:119], v[172:175], v[188:191], v[116:119]
	v_mfma_f32_16x16x32_bf16 v[112:115], v[180:183], v[188:191], v[112:115]
	v_mfma_f32_16x16x32_bf16 v[100:103], v[172:175], v[196:199], v[100:103]
	v_mfma_f32_16x16x32_bf16 v[96:99], v[180:183], v[196:199], v[96:99]
	v_mfma_f32_16x16x32_bf16 v[84:87], v[172:175], v[204:207], v[84:87]
	v_mfma_f32_16x16x32_bf16 v[80:83], v[180:183], v[204:207], v[80:83]
	v_mfma_f32_16x16x32_bf16 v[68:71], v[172:175], v[212:215], v[68:71]
	s_setprio 0
	v_mfma_f32_16x16x32_bf16 v[64:67], v[180:183], v[212:215], v[64:67]
	s_barrier
	s_add_i32 s28, s55, s33
	v_lshl_add_u64 v[216:217], v[216:217], 0, s[10:11]
	s_mov_b32 m0, s28
	ds_read_b128 v[184:187], v150 offset:49152
	ds_read_b128 v[188:191], v150 offset:50176
	ds_read_b128 v[192:195], v150 offset:51200
	ds_read_b128 v[196:199], v150 offset:52224
	ds_read_b128 v[200:203], v150 offset:53248
	ds_read_b128 v[204:207], v150 offset:54272
	ds_read_b128 v[208:211], v150 offset:55296
	ds_read_b128 v[212:215], v150 offset:56320
	global_load_lds_dwordx4 v[216:217], off
	s_add_i32 m0, s28, 0x2000
	s_add_u32 s26, s26, 0x40080
	v_lshl_add_u64 v[216:217], v[218:219], 0, s[10:11]
	s_addc_u32 s27, s27, 0
	s_add_i32 s28, s56, s33
	global_load_lds_dwordx4 v[216:217], off
	s_mov_b32 m0, s28
	s_nop 0
	global_load_lds_dwordx4 v132, s[26:27]
	s_add_i32 m0, s28, 0x2000
	s_nop 0
	global_load_lds_dwordx4 v128, s[26:27]
	v_lshl_add_u64 v[216:217], v[220:221], 0, s[10:11]
	s_mov_b32 m0, s42
	s_nop 0
	global_load_lds_dwordx4 v[216:217], off
	v_lshl_add_u64 v[216:217], v[222:223], 0, s[10:11]
	s_mov_b32 m0, s43
	s_nop 0
	global_load_lds_dwordx4 v[216:217], off
	s_waitcnt vmcnt(8)
	s_waitcnt lgkmcnt(0)
	s_setprio 1
	s_barrier
	v_mfma_f32_16x16x32_bf16 v[60:63], v[152:155], v[184:187], v[60:63]
	v_mfma_f32_16x16x32_bf16 v[56:59], v[160:163], v[184:187], v[56:59]
	v_mfma_f32_16x16x32_bf16 v[44:47], v[152:155], v[192:195], v[44:47]
	v_mfma_f32_16x16x32_bf16 v[40:43], v[160:163], v[192:195], v[40:43]
	v_mfma_f32_16x16x32_bf16 v[28:31], v[152:155], v[200:203], v[28:31]
	v_mfma_f32_16x16x32_bf16 v[24:27], v[160:163], v[200:203], v[24:27]
	v_mfma_f32_16x16x32_bf16 v[12:15], v[152:155], v[208:211], v[12:15]
	v_mfma_f32_16x16x32_bf16 v[8:11], v[160:163], v[208:211], v[8:11]
	v_mfma_f32_16x16x32_bf16 v[60:63], v[156:159], v[188:191], v[60:63]
	v_mfma_f32_16x16x32_bf16 v[56:59], v[164:167], v[188:191], v[56:59]
	v_mfma_f32_16x16x32_bf16 v[44:47], v[156:159], v[196:199], v[44:47]
	v_mfma_f32_16x16x32_bf16 v[40:43], v[164:167], v[196:199], v[40:43]
	v_mfma_f32_16x16x32_bf16 v[28:31], v[156:159], v[204:207], v[28:31]
	v_mfma_f32_16x16x32_bf16 v[24:27], v[164:167], v[204:207], v[24:27]
	v_mfma_f32_16x16x32_bf16 v[12:15], v[156:159], v[212:215], v[12:15]
	v_mfma_f32_16x16x32_bf16 v[8:11], v[164:167], v[212:215], v[8:11]
	v_mfma_f32_16x16x32_bf16 v[52:55], v[168:171], v[184:187], v[52:55]
	v_mfma_f32_16x16x32_bf16 v[48:51], v[176:179], v[184:187], v[48:51]
	v_mfma_f32_16x16x32_bf16 v[36:39], v[168:171], v[192:195], v[36:39]
	v_mfma_f32_16x16x32_bf16 v[32:35], v[176:179], v[192:195], v[32:35]
	v_mfma_f32_16x16x32_bf16 v[20:23], v[168:171], v[200:203], v[20:23]
	v_mfma_f32_16x16x32_bf16 v[16:19], v[176:179], v[200:203], v[16:19]
	v_mfma_f32_16x16x32_bf16 v[4:7], v[168:171], v[208:211], v[4:7]
	v_mfma_f32_16x16x32_bf16 v[0:3], v[176:179], v[208:211], v[0:3]
	v_mfma_f32_16x16x32_bf16 v[52:55], v[172:175], v[188:191], v[52:55]
	v_mfma_f32_16x16x32_bf16 v[48:51], v[180:183], v[188:191], v[48:51]
	v_mfma_f32_16x16x32_bf16 v[36:39], v[172:175], v[196:199], v[36:39]
	v_mfma_f32_16x16x32_bf16 v[32:35], v[180:183], v[196:199], v[32:35]
	v_mfma_f32_16x16x32_bf16 v[20:23], v[172:175], v[204:207], v[20:23]
	v_mfma_f32_16x16x32_bf16 v[16:19], v[180:183], v[204:207], v[16:19]
	v_mfma_f32_16x16x32_bf16 v[4:7], v[172:175], v[212:215], v[4:7]
	s_setprio 0
	v_mfma_f32_16x16x32_bf16 v[0:3], v[180:183], v[212:215], v[0:3]
	s_barrier
	s_add_i32 s54, s54, 2
	s_add_u32 s24, s24, 0x100
	s_addc_u32 s25, s25, 0
	s_add_u32 s52, s52, 0x100
	s_addc_u32 s53, s53, 0
	s_cmp_gt_u32 s54, 13
; #define PG8_STAGE(bufoff, gbase, voff) do { _Pragma("unroll") for (int _i = 0; _i < 2; ++_i) \
;         __builtin_amdgcn_global_load_lds((const unsigned*)((const char*)(gbase) + (voff)[_i]), (PG8_LAS unsigned*)(lds + (bufoff) + ldsw + _i * 8192), 16, 0, 0); } while (0)
; #define PG8_LDA(dst, b, h) do { _Pragma("unroll") for (int m = 0; m < 4; ++m) _Pragma("unroll") for (int k = 0; k < 2; ++k) dst[m][k] = *(const PG8_LAS bf16x8*)(lds + PG8_SA(b, h) + aoff + m * 2048 + k * 1024); } while (0)
; #define PG8_LDB(dst, b, h) do { _Pragma("unroll") for (int n = 0; n < 2; ++n) _Pragma("unroll") for (int k = 0; k < 2; ++k) dst[n][k] = *(const PG8_LAS bf16x8*)(lds + PG8_SB(b, h) + boff + n * 2048 + k * 1024); } while (0)
; #define PG8_MMA(ai, bj, At, Bt) do { __builtin_amdgcn_s_setprio(1); _Pragma("unroll") for (int m = 0; m < 4; ++m) _Pragma("unroll") for (int n = 0; n < 2; ++n) _Pragma("unroll") for (int k = 0; k < 2; ++k) \
;         acc[ai][bj][m][n] = __builtin_amdgcn_mfma_f32_16x16x32_bf16(Bt[n][k], At[m][k], acc[ai][bj][m][n], 0, 0, 0); __builtin_amdgcn_s_setprio(0); } while (0)
; #define PG8_WAIT_V(n) asm volatile("s_waitcnt vmcnt(" #n ")" ::: "memory")
; #define PG8_WAIT_L(n) asm volatile("s_waitcnt lgkmcnt(" #n ")" ::: "memory")
; #define PG8_BAR __builtin_amdgcn_s_barrier()
; #define PG8_SCHED __builtin_amdgcn_sched_barrier(0)
; template <class Epi, class Sched, bool ALIGN_EPI = false, bool SP2 = false>
; __device__ __forceinline__ void gemm_phase(PG8_LAS unsigned char* lds, const Gemm g, const Sched& S, const Epi& E) {
;     ...
;             PG8_LDB(B0, 0, 0); PG8_LDB(B1, 0, 1); PG8_SCHED; PG8_LDA(At, 0, 0); PG8_STAGE(PG8_SA(1, 1), a1 + hstep, voffA);
;             PG8_WAIT_V(8); PG8_WAIT_L(0); PG8_BAR; PG8_MMA(0, 0, At, B0); PG8_MMA(0, 1, At, B1); PG8_BAR; PG8_SCHED;
;             PG8_LDA(At, 0, 1); PG8_STAGE(PG8_SB(0, 0), b2, voffB); PG8_STAGE(PG8_SB(0, 1), b2 + hstep, voffB); PG8_STAGE(PG8_SA(0, 0), a2, voffA);
;             PG8_WAIT_V(8); PG8_WAIT_L(0); PG8_BAR; PG8_MMA(1, 0, At, B0); PG8_MMA(1, 1, At, B1); PG8_BAR; PG8_SCHED;
.LBB0_1219:
	ds_read_b128 v[152:155], v148
	ds_read_b128 v[156:159], v148 offset:1024
	ds_read_b128 v[160:163], v148 offset:2048
	ds_read_b128 v[164:167], v148 offset:3072
	ds_read_b128 v[168:171], v149
	ds_read_b128 v[172:175], v149 offset:1024
	ds_read_b128 v[176:179], v149 offset:2048
	ds_read_b128 v[180:183], v149 offset:3072
	s_add_u32 s26, s24, 0xfffc0080
	s_addc_u32 s27, s25, -1
	s_cmp_eq_u32 s54, 12
	s_cselect_b32 s29, s17, s27
	s_cselect_b32 s28, s50, s26
	s_cselect_b32 s27, s15, s53
	s_cselect_b32 s26, s51, s52
	s_add_i32 m0, s23, 0xc000
	ds_read_b128 v[184:187], v150
	ds_read_b128 v[188:191], v150 offset:1024
	ds_read_b128 v[192:195], v150 offset:2048
	ds_read_b128 v[196:199], v150 offset:3072
	ds_read_b128 v[200:203], v150 offset:4096
	ds_read_b128 v[204:207], v150 offset:5120
	ds_read_b128 v[208:211], v150 offset:6144
	ds_read_b128 v[212:215], v150 offset:7168
	global_load_lds_dwordx4 v136, s[24:25]
	s_add_i32 m0, s23, 0xe000
	s_nop 0
	global_load_lds_dwordx4 v138, s[24:25]
	s_waitcnt vmcnt(8)
	s_waitcnt lgkmcnt(0)
	s_setprio 1
	s_barrier
	v_mfma_f32_16x16x32_bf16 v[124:127], v[152:155], v[184:187], v[124:127]
	v_mfma_f32_16x16x32_bf16 v[120:123], v[160:163], v[184:187], v[120:123]
	v_mfma_f32_16x16x32_bf16 v[108:111], v[152:155], v[192:195], v[108:111]
	v_mfma_f32_16x16x32_bf16 v[104:107], v[160:163], v[192:195], v[104:107]
	v_mfma_f32_16x16x32_bf16 v[92:95], v[152:155], v[200:203], v[92:95]
	v_mfma_f32_16x16x32_bf16 v[88:91], v[160:163], v[200:203], v[88:91]
	v_mfma_f32_16x16x32_bf16 v[76:79], v[152:155], v[208:211], v[76:79]
	v_mfma_f32_16x16x32_bf16 v[72:75], v[160:163], v[208:211], v[72:75]
	v_mfma_f32_16x16x32_bf16 v[124:127], v[156:159], v[188:191], v[124:127]
	v_mfma_f32_16x16x32_bf16 v[120:123], v[164:167], v[188:191], v[120:123]
	v_mfma_f32_16x16x32_bf16 v[108:111], v[156:159], v[196:199], v[108:111]
	v_mfma_f32_16x16x32_bf16 v[104:107], v[164:167], v[196:199], v[104:107]
	v_mfma_f32_16x16x32_bf16 v[92:95], v[156:159], v[204:207], v[92:95]
	v_mfma_f32_16x16x32_bf16 v[88:91], v[164:167], v[204:207], v[88:91]
	v_mfma_f32_16x16x32_bf16 v[76:79], v[156:159], v[212:215], v[76:79]
	v_mfma_f32_16x16x32_bf16 v[72:75], v[164:167], v[212:215], v[72:75]
	v_mfma_f32_16x16x32_bf16 v[116:119], v[168:171], v[184:187], v[116:119]
	v_mfma_f32_16x16x32_bf16 v[112:115], v[176:179], v[184:187], v[112:115]
	v_mfma_f32_16x16x32_bf16 v[100:103], v[168:171], v[192:195], v[100:103]
	v_mfma_f32_16x16x32_bf16 v[96:99], v[176:179], v[192:195], v[96:99]
	v_mfma_f32_16x16x32_bf16 v[84:87], v[168:171], v[200:203], v[84:87]
	v_mfma_f32_16x16x32_bf16 v[80:83], v[176:179], v[200:203], v[80:83]
	v_mfma_f32_16x16x32_bf16 v[68:71], v[168:171], v[208:211], v[68:71]
	v_mfma_f32_16x16x32_bf16 v[64:67], v[176:179], v[208:211], v[64:67]
	v_mfma_f32_16x16x32_bf16 v[116:119], v[172:175], v[188:191], v[116:119]
	v_mfma_f32_16x16x32_bf16 v[112:115], v[180:183], v[188:191], v[112:115]
	v_mfma_f32_16x16x32_bf16 v[100:103], v[172:175], v[196:199], v[100:103]
	v_mfma_f32_16x16x32_bf16 v[96:99], v[180:183], v[196:199], v[96:99]
	v_mfma_f32_16x16x32_bf16 v[84:87], v[172:175], v[204:207], v[84:87]
	v_mfma_f32_16x16x32_bf16 v[80:83], v[180:183], v[204:207], v[80:83]
	v_mfma_f32_16x16x32_bf16 v[68:71], v[172:175], v[212:215], v[68:71]
	s_setprio 0
	v_mfma_f32_16x16x32_bf16 v[64:67], v[180:183], v[212:215], v[64:67]
	s_barrier
	s_add_i32 s55, s44, s33
	v_lshl_add_u64 v[216:217], s[26:27], 0, v[132:133]
	s_mov_b32 m0, s55
	ds_read_b128 v[184:187], v150 offset:16384
	ds_read_b128 v[188:191], v150 offset:17408
	ds_read_b128 v[192:195], v150 offset:18432
	ds_read_b128 v[196:199], v150 offset:19456
	ds_read_b128 v[200:203], v150 offset:20480
	ds_read_b128 v[204:207], v150 offset:21504
	ds_read_b128 v[208:211], v150 offset:22528
	ds_read_b128 v[212:215], v150 offset:23552
	global_load_lds_dwordx4 v[216:217], off
	s_add_i32 m0, s55, 0x2000
	s_add_u32 s56, s26, 0x40000
	v_lshl_add_u64 v[218:219], s[26:27], 0, v[128:129]
	s_addc_u32 s57, s27, 0
	s_add_i32 s55, s45, s33
	global_load_lds_dwordx4 v[218:219], off
	s_mov_b32 m0, s55
	v_lshl_add_u64 v[222:223], s[28:29], 0, v[130:131]
	global_load_lds_dwordx4 v132, s[56:57]
	s_add_i32 m0, s55, 0x2000
	s_nop 0
	global_load_lds_dwordx4 v128, s[56:57]
	v_lshl_add_u64 v[220:221], s[28:29], 0, v[134:135]
	s_mov_b32 m0, s23
	s_nop 0
	global_load_lds_dwordx4 v[220:221], off
	s_mov_b32 m0, s39
	s_nop 0
	global_load_lds_dwordx4 v[222:223], off
	s_waitcnt vmcnt(8)
	s_waitcnt lgkmcnt(0)
	s_setprio 1
	s_barrier
	v_mfma_f32_16x16x32_bf16 v[60:63], v[152:155], v[184:187], v[60:63]
	v_mfma_f32_16x16x32_bf16 v[56:59], v[160:163], v[184:187], v[56:59]
	v_mfma_f32_16x16x32_bf16 v[44:47], v[152:155], v[192:195], v[44:47]
	v_mfma_f32_16x16x32_bf16 v[40:43], v[160:163], v[192:195], v[40:43]
	v_mfma_f32_16x16x32_bf16 v[28:31], v[152:155], v[200:203], v[28:31]
	v_mfma_f32_16x16x32_bf16 v[24:27], v[160:163], v[200:203], v[24:27]
	v_mfma_f32_16x16x32_bf16 v[12:15], v[152:155], v[208:211], v[12:15]
	v_mfma_f32_16x16x32_bf16 v[8:11], v[160:163], v[208:211], v[8:11]
	v_mfma_f32_16x16x32_bf16 v[60:63], v[156:159], v[188:191], v[60:63]
	v_mfma_f32_16x16x32_bf16 v[56:59], v[164:167], v[188:191], v[56:59]
	v_mfma_f32_16x16x32_bf16 v[44:47], v[156:159], v[196:199], v[44:47]
	v_mfma_f32_16x16x32_bf16 v[40:43], v[164:167], v[196:199], v[40:43]
	v_mfma_f32_16x16x32_bf16 v[28:31], v[156:159], v[204:207], v[28:31]
	v_mfma_f32_16x16x32_bf16 v[24:27], v[164:167], v[204:207], v[24:27]
	v_mfma_f32_16x16x32_bf16 v[12:15], v[156:159], v[212:215], v[12:15]
	v_mfma_f32_16x16x32_bf16 v[8:11], v[164:167], v[212:215], v[8:11]
	v_mfma_f32_16x16x32_bf16 v[52:55], v[168:171], v[184:187], v[52:55]
	v_mfma_f32_16x16x32_bf16 v[48:51], v[176:179], v[184:187], v[48:51]
	v_mfma_f32_16x16x32_bf16 v[36:39], v[168:171], v[192:195], v[36:39]
	v_mfma_f32_16x16x32_bf16 v[32:35], v[176:179], v[192:195], v[32:35]
	v_mfma_f32_16x16x32_bf16 v[20:23], v[168:171], v[200:203], v[20:23]
	v_mfma_f32_16x16x32_bf16 v[16:19], v[176:179], v[200:203], v[16:19]
	v_mfma_f32_16x16x32_bf16 v[4:7], v[168:171], v[208:211], v[4:7]
	v_mfma_f32_16x16x32_bf16 v[0:3], v[176:179], v[208:211], v[0:3]
	v_mfma_f32_16x16x32_bf16 v[52:55], v[172:175], v[188:191], v[52:55]
	v_mfma_f32_16x16x32_bf16 v[48:51], v[180:183], v[188:191], v[48:51]
	v_mfma_f32_16x16x32_bf16 v[36:39], v[172:175], v[196:199], v[36:39]
	v_mfma_f32_16x16x32_bf16 v[32:35], v[180:183], v[196:199], v[32:35]
	v_mfma_f32_16x16x32_bf16 v[20:23], v[172:175], v[204:207], v[20:23]
	v_mfma_f32_16x16x32_bf16 v[16:19], v[180:183], v[204:207], v[16:19]
	v_mfma_f32_16x16x32_bf16 v[4:7], v[172:175], v[212:215], v[4:7]
	s_setprio 0
	v_mfma_f32_16x16x32_bf16 v[0:3], v[180:183], v[212:215], v[0:3]
	s_barrier
; #define PG8_STAGE(bufoff, gbase, voff) do { _Pragma("unroll") for (int _i = 0; _i < 2; ++_i) \
;         __builtin_amdgcn_global_load_lds((const unsigned*)((const char*)(gbase) + (voff)[_i]), (PG8_LAS unsigned*)(lds + (bufoff) + ldsw + _i * 8192), 16, 0, 0); } while (0)
; #define PG8_LDA(dst, b, h) do { _Pragma("unroll") for (int m = 0; m < 4; ++m) _Pragma("unroll") for (int k = 0; k < 2; ++k) dst[m][k] = *(const PG8_LAS bf16x8*)(lds + PG8_SA(b, h) + aoff + m * 2048 + k * 1024); } while (0)
; #define PG8_LDB(dst, b, h) do { _Pragma("unroll") for (int n = 0; n < 2; ++n) _Pragma("unroll") for (int k = 0; k < 2; ++k) dst[n][k] = *(const PG8_LAS bf16x8*)(lds + PG8_SB(b, h) + boff + n * 2048 + k * 1024); } while (0)
; #define PG8_MMA(ai, bj, At, Bt) do { __builtin_amdgcn_s_setprio(1); _Pragma("unroll") for (int m = 0; m < 4; ++m) _Pragma("unroll") for (int n = 0; n < 2; ++n) _Pragma("unroll") for (int k = 0; k < 2; ++k) \
;         acc[ai][bj][m][n] = __builtin_amdgcn_mfma_f32_16x16x32_bf16(Bt[n][k], At[m][k], acc[ai][bj][m][n], 0, 0, 0); __builtin_amdgcn_s_setprio(0); } while (0)
; #define PG8_WAIT_V(n) asm volatile("s_waitcnt vmcnt(" #n ")" ::: "memory")
; #define PG8_WAIT_L(n) asm volatile("s_waitcnt lgkmcnt(" #n ")" ::: "memory")
; #define PG8_BAR __builtin_amdgcn_s_barrier()
; #define PG8_SCHED __builtin_amdgcn_sched_barrier(0)
; template <class Epi, class Sched, bool ALIGN_EPI = false, bool SP2 = false>
; __device__ __forceinline__ void gemm_phase(PG8_LAS unsigned char* lds, const Gemm g, const Sched& S, const Epi& E) {
;     ...
;         for (int t = 0; t < nt; t += 2) {
;     ...
;             PG8_LDB(B0, 1, 0); PG8_LDB(B1, 1, 1); PG8_SCHED; PG8_LDA(At, 1, 0); PG8_STAGE(PG8_SA(0, 1), a2 + hstep, voffA);
;             PG8_WAIT_V(8); PG8_WAIT_L(0); PG8_BAR; PG8_MMA(0, 0, At, B0); PG8_MMA(0, 1, At, B1); PG8_BAR; PG8_SCHED;
;             PG8_LDA(At, 1, 1); PG8_STAGE(PG8_SB(1, 0), b3, voffB); PG8_STAGE(PG8_SB(1, 1), b3 + hstep, voffB); PG8_STAGE(PG8_SA(1, 0), a3, voffA);
;             PG8_WAIT_V(8); PG8_WAIT_L(0); PG8_BAR; PG8_MMA(1, 0, At, B0); PG8_MMA(1, 1, At, B1); PG8_BAR; PG8_SCHED;
	s_add_i32 s55, 0, 0x18000
	v_add_u32_e32 v151, s55, v145
	s_add_i32 s56, 0, 0x1c000
	ds_read_b128 v[152:155], v151
	ds_read_b128 v[156:159], v151 offset:1024
	ds_read_b128 v[160:163], v151 offset:2048
	ds_read_b128 v[164:167], v151 offset:3072
	v_add_u32_e32 v151, s56, v145
	ds_read_b128 v[168:171], v151
	ds_read_b128 v[172:175], v151 offset:1024
	ds_read_b128 v[176:179], v151 offset:2048
	ds_read_b128 v[180:183], v151 offset:3072
	s_add_u32 s28, s28, 0x40000
	s_addc_u32 s29, s29, 0
	s_mov_b32 m0, s40
	ds_read_b128 v[184:187], v150 offset:32768
	ds_read_b128 v[188:191], v150 offset:33792
	ds_read_b128 v[192:195], v150 offset:34816
	ds_read_b128 v[196:199], v150 offset:35840
	ds_read_b128 v[200:203], v150 offset:36864
	ds_read_b128 v[204:207], v150 offset:37888
	ds_read_b128 v[208:211], v150 offset:38912
	ds_read_b128 v[212:215], v150 offset:39936
	global_load_lds_dwordx4 v134, s[28:29]
	s_mov_b32 m0, s41
	s_nop 0
	global_load_lds_dwordx4 v130, s[28:29]
	s_waitcnt vmcnt(8)
	s_waitcnt lgkmcnt(0)
	s_setprio 1
	s_barrier
	v_mfma_f32_16x16x32_bf16 v[124:127], v[152:155], v[184:187], v[124:127]
	v_mfma_f32_16x16x32_bf16 v[120:123], v[160:163], v[184:187], v[120:123]
	v_mfma_f32_16x16x32_bf16 v[108:111], v[152:155], v[192:195], v[108:111]
	v_mfma_f32_16x16x32_bf16 v[104:107], v[160:163], v[192:195], v[104:107]
	v_mfma_f32_16x16x32_bf16 v[92:95], v[152:155], v[200:203], v[92:95]
	v_mfma_f32_16x16x32_bf16 v[88:91], v[160:163], v[200:203], v[88:91]
	v_mfma_f32_16x16x32_bf16 v[76:79], v[152:155], v[208:211], v[76:79]
	v_mfma_f32_16x16x32_bf16 v[72:75], v[160:163], v[208:211], v[72:75]
	v_mfma_f32_16x16x32_bf16 v[124:127], v[156:159], v[188:191], v[124:127]
	v_mfma_f32_16x16x32_bf16 v[120:123], v[164:167], v[188:191], v[120:123]
	v_mfma_f32_16x16x32_bf16 v[108:111], v[156:159], v[196:199], v[108:111]
	v_mfma_f32_16x16x32_bf16 v[104:107], v[164:167], v[196:199], v[104:107]
	v_mfma_f32_16x16x32_bf16 v[92:95], v[156:159], v[204:207], v[92:95]
	v_mfma_f32_16x16x32_bf16 v[88:91], v[164:167], v[204:207], v[88:91]
	v_mfma_f32_16x16x32_bf16 v[76:79], v[156:159], v[212:215], v[76:79]
	v_mfma_f32_16x16x32_bf16 v[72:75], v[164:167], v[212:215], v[72:75]
	v_mfma_f32_16x16x32_bf16 v[116:119], v[168:171], v[184:187], v[116:119]
	v_mfma_f32_16x16x32_bf16 v[112:115], v[176:179], v[184:187], v[112:115]
	v_mfma_f32_16x16x32_bf16 v[100:103], v[168:171], v[192:195], v[100:103]
	v_mfma_f32_16x16x32_bf16 v[96:99], v[176:179], v[192:195], v[96:99]
	v_mfma_f32_16x16x32_bf16 v[84:87], v[168:171], v[200:203], v[84:87]
	v_mfma_f32_16x16x32_bf16 v[80:83], v[176:179], v[200:203], v[80:83]
	v_mfma_f32_16x16x32_bf16 v[68:71], v[168:171], v[208:211], v[68:71]
	v_mfma_f32_16x16x32_bf16 v[64:67], v[176:179], v[208:211], v[64:67]
	v_mfma_f32_16x16x32_bf16 v[116:119], v[172:175], v[188:191], v[116:119]
	v_mfma_f32_16x16x32_bf16 v[112:115], v[180:183], v[188:191], v[112:115]
	v_mfma_f32_16x16x32_bf16 v[100:103], v[172:175], v[196:199], v[100:103]
	v_mfma_f32_16x16x32_bf16 v[96:99], v[180:183], v[196:199], v[96:99]
	v_mfma_f32_16x16x32_bf16 v[84:87], v[172:175], v[204:207], v[84:87]
	v_mfma_f32_16x16x32_bf16 v[80:83], v[180:183], v[204:207], v[80:83]
	v_mfma_f32_16x16x32_bf16 v[68:71], v[172:175], v[212:215], v[68:71]
	s_setprio 0
	v_mfma_f32_16x16x32_bf16 v[64:67], v[180:183], v[212:215], v[64:67]
	s_barrier
	s_add_i32 s28, s55, s33
	v_lshl_add_u64 v[216:217], v[216:217], 0, s[10:11]
	s_mov_b32 m0, s28
	ds_read_b128 v[184:187], v150 offset:49152
	ds_read_b128 v[188:191], v150 offset:50176
	ds_read_b128 v[192:195], v150 offset:51200
	ds_read_b128 v[196:199], v150 offset:52224
	ds_read_b128 v[200:203], v150 offset:53248
	ds_read_b128 v[204:207], v150 offset:54272
	ds_read_b128 v[208:211], v150 offset:55296
	ds_read_b128 v[212:215], v150 offset:56320
	global_load_lds_dwordx4 v[216:217], off
	s_add_i32 m0, s28, 0x2000
	s_add_u32 s26, s26, 0x40080
	v_lshl_add_u64 v[216:217], v[218:219], 0, s[10:11]
	s_addc_u32 s27, s27, 0
	s_add_i32 s28, s56, s33
	global_load_lds_dwordx4 v[216:217], off
	s_mov_b32 m0, s28
	s_nop 0
	global_load_lds_dwordx4 v132, s[26:27]
	s_add_i32 m0, s28, 0x2000
	s_nop 0
	global_load_lds_dwordx4 v128, s[26:27]
	v_lshl_add_u64 v[216:217], v[220:221], 0, s[10:11]
	s_mov_b32 m0, s42
	s_nop 0
	global_load_lds_dwordx4 v[216:217], off
	v_lshl_add_u64 v[216:217], v[222:223], 0, s[10:11]
	s_mov_b32 m0, s43
	s_nop 0
	global_load_lds_dwordx4 v[216:217], off
	s_waitcnt vmcnt(8)
	s_waitcnt lgkmcnt(0)
	s_setprio 1
	s_barrier
	v_mfma_f32_16x16x32_bf16 v[60:63], v[152:155], v[184:187], v[60:63]
	v_mfma_f32_16x16x32_bf16 v[56:59], v[160:163], v[184:187], v[56:59]
	v_mfma_f32_16x16x32_bf16 v[44:47], v[152:155], v[192:195], v[44:47]
	v_mfma_f32_16x16x32_bf16 v[40:43], v[160:163], v[192:195], v[40:43]
	v_mfma_f32_16x16x32_bf16 v[28:31], v[152:155], v[200:203], v[28:31]
	v_mfma_f32_16x16x32_bf16 v[24:27], v[160:163], v[200:203], v[24:27]
	v_mfma_f32_16x16x32_bf16 v[12:15], v[152:155], v[208:211], v[12:15]
	v_mfma_f32_16x16x32_bf16 v[8:11], v[160:163], v[208:211], v[8:11]
	v_mfma_f32_16x16x32_bf16 v[60:63], v[156:159], v[188:191], v[60:63]
	v_mfma_f32_16x16x32_bf16 v[56:59], v[164:167], v[188:191], v[56:59]
	v_mfma_f32_16x16x32_bf16 v[44:47], v[156:159], v[196:199], v[44:47]
	v_mfma_f32_16x16x32_bf16 v[40:43], v[164:167], v[196:199], v[40:43]
	v_mfma_f32_16x16x32_bf16 v[28:31], v[156:159], v[204:207], v[28:31]
	v_mfma_f32_16x16x32_bf16 v[24:27], v[164:167], v[204:207], v[24:27]
	v_mfma_f32_16x16x32_bf16 v[12:15], v[156:159], v[212:215], v[12:15]
	v_mfma_f32_16x16x32_bf16 v[8:11], v[164:167], v[212:215], v[8:11]
	v_mfma_f32_16x16x32_bf16 v[52:55], v[168:171], v[184:187], v[52:55]
	v_mfma_f32_16x16x32_bf16 v[48:51], v[176:179], v[184:187], v[48:51]
	v_mfma_f32_16x16x32_bf16 v[36:39], v[168:171], v[192:195], v[36:39]
	v_mfma_f32_16x16x32_bf16 v[32:35], v[176:179], v[192:195], v[32:35]
	v_mfma_f32_16x16x32_bf16 v[20:23], v[168:171], v[200:203], v[20:23]
	v_mfma_f32_16x16x32_bf16 v[16:19], v[176:179], v[200:203], v[16:19]
	v_mfma_f32_16x16x32_bf16 v[4:7], v[168:171], v[208:211], v[4:7]
	v_mfma_f32_16x16x32_bf16 v[0:3], v[176:179], v[208:211], v[0:3]
	v_mfma_f32_16x16x32_bf16 v[52:55], v[172:175], v[188:191], v[52:55]
	v_mfma_f32_16x16x32_bf16 v[48:51], v[180:183], v[188:191], v[48:51]
	v_mfma_f32_16x16x32_bf16 v[36:39], v[172:175], v[196:199], v[36:39]
	v_mfma_f32_16x16x32_bf16 v[32:35], v[180:183], v[196:199], v[32:35]
	v_mfma_f32_16x16x32_bf16 v[20:23], v[172:175], v[204:207], v[20:23]
	v_mfma_f32_16x16x32_bf16 v[16:19], v[180:183], v[204:207], v[16:19]
	v_mfma_f32_16x16x32_bf16 v[4:7], v[172:175], v[212:215], v[4:7]
	s_setprio 0
	v_mfma_f32_16x16x32_bf16 v[0:3], v[180:183], v[212:215], v[0:3]
	s_barrier
	s_add_i32 s54, s54, 2
	s_add_u32 s24, s24, 0x100
	s_addc_u32 s25, s25, 0
	s_add_u32 s52, s52, 0x100
	s_addc_u32 s53, s53, 0
	s_cmp_gt_u32 s54, 13
	s_cbranch_scc0 .LBB0_1219
	s_and_b64 vcc, exec, s[12:13]
	s_cbranch_vccz .LBB0_1222
	s_barrier
